# MFMA order in K-loops: same-accumulator k0/k1 pair issued back-to-back (D->SrcC forwarding), bit-identical math
# speedup vs baseline: 1.0087x; 1.0087x over previous
.LBB0_142:
	ds_read_b128 v[168:171], v165
	ds_read_b128 v[172:175], v165 offset:1024
	ds_read_b128 v[176:179], v165 offset:2048
	ds_read_b128 v[180:183], v165 offset:3072
	ds_read_b128 v[184:187], v166
	ds_read_b128 v[188:191], v166 offset:1024
	ds_read_b128 v[192:195], v166 offset:2048
	ds_read_b128 v[196:199], v166 offset:3072
	s_add_i32 s54, s22, 2
	s_add_u32 s55, s20, 0x80
	s_addc_u32 s23, s21, 0
	s_cmp_eq_u32 s42, s22
	s_cselect_b32 s22, s4, s55
	s_cselect_b32 s23, s5, s23
	s_cselect_b32 s61, s19, s53
	s_cselect_b32 s60, s18, s52
	v_lshl_add_u64 v[234:235], s[20:21], 0, v[154:155]
	s_add_i32 m0, s31, 0xc000
	ds_read_b128 v[200:203], v167
	ds_read_b128 v[204:207], v167 offset:1024
	ds_read_b128 v[208:211], v167 offset:2048
	ds_read_b128 v[212:215], v167 offset:3072
	ds_read_b128 v[216:219], v167 offset:4096
	ds_read_b128 v[222:225], v167 offset:5120
	ds_read_b128 v[226:229], v167 offset:6144
	ds_read_b128 v[230:233], v167 offset:7168
	global_load_lds_dwordx4 v[234:235], off
	v_lshl_add_u64 v[234:235], s[20:21], 0, v[156:157]
	s_add_i32 m0, s31, 0xe000
	s_nop 0
	global_load_lds_dwordx4 v[234:235], off
	s_waitcnt vmcnt(8)
	s_waitcnt lgkmcnt(0)
	s_barrier
	s_setprio 1
	s_waitcnt lgkmcnt(0)
	v_mfma_f32_16x16x32_bf16 v[120:123], v[168:171], v[200:203], v[120:123]
	v_mfma_f32_16x16x32_bf16 v[120:123], v[172:175], v[204:207], v[120:123]
	v_mfma_f32_16x16x32_bf16 v[116:119], v[176:179], v[200:203], v[116:119]
	v_mfma_f32_16x16x32_bf16 v[116:119], v[180:183], v[204:207], v[116:119]
	v_mfma_f32_16x16x32_bf16 v[108:111], v[168:171], v[208:211], v[108:111]
	v_mfma_f32_16x16x32_bf16 v[108:111], v[172:175], v[212:215], v[108:111]
	v_mfma_f32_16x16x32_bf16 v[100:103], v[176:179], v[208:211], v[100:103]
	v_mfma_f32_16x16x32_bf16 v[100:103], v[180:183], v[212:215], v[100:103]
	v_mfma_f32_16x16x32_bf16 v[92:95], v[168:171], v[216:219], v[92:95]
	v_mfma_f32_16x16x32_bf16 v[92:95], v[172:175], v[222:225], v[92:95]
	v_mfma_f32_16x16x32_bf16 v[84:87], v[176:179], v[216:219], v[84:87]
	v_mfma_f32_16x16x32_bf16 v[84:87], v[180:183], v[222:225], v[84:87]
	v_mfma_f32_16x16x32_bf16 v[76:79], v[168:171], v[226:229], v[76:79]
	v_mfma_f32_16x16x32_bf16 v[76:79], v[172:175], v[230:233], v[76:79]
	v_mfma_f32_16x16x32_bf16 v[68:71], v[176:179], v[226:229], v[68:71]
	v_mfma_f32_16x16x32_bf16 v[68:71], v[180:183], v[230:233], v[68:71]
	s_setprio 0
	s_setprio 1
	v_mfma_f32_16x16x32_bf16 v[124:127], v[184:187], v[200:203], v[124:127]
	v_mfma_f32_16x16x32_bf16 v[124:127], v[188:191], v[204:207], v[124:127]
	v_mfma_f32_16x16x32_bf16 v[112:115], v[192:195], v[200:203], v[112:115]
	v_mfma_f32_16x16x32_bf16 v[112:115], v[196:199], v[204:207], v[112:115]
	v_mfma_f32_16x16x32_bf16 v[104:107], v[184:187], v[208:211], v[104:107]
	v_mfma_f32_16x16x32_bf16 v[104:107], v[188:191], v[212:215], v[104:107]
	v_mfma_f32_16x16x32_bf16 v[96:99], v[192:195], v[208:211], v[96:99]
	v_mfma_f32_16x16x32_bf16 v[96:99], v[196:199], v[212:215], v[96:99]
	v_mfma_f32_16x16x32_bf16 v[88:91], v[184:187], v[216:219], v[88:91]
	v_mfma_f32_16x16x32_bf16 v[88:91], v[188:191], v[222:225], v[88:91]
	v_mfma_f32_16x16x32_bf16 v[80:83], v[192:195], v[216:219], v[80:83]
	v_mfma_f32_16x16x32_bf16 v[80:83], v[196:199], v[222:225], v[80:83]
	v_mfma_f32_16x16x32_bf16 v[72:75], v[184:187], v[226:229], v[72:75]
	v_mfma_f32_16x16x32_bf16 v[72:75], v[188:191], v[230:233], v[72:75]
	v_mfma_f32_16x16x32_bf16 v[64:67], v[192:195], v[226:229], v[64:67]
	v_mfma_f32_16x16x32_bf16 v[64:67], v[196:199], v[230:233], v[64:67]
	s_setprio 0
	s_barrier
	s_add_i32 s55, s46, s28
	v_lshl_add_u64 v[234:235], s[60:61], 0, v[132:133]
	s_mov_b32 m0, s55
	ds_read_b128 v[200:203], v167 offset:16384
	ds_read_b128 v[204:207], v167 offset:17408
	ds_read_b128 v[208:211], v167 offset:18432
	ds_read_b128 v[212:215], v167 offset:19456
	ds_read_b128 v[216:219], v167 offset:20480
	ds_read_b128 v[222:225], v167 offset:21504
	ds_read_b128 v[226:229], v167 offset:22528
	ds_read_b128 v[230:233], v167 offset:23552
	global_load_lds_dwordx4 v[234:235], off
	s_add_i32 m0, s55, 0x2000
	v_lshl_add_u64 v[236:237], s[60:61], 0, v[128:129]
	s_add_u32 s60, s60, s10
	s_addc_u32 s61, s61, s11
	s_add_i32 s55, s47, s28
	global_load_lds_dwordx4 v[236:237], off
	v_lshl_add_u64 v[238:239], s[60:61], 0, v[132:133]
	s_mov_b32 m0, s55
	v_lshl_add_u64 v[240:241], s[60:61], 0, v[128:129]
	global_load_lds_dwordx4 v[238:239], off
	s_add_i32 m0, s55, 0x2000
	v_lshl_add_u64 v[242:243], s[22:23], 0, v[134:135]
	global_load_lds_dwordx4 v[240:241], off
	s_mov_b32 m0, s31
	v_lshl_add_u64 v[244:245], s[22:23], 0, v[130:131]
	global_load_lds_dwordx4 v[242:243], off
	s_mov_b32 m0, s33
	s_nop 0
	global_load_lds_dwordx4 v[244:245], off
	s_waitcnt vmcnt(8)
	s_waitcnt lgkmcnt(0)
	s_barrier
	s_setprio 1
	s_waitcnt lgkmcnt(0)
	v_mfma_f32_16x16x32_bf16 v[60:63], v[168:171], v[200:203], v[60:63]
	v_mfma_f32_16x16x32_bf16 v[60:63], v[172:175], v[204:207], v[60:63]
	v_mfma_f32_16x16x32_bf16 v[52:55], v[176:179], v[200:203], v[52:55]
	v_mfma_f32_16x16x32_bf16 v[52:55], v[180:183], v[204:207], v[52:55]
	v_mfma_f32_16x16x32_bf16 v[44:47], v[168:171], v[208:211], v[44:47]
	v_mfma_f32_16x16x32_bf16 v[44:47], v[172:175], v[212:215], v[44:47]
	v_mfma_f32_16x16x32_bf16 v[36:39], v[176:179], v[208:211], v[36:39]
	v_mfma_f32_16x16x32_bf16 v[36:39], v[180:183], v[212:215], v[36:39]
	v_mfma_f32_16x16x32_bf16 v[28:31], v[168:171], v[216:219], v[28:31]
	v_mfma_f32_16x16x32_bf16 v[28:31], v[172:175], v[222:225], v[28:31]
	v_mfma_f32_16x16x32_bf16 v[20:23], v[176:179], v[216:219], v[20:23]
	v_mfma_f32_16x16x32_bf16 v[20:23], v[180:183], v[222:225], v[20:23]
	v_mfma_f32_16x16x32_bf16 v[12:15], v[168:171], v[226:229], v[12:15]
	v_mfma_f32_16x16x32_bf16 v[12:15], v[172:175], v[230:233], v[12:15]
	v_mfma_f32_16x16x32_bf16 v[4:7], v[176:179], v[226:229], v[4:7]
	v_mfma_f32_16x16x32_bf16 v[4:7], v[180:183], v[230:233], v[4:7]
	s_setprio 0
	s_setprio 1
	v_mfma_f32_16x16x32_bf16 v[56:59], v[184:187], v[200:203], v[56:59]
	v_mfma_f32_16x16x32_bf16 v[56:59], v[188:191], v[204:207], v[56:59]
	v_mfma_f32_16x16x32_bf16 v[48:51], v[192:195], v[200:203], v[48:51]
	v_mfma_f32_16x16x32_bf16 v[48:51], v[196:199], v[204:207], v[48:51]
	v_mfma_f32_16x16x32_bf16 v[40:43], v[184:187], v[208:211], v[40:43]
	v_mfma_f32_16x16x32_bf16 v[40:43], v[188:191], v[212:215], v[40:43]
	v_mfma_f32_16x16x32_bf16 v[32:35], v[192:195], v[208:211], v[32:35]
	v_mfma_f32_16x16x32_bf16 v[32:35], v[196:199], v[212:215], v[32:35]
	v_mfma_f32_16x16x32_bf16 v[24:27], v[184:187], v[216:219], v[24:27]
	v_mfma_f32_16x16x32_bf16 v[24:27], v[188:191], v[222:225], v[24:27]
	v_mfma_f32_16x16x32_bf16 v[16:19], v[192:195], v[216:219], v[16:19]
	v_mfma_f32_16x16x32_bf16 v[16:19], v[196:199], v[222:225], v[16:19]
	v_mfma_f32_16x16x32_bf16 v[8:11], v[184:187], v[226:229], v[8:11]
	v_mfma_f32_16x16x32_bf16 v[8:11], v[188:191], v[230:233], v[8:11]
	v_mfma_f32_16x16x32_bf16 v[0:3], v[192:195], v[226:229], v[0:3]
	v_mfma_f32_16x16x32_bf16 v[0:3], v[196:199], v[230:233], v[0:3]
	s_setprio 0
	s_barrier
	s_add_i32 s55, 0, 0x18000
	s_add_i32 s60, 0, 0x1c000
	v_add_u32_e32 v180, s55, v164
	v_add_u32_e32 v196, s60, v164
	ds_read_b128 v[168:171], v180
	ds_read_b128 v[172:175], v180 offset:1024
	ds_read_b128 v[176:179], v180 offset:2048
	ds_read_b128 v[180:183], v180 offset:3072
	ds_read_b128 v[184:187], v196
	ds_read_b128 v[188:191], v196 offset:1024
	ds_read_b128 v[192:195], v196 offset:2048
	ds_read_b128 v[196:199], v196 offset:3072
	s_add_u32 s22, s22, s10
	s_addc_u32 s23, s23, s11
	s_mov_b32 m0, s34
	v_lshl_add_u64 v[246:247], s[22:23], 0, v[134:135]
	ds_read_b128 v[200:203], v167 offset:32768
	ds_read_b128 v[204:207], v167 offset:33792
	ds_read_b128 v[208:211], v167 offset:34816
	ds_read_b128 v[212:215], v167 offset:35840
	ds_read_b128 v[216:219], v167 offset:36864
	ds_read_b128 v[222:225], v167 offset:37888
	ds_read_b128 v[226:229], v167 offset:38912
	ds_read_b128 v[230:233], v167 offset:39936
	global_load_lds_dwordx4 v[246:247], off
	v_lshl_add_u64 v[246:247], s[22:23], 0, v[130:131]
	s_mov_b32 m0, s35
	s_nop 0
	global_load_lds_dwordx4 v[246:247], off
	s_waitcnt vmcnt(8)
	s_waitcnt lgkmcnt(0)
	s_barrier
	s_setprio 1
	s_waitcnt lgkmcnt(0)
	v_mfma_f32_16x16x32_bf16 v[120:123], v[168:171], v[200:203], v[120:123]
	v_mfma_f32_16x16x32_bf16 v[120:123], v[172:175], v[204:207], v[120:123]
	v_mfma_f32_16x16x32_bf16 v[116:119], v[176:179], v[200:203], v[116:119]
	v_mfma_f32_16x16x32_bf16 v[116:119], v[180:183], v[204:207], v[116:119]
	v_mfma_f32_16x16x32_bf16 v[108:111], v[168:171], v[208:211], v[108:111]
	v_mfma_f32_16x16x32_bf16 v[108:111], v[172:175], v[212:215], v[108:111]
	v_mfma_f32_16x16x32_bf16 v[100:103], v[176:179], v[208:211], v[100:103]
	v_mfma_f32_16x16x32_bf16 v[100:103], v[180:183], v[212:215], v[100:103]
	v_mfma_f32_16x16x32_bf16 v[92:95], v[168:171], v[216:219], v[92:95]
	v_mfma_f32_16x16x32_bf16 v[92:95], v[172:175], v[222:225], v[92:95]
	v_mfma_f32_16x16x32_bf16 v[84:87], v[176:179], v[216:219], v[84:87]
	v_mfma_f32_16x16x32_bf16 v[84:87], v[180:183], v[222:225], v[84:87]
	v_mfma_f32_16x16x32_bf16 v[76:79], v[168:171], v[226:229], v[76:79]
	v_mfma_f32_16x16x32_bf16 v[76:79], v[172:175], v[230:233], v[76:79]
	v_mfma_f32_16x16x32_bf16 v[68:71], v[176:179], v[226:229], v[68:71]
	v_mfma_f32_16x16x32_bf16 v[68:71], v[180:183], v[230:233], v[68:71]
	s_setprio 0
	s_setprio 1
	v_mfma_f32_16x16x32_bf16 v[124:127], v[184:187], v[200:203], v[124:127]
	v_mfma_f32_16x16x32_bf16 v[124:127], v[188:191], v[204:207], v[124:127]
	v_mfma_f32_16x16x32_bf16 v[112:115], v[192:195], v[200:203], v[112:115]
	v_mfma_f32_16x16x32_bf16 v[112:115], v[196:199], v[204:207], v[112:115]
	v_mfma_f32_16x16x32_bf16 v[104:107], v[184:187], v[208:211], v[104:107]
	v_mfma_f32_16x16x32_bf16 v[104:107], v[188:191], v[212:215], v[104:107]
	v_mfma_f32_16x16x32_bf16 v[96:99], v[192:195], v[208:211], v[96:99]
	v_mfma_f32_16x16x32_bf16 v[96:99], v[196:199], v[212:215], v[96:99]
	v_mfma_f32_16x16x32_bf16 v[88:91], v[184:187], v[216:219], v[88:91]
	v_mfma_f32_16x16x32_bf16 v[88:91], v[188:191], v[222:225], v[88:91]
	v_mfma_f32_16x16x32_bf16 v[80:83], v[192:195], v[216:219], v[80:83]
	v_mfma_f32_16x16x32_bf16 v[80:83], v[196:199], v[222:225], v[80:83]
	v_mfma_f32_16x16x32_bf16 v[72:75], v[184:187], v[226:229], v[72:75]
	v_mfma_f32_16x16x32_bf16 v[72:75], v[188:191], v[230:233], v[72:75]
	v_mfma_f32_16x16x32_bf16 v[64:67], v[192:195], v[226:229], v[64:67]
	v_mfma_f32_16x16x32_bf16 v[64:67], v[196:199], v[230:233], v[64:67]
	s_setprio 0
	s_barrier
	s_add_i32 s22, s55, s28
	v_lshl_add_u64 v[234:235], v[234:235], 0, s[14:15]
	s_mov_b32 m0, s22
	ds_read_b128 v[200:203], v167 offset:49152
	ds_read_b128 v[204:207], v167 offset:50176
	ds_read_b128 v[208:211], v167 offset:51200
	ds_read_b128 v[212:215], v167 offset:52224
	ds_read_b128 v[216:219], v167 offset:53248
	ds_read_b128 v[222:225], v167 offset:54272
	ds_read_b128 v[226:229], v167 offset:55296
	ds_read_b128 v[230:233], v167 offset:56320
	global_load_lds_dwordx4 v[234:235], off
	v_lshl_add_u64 v[234:235], v[236:237], 0, s[14:15]
	s_add_i32 m0, s22, 0x2000
	s_add_i32 s22, s60, s28
	global_load_lds_dwordx4 v[234:235], off
	v_lshl_add_u64 v[234:235], v[238:239], 0, s[14:15]
	s_mov_b32 m0, s22
	s_nop 0
	global_load_lds_dwordx4 v[234:235], off
	v_lshl_add_u64 v[234:235], v[240:241], 0, s[14:15]
	s_add_i32 m0, s22, 0x2000
	s_nop 0
	global_load_lds_dwordx4 v[234:235], off
	v_lshl_add_u64 v[234:235], v[242:243], 0, s[14:15]
	s_mov_b32 m0, s39
	s_nop 0
	global_load_lds_dwordx4 v[234:235], off
	v_lshl_add_u64 v[234:235], v[244:245], 0, s[14:15]
	s_mov_b32 m0, s40
	s_nop 0
	global_load_lds_dwordx4 v[234:235], off
	s_waitcnt vmcnt(8)
	s_waitcnt lgkmcnt(0)
	s_barrier
	s_setprio 1
	s_waitcnt lgkmcnt(0)
	v_mfma_f32_16x16x32_bf16 v[60:63], v[168:171], v[200:203], v[60:63]
	v_mfma_f32_16x16x32_bf16 v[60:63], v[172:175], v[204:207], v[60:63]
	v_mfma_f32_16x16x32_bf16 v[52:55], v[176:179], v[200:203], v[52:55]
	v_mfma_f32_16x16x32_bf16 v[52:55], v[180:183], v[204:207], v[52:55]
	v_mfma_f32_16x16x32_bf16 v[44:47], v[168:171], v[208:211], v[44:47]
	v_mfma_f32_16x16x32_bf16 v[44:47], v[172:175], v[212:215], v[44:47]
	v_mfma_f32_16x16x32_bf16 v[36:39], v[176:179], v[208:211], v[36:39]
	v_mfma_f32_16x16x32_bf16 v[36:39], v[180:183], v[212:215], v[36:39]
	v_mfma_f32_16x16x32_bf16 v[28:31], v[168:171], v[216:219], v[28:31]
	v_mfma_f32_16x16x32_bf16 v[28:31], v[172:175], v[222:225], v[28:31]
	v_mfma_f32_16x16x32_bf16 v[20:23], v[176:179], v[216:219], v[20:23]
	v_mfma_f32_16x16x32_bf16 v[20:23], v[180:183], v[222:225], v[20:23]
	v_mfma_f32_16x16x32_bf16 v[12:15], v[168:171], v[226:229], v[12:15]
	v_mfma_f32_16x16x32_bf16 v[12:15], v[172:175], v[230:233], v[12:15]
	v_mfma_f32_16x16x32_bf16 v[4:7], v[176:179], v[226:229], v[4:7]
	v_mfma_f32_16x16x32_bf16 v[4:7], v[180:183], v[230:233], v[4:7]
	s_setprio 0
	s_setprio 1
	v_mfma_f32_16x16x32_bf16 v[56:59], v[184:187], v[200:203], v[56:59]
	v_mfma_f32_16x16x32_bf16 v[56:59], v[188:191], v[204:207], v[56:59]
	v_mfma_f32_16x16x32_bf16 v[48:51], v[192:195], v[200:203], v[48:51]
	v_mfma_f32_16x16x32_bf16 v[48:51], v[196:199], v[204:207], v[48:51]
	v_mfma_f32_16x16x32_bf16 v[40:43], v[184:187], v[208:211], v[40:43]
	v_mfma_f32_16x16x32_bf16 v[40:43], v[188:191], v[212:215], v[40:43]
	v_mfma_f32_16x16x32_bf16 v[32:35], v[192:195], v[208:211], v[32:35]
	v_mfma_f32_16x16x32_bf16 v[32:35], v[196:199], v[212:215], v[32:35]
	v_mfma_f32_16x16x32_bf16 v[24:27], v[184:187], v[216:219], v[24:27]
	v_mfma_f32_16x16x32_bf16 v[24:27], v[188:191], v[222:225], v[24:27]
	v_mfma_f32_16x16x32_bf16 v[16:19], v[192:195], v[216:219], v[16:19]
	v_mfma_f32_16x16x32_bf16 v[16:19], v[196:199], v[222:225], v[16:19]
	v_mfma_f32_16x16x32_bf16 v[8:11], v[184:187], v[226:229], v[8:11]
	v_mfma_f32_16x16x32_bf16 v[8:11], v[188:191], v[230:233], v[8:11]
	v_mfma_f32_16x16x32_bf16 v[0:3], v[192:195], v[226:229], v[0:3]
	v_mfma_f32_16x16x32_bf16 v[0:3], v[196:199], v[230:233], v[0:3]
	s_setprio 0
	s_barrier
	s_add_u32 s20, s20, 0x100
	s_addc_u32 s21, s21, 0
	s_add_u32 s52, s52, 0x100
	s_addc_u32 s53, s53, 0
	s_cmp_ge_i32 s54, s41
	s_mov_b32 s22, s54
	s_cbranch_scc0 .LBB0_142

.LBB0_228:
	ds_read_b128 v[140:143], v219
	ds_read_b128 v[144:147], v219 offset:1024
	ds_read_b128 v[148:151], v219 offset:2048
	ds_read_b128 v[152:155], v219 offset:3072
	ds_read_b128 v[156:159], v221
	ds_read_b128 v[164:167], v221 offset:1024
	ds_read_b128 v[168:171], v221 offset:2048
	ds_read_b128 v[172:175], v221 offset:3072
	s_add_i32 s62, s26, 2
	s_add_u32 s27, s24, 0x4000
	s_addc_u32 s28, s25, 0
	s_cmp_eq_u32 s46, s26
	s_cselect_b32 s30, s0, s27
	s_cselect_b32 s31, s1, s28
	s_cselect_b32 s28, s22, s60
	s_cselect_b32 s29, s23, s61
	s_add_u32 s26, s30, 0x8000
	s_addc_u32 s27, s31, 0
	v_lshl_add_u64 v[160:161], s[24:25], 0, v[132:133]
	s_add_i32 m0, s38, 0xc000
	ds_read_b128 v[176:179], v222
	ds_read_b128 v[180:183], v222 offset:1024
	ds_read_b128 v[184:187], v222 offset:2048
	ds_read_b128 v[188:191], v222 offset:3072
	ds_read_b128 v[192:195], v222 offset:4096
	ds_read_b128 v[196:199], v222 offset:5120
	ds_read_b128 v[200:203], v222 offset:6144
	ds_read_b128 v[204:207], v222 offset:7168
	global_load_lds_dwordx4 v[160:161], off
	v_lshl_add_u64 v[160:161], s[24:25], 0, v[134:135]
	s_add_i32 m0, s38, 0xe000
	s_nop 0
	global_load_lds_dwordx4 v[160:161], off
	s_waitcnt vmcnt(8)
	s_waitcnt lgkmcnt(0)
	s_barrier
	s_setprio 1
	s_waitcnt lgkmcnt(0)
	v_mfma_f32_16x16x32_bf16 v[124:127], v[140:143], v[176:179], v[124:127]
	v_mfma_f32_16x16x32_bf16 v[124:127], v[144:147], v[180:183], v[124:127]
	v_mfma_f32_16x16x32_bf16 v[120:123], v[148:151], v[176:179], v[120:123]
	v_mfma_f32_16x16x32_bf16 v[120:123], v[152:155], v[180:183], v[120:123]
	v_mfma_f32_16x16x32_bf16 v[116:119], v[140:143], v[184:187], v[116:119]
	v_mfma_f32_16x16x32_bf16 v[116:119], v[144:147], v[188:191], v[116:119]
	v_mfma_f32_16x16x32_bf16 v[112:115], v[148:151], v[184:187], v[112:115]
	v_mfma_f32_16x16x32_bf16 v[112:115], v[152:155], v[188:191], v[112:115]
	v_mfma_f32_16x16x32_bf16 v[104:107], v[140:143], v[192:195], v[104:107]
	v_mfma_f32_16x16x32_bf16 v[104:107], v[144:147], v[196:199], v[104:107]
	v_mfma_f32_16x16x32_bf16 v[96:99], v[148:151], v[192:195], v[96:99]
	v_mfma_f32_16x16x32_bf16 v[96:99], v[152:155], v[196:199], v[96:99]
	v_mfma_f32_16x16x32_bf16 v[88:91], v[140:143], v[200:203], v[88:91]
	v_mfma_f32_16x16x32_bf16 v[88:91], v[144:147], v[204:207], v[88:91]
	v_mfma_f32_16x16x32_bf16 v[80:83], v[148:151], v[200:203], v[80:83]
	v_mfma_f32_16x16x32_bf16 v[80:83], v[152:155], v[204:207], v[80:83]
	s_setprio 0
	s_setprio 1
	v_mfma_f32_16x16x32_bf16 v[108:111], v[156:159], v[176:179], v[108:111]
	v_mfma_f32_16x16x32_bf16 v[108:111], v[164:167], v[180:183], v[108:111]
	v_mfma_f32_16x16x32_bf16 v[100:103], v[168:171], v[176:179], v[100:103]
	v_mfma_f32_16x16x32_bf16 v[100:103], v[172:175], v[180:183], v[100:103]
	v_mfma_f32_16x16x32_bf16 v[92:95], v[156:159], v[184:187], v[92:95]
	v_mfma_f32_16x16x32_bf16 v[92:95], v[164:167], v[188:191], v[92:95]
	v_mfma_f32_16x16x32_bf16 v[84:87], v[168:171], v[184:187], v[84:87]
	v_mfma_f32_16x16x32_bf16 v[84:87], v[172:175], v[188:191], v[84:87]
	v_mfma_f32_16x16x32_bf16 v[76:79], v[156:159], v[192:195], v[76:79]
	v_mfma_f32_16x16x32_bf16 v[76:79], v[164:167], v[196:199], v[76:79]
	v_mfma_f32_16x16x32_bf16 v[72:75], v[168:171], v[192:195], v[72:75]
	v_mfma_f32_16x16x32_bf16 v[72:75], v[172:175], v[196:199], v[72:75]
	v_mfma_f32_16x16x32_bf16 v[68:71], v[156:159], v[200:203], v[68:71]
	v_mfma_f32_16x16x32_bf16 v[68:71], v[164:167], v[204:207], v[68:71]
	v_mfma_f32_16x16x32_bf16 v[64:67], v[168:171], v[200:203], v[64:67]
	v_mfma_f32_16x16x32_bf16 v[64:67], v[172:175], v[204:207], v[64:67]
	s_setprio 0
	s_barrier
	s_add_i32 s63, s50, s37
	v_lshl_add_u64 v[160:161], s[28:29], 0, v[128:129]
	s_mov_b32 m0, s63
	ds_read_b128 v[176:179], v222 offset:16384
	ds_read_b128 v[180:183], v222 offset:17408
	ds_read_b128 v[184:187], v222 offset:18432
	ds_read_b128 v[188:191], v222 offset:19456
	ds_read_b128 v[192:195], v222 offset:20480
	ds_read_b128 v[196:199], v222 offset:21504
	ds_read_b128 v[200:203], v222 offset:22528
	ds_read_b128 v[204:207], v222 offset:23552
	global_load_lds_dwordx4 v[160:161], off
	s_add_i32 m0, s63, 0x2000
	s_add_u32 s64, s28, 0x4000
	v_lshl_add_u64 v[160:161], s[28:29], 0, v[130:131]
	s_addc_u32 s65, s29, 0
	s_add_i32 s63, s51, s37
	global_load_lds_dwordx4 v[160:161], off
	v_lshl_add_u64 v[160:161], s[64:65], 0, v[128:129]
	s_mov_b32 m0, s63
	s_nop 0
	global_load_lds_dwordx4 v[160:161], off
	v_lshl_add_u64 v[160:161], s[64:65], 0, v[130:131]
	s_add_i32 m0, s63, 0x2000
	s_nop 0
	global_load_lds_dwordx4 v[160:161], off
	v_lshl_add_u64 v[160:161], s[30:31], 0, v[128:129]
	s_mov_b32 m0, s38
	s_nop 0
	global_load_lds_dwordx4 v[160:161], off
	v_lshl_add_u64 v[160:161], s[30:31], 0, v[130:131]
	s_mov_b32 m0, s39
	s_nop 0
	global_load_lds_dwordx4 v[160:161], off
	s_waitcnt vmcnt(8)
	s_waitcnt lgkmcnt(0)
	s_barrier
	s_setprio 1
	s_waitcnt lgkmcnt(0)
	v_mfma_f32_16x16x32_bf16 v[60:63], v[140:143], v[176:179], v[60:63]
	v_mfma_f32_16x16x32_bf16 v[60:63], v[144:147], v[180:183], v[60:63]
	v_mfma_f32_16x16x32_bf16 v[56:59], v[148:151], v[176:179], v[56:59]
	v_mfma_f32_16x16x32_bf16 v[56:59], v[152:155], v[180:183], v[56:59]
	v_mfma_f32_16x16x32_bf16 v[52:55], v[140:143], v[184:187], v[52:55]
	v_mfma_f32_16x16x32_bf16 v[52:55], v[144:147], v[188:191], v[52:55]
	v_mfma_f32_16x16x32_bf16 v[48:51], v[148:151], v[184:187], v[48:51]
	v_mfma_f32_16x16x32_bf16 v[48:51], v[152:155], v[188:191], v[48:51]
	v_mfma_f32_16x16x32_bf16 v[40:43], v[140:143], v[192:195], v[40:43]
	v_mfma_f32_16x16x32_bf16 v[40:43], v[144:147], v[196:199], v[40:43]
	v_mfma_f32_16x16x32_bf16 v[32:35], v[148:151], v[192:195], v[32:35]
	v_mfma_f32_16x16x32_bf16 v[32:35], v[152:155], v[196:199], v[32:35]
	v_mfma_f32_16x16x32_bf16 v[24:27], v[140:143], v[200:203], v[24:27]
	v_mfma_f32_16x16x32_bf16 v[24:27], v[144:147], v[204:207], v[24:27]
	v_mfma_f32_16x16x32_bf16 v[16:19], v[148:151], v[200:203], v[16:19]
	v_mfma_f32_16x16x32_bf16 v[16:19], v[152:155], v[204:207], v[16:19]
	s_setprio 0
	s_setprio 1
	v_mfma_f32_16x16x32_bf16 v[44:47], v[156:159], v[176:179], v[44:47]
	v_mfma_f32_16x16x32_bf16 v[44:47], v[164:167], v[180:183], v[44:47]
	v_mfma_f32_16x16x32_bf16 v[36:39], v[168:171], v[176:179], v[36:39]
	v_mfma_f32_16x16x32_bf16 v[36:39], v[172:175], v[180:183], v[36:39]
	v_mfma_f32_16x16x32_bf16 v[28:31], v[156:159], v[184:187], v[28:31]
	v_mfma_f32_16x16x32_bf16 v[28:31], v[164:167], v[188:191], v[28:31]
	v_mfma_f32_16x16x32_bf16 v[20:23], v[168:171], v[184:187], v[20:23]
	v_mfma_f32_16x16x32_bf16 v[20:23], v[172:175], v[188:191], v[20:23]
	v_mfma_f32_16x16x32_bf16 v[12:15], v[156:159], v[192:195], v[12:15]
	v_mfma_f32_16x16x32_bf16 v[12:15], v[164:167], v[196:199], v[12:15]
	v_mfma_f32_16x16x32_bf16 v[8:11], v[168:171], v[192:195], v[8:11]
	v_mfma_f32_16x16x32_bf16 v[8:11], v[172:175], v[196:199], v[8:11]
	v_mfma_f32_16x16x32_bf16 v[4:7], v[156:159], v[200:203], v[4:7]
	v_mfma_f32_16x16x32_bf16 v[4:7], v[164:167], v[204:207], v[4:7]
	v_mfma_f32_16x16x32_bf16 v[0:3], v[168:171], v[200:203], v[0:3]
	v_mfma_f32_16x16x32_bf16 v[0:3], v[172:175], v[204:207], v[0:3]
	s_setprio 0
	s_barrier
	s_add_i32 s63, 0, 0x18000
	s_add_i32 s64, 0, 0x1c000
	v_add_u32_e32 v152, s63, v217
	v_add_u32_e32 v160, s64, v217
	ds_read_b128 v[140:143], v152
	ds_read_b128 v[144:147], v152 offset:1024
	ds_read_b128 v[148:151], v152 offset:2048
	ds_read_b128 v[152:155], v152 offset:3072
	ds_read_b128 v[156:159], v160
	ds_read_b128 v[164:167], v160 offset:1024
	ds_read_b128 v[168:171], v160 offset:2048
	ds_read_b128 v[172:175], v160 offset:3072
	s_add_u32 s30, s30, 0x4000
	s_addc_u32 s31, s31, 0
	s_mov_b32 m0, s40
	v_lshl_add_u64 v[160:161], s[30:31], 0, v[128:129]
	ds_read_b128 v[176:179], v222 offset:32768
	ds_read_b128 v[180:183], v222 offset:33792
	ds_read_b128 v[184:187], v222 offset:34816
	ds_read_b128 v[188:191], v222 offset:35840
	ds_read_b128 v[192:195], v222 offset:36864
	ds_read_b128 v[196:199], v222 offset:37888
	ds_read_b128 v[200:203], v222 offset:38912
	ds_read_b128 v[204:207], v222 offset:39936
	global_load_lds_dwordx4 v[160:161], off
	v_lshl_add_u64 v[160:161], s[30:31], 0, v[130:131]
	s_mov_b32 m0, s41
	s_nop 0
	global_load_lds_dwordx4 v[160:161], off
	s_waitcnt vmcnt(8)
	s_waitcnt lgkmcnt(0)
	s_barrier
	s_setprio 1
	s_waitcnt lgkmcnt(0)
	v_mfma_f32_16x16x32_bf16 v[124:127], v[140:143], v[176:179], v[124:127]
	v_mfma_f32_16x16x32_bf16 v[124:127], v[144:147], v[180:183], v[124:127]
	v_mfma_f32_16x16x32_bf16 v[120:123], v[148:151], v[176:179], v[120:123]
	v_mfma_f32_16x16x32_bf16 v[120:123], v[152:155], v[180:183], v[120:123]
	v_mfma_f32_16x16x32_bf16 v[116:119], v[140:143], v[184:187], v[116:119]
	v_mfma_f32_16x16x32_bf16 v[116:119], v[144:147], v[188:191], v[116:119]
	v_mfma_f32_16x16x32_bf16 v[112:115], v[148:151], v[184:187], v[112:115]
	v_mfma_f32_16x16x32_bf16 v[112:115], v[152:155], v[188:191], v[112:115]
	v_mfma_f32_16x16x32_bf16 v[104:107], v[140:143], v[192:195], v[104:107]
	v_mfma_f32_16x16x32_bf16 v[104:107], v[144:147], v[196:199], v[104:107]
	v_mfma_f32_16x16x32_bf16 v[96:99], v[148:151], v[192:195], v[96:99]
	v_mfma_f32_16x16x32_bf16 v[96:99], v[152:155], v[196:199], v[96:99]
	v_mfma_f32_16x16x32_bf16 v[88:91], v[140:143], v[200:203], v[88:91]
	v_mfma_f32_16x16x32_bf16 v[88:91], v[144:147], v[204:207], v[88:91]
	v_mfma_f32_16x16x32_bf16 v[80:83], v[148:151], v[200:203], v[80:83]
	v_mfma_f32_16x16x32_bf16 v[80:83], v[152:155], v[204:207], v[80:83]
	s_setprio 0
	s_setprio 1
	v_mfma_f32_16x16x32_bf16 v[108:111], v[156:159], v[176:179], v[108:111]
	v_mfma_f32_16x16x32_bf16 v[108:111], v[164:167], v[180:183], v[108:111]
	v_mfma_f32_16x16x32_bf16 v[100:103], v[168:171], v[176:179], v[100:103]
	v_mfma_f32_16x16x32_bf16 v[100:103], v[172:175], v[180:183], v[100:103]
	v_mfma_f32_16x16x32_bf16 v[92:95], v[156:159], v[184:187], v[92:95]
	v_mfma_f32_16x16x32_bf16 v[92:95], v[164:167], v[188:191], v[92:95]
	v_mfma_f32_16x16x32_bf16 v[84:87], v[168:171], v[184:187], v[84:87]
	v_mfma_f32_16x16x32_bf16 v[84:87], v[172:175], v[188:191], v[84:87]
	v_mfma_f32_16x16x32_bf16 v[76:79], v[156:159], v[192:195], v[76:79]
	v_mfma_f32_16x16x32_bf16 v[76:79], v[164:167], v[196:199], v[76:79]
	v_mfma_f32_16x16x32_bf16 v[72:75], v[168:171], v[192:195], v[72:75]
	v_mfma_f32_16x16x32_bf16 v[72:75], v[172:175], v[196:199], v[72:75]
	v_mfma_f32_16x16x32_bf16 v[68:71], v[156:159], v[200:203], v[68:71]
	v_mfma_f32_16x16x32_bf16 v[68:71], v[164:167], v[204:207], v[68:71]
	v_mfma_f32_16x16x32_bf16 v[64:67], v[168:171], v[200:203], v[64:67]
	v_mfma_f32_16x16x32_bf16 v[64:67], v[172:175], v[204:207], v[64:67]
	s_setprio 0
	s_barrier
	s_add_u32 s30, s28, 0x8000
	s_addc_u32 s31, s29, 0
	s_add_i32 s63, s63, s37
	v_lshl_add_u64 v[160:161], s[30:31], 0, v[128:129]
	s_mov_b32 m0, s63
	ds_read_b128 v[176:179], v222 offset:49152
	ds_read_b128 v[180:183], v222 offset:50176
	ds_read_b128 v[184:187], v222 offset:51200
	ds_read_b128 v[188:191], v222 offset:52224
	ds_read_b128 v[192:195], v222 offset:53248
	ds_read_b128 v[196:199], v222 offset:54272
	ds_read_b128 v[200:203], v222 offset:55296
	ds_read_b128 v[204:207], v222 offset:56320
	global_load_lds_dwordx4 v[160:161], off
	s_add_i32 m0, s63, 0x2000
	s_add_u32 s28, s28, 0xc000
	v_lshl_add_u64 v[160:161], s[30:31], 0, v[130:131]
	s_addc_u32 s29, s29, 0
	s_add_i32 s30, s64, s37
	global_load_lds_dwordx4 v[160:161], off
	v_lshl_add_u64 v[160:161], s[28:29], 0, v[128:129]
	s_mov_b32 m0, s30
	s_nop 0
	global_load_lds_dwordx4 v[160:161], off
	v_lshl_add_u64 v[160:161], s[28:29], 0, v[130:131]
	s_add_i32 m0, s30, 0x2000
	s_nop 0
	global_load_lds_dwordx4 v[160:161], off
	v_lshl_add_u64 v[160:161], s[26:27], 0, v[128:129]
	s_mov_b32 m0, s44
	s_nop 0
	global_load_lds_dwordx4 v[160:161], off
	v_lshl_add_u64 v[160:161], s[26:27], 0, v[130:131]
	s_mov_b32 m0, s45
	s_nop 0
	global_load_lds_dwordx4 v[160:161], off
	s_waitcnt vmcnt(8)
	s_waitcnt lgkmcnt(0)
	s_barrier
	s_setprio 1
	s_waitcnt lgkmcnt(0)
	v_mfma_f32_16x16x32_bf16 v[60:63], v[140:143], v[176:179], v[60:63]
	v_mfma_f32_16x16x32_bf16 v[60:63], v[144:147], v[180:183], v[60:63]
	v_mfma_f32_16x16x32_bf16 v[56:59], v[148:151], v[176:179], v[56:59]
	v_mfma_f32_16x16x32_bf16 v[56:59], v[152:155], v[180:183], v[56:59]
	v_mfma_f32_16x16x32_bf16 v[52:55], v[140:143], v[184:187], v[52:55]
	v_mfma_f32_16x16x32_bf16 v[52:55], v[144:147], v[188:191], v[52:55]
	v_mfma_f32_16x16x32_bf16 v[48:51], v[148:151], v[184:187], v[48:51]
	v_mfma_f32_16x16x32_bf16 v[48:51], v[152:155], v[188:191], v[48:51]
	v_mfma_f32_16x16x32_bf16 v[40:43], v[140:143], v[192:195], v[40:43]
	v_mfma_f32_16x16x32_bf16 v[40:43], v[144:147], v[196:199], v[40:43]
	v_mfma_f32_16x16x32_bf16 v[32:35], v[148:151], v[192:195], v[32:35]
	v_mfma_f32_16x16x32_bf16 v[32:35], v[152:155], v[196:199], v[32:35]
	v_mfma_f32_16x16x32_bf16 v[24:27], v[140:143], v[200:203], v[24:27]
	v_mfma_f32_16x16x32_bf16 v[24:27], v[144:147], v[204:207], v[24:27]
	v_mfma_f32_16x16x32_bf16 v[16:19], v[148:151], v[200:203], v[16:19]
	v_mfma_f32_16x16x32_bf16 v[16:19], v[152:155], v[204:207], v[16:19]
	s_setprio 0
	s_setprio 1
	v_mfma_f32_16x16x32_bf16 v[44:47], v[156:159], v[176:179], v[44:47]
	v_mfma_f32_16x16x32_bf16 v[44:47], v[164:167], v[180:183], v[44:47]
	v_mfma_f32_16x16x32_bf16 v[36:39], v[168:171], v[176:179], v[36:39]
	v_mfma_f32_16x16x32_bf16 v[36:39], v[172:175], v[180:183], v[36:39]
	v_mfma_f32_16x16x32_bf16 v[28:31], v[156:159], v[184:187], v[28:31]
	v_mfma_f32_16x16x32_bf16 v[28:31], v[164:167], v[188:191], v[28:31]
	v_mfma_f32_16x16x32_bf16 v[20:23], v[168:171], v[184:187], v[20:23]
	v_mfma_f32_16x16x32_bf16 v[20:23], v[172:175], v[188:191], v[20:23]
	v_mfma_f32_16x16x32_bf16 v[12:15], v[156:159], v[192:195], v[12:15]
	v_mfma_f32_16x16x32_bf16 v[12:15], v[164:167], v[196:199], v[12:15]
	v_mfma_f32_16x16x32_bf16 v[8:11], v[168:171], v[192:195], v[8:11]
	v_mfma_f32_16x16x32_bf16 v[8:11], v[172:175], v[196:199], v[8:11]
	v_mfma_f32_16x16x32_bf16 v[4:7], v[156:159], v[200:203], v[4:7]
	v_mfma_f32_16x16x32_bf16 v[4:7], v[164:167], v[204:207], v[4:7]
	v_mfma_f32_16x16x32_bf16 v[0:3], v[168:171], v[200:203], v[0:3]
	v_mfma_f32_16x16x32_bf16 v[0:3], v[172:175], v[204:207], v[0:3]
	s_setprio 0
	s_barrier
	s_add_u32 s24, s24, 0x10000
	s_addc_u32 s25, s25, 0
	s_add_u32 s60, s60, 0x10000
	s_addc_u32 s61, s61, 0
	s_cmp_ge_i32 s62, s43
	s_mov_b32 s26, s62
	s_cbranch_scc0 .LBB0_228
	v_pk_mul_f32 v[200:201], v[126:127], 0.5 op_sel_hi:[1,0]
	v_pk_mul_f32 v[202:203], v[124:125], 0.5 op_sel_hi:[1,0]
	v_pk_mul_f32 v[204:205], v[122:123], 0.5 op_sel_hi:[1,0]
	v_pk_mul_f32 v[206:207], v[120:121], 0.5 op_sel_hi:[1,0]
	v_pk_mul_f32 v[210:211], v[110:111], 0.5 op_sel_hi:[1,0]
	v_pk_mul_f32 v[208:209], v[108:109], 0.5 op_sel_hi:[1,0]
	v_pk_mul_f32 v[198:199], v[102:103], 0.5 op_sel_hi:[1,0]
	v_pk_mul_f32 v[196:197], v[100:101], 0.5 op_sel_hi:[1,0]
	v_pk_mul_f32 v[194:195], v[118:119], 0.5 op_sel_hi:[1,0]
	v_pk_mul_f32 v[192:193], v[116:117], 0.5 op_sel_hi:[1,0]
	v_pk_mul_f32 v[190:191], v[114:115], 0.5 op_sel_hi:[1,0]
	v_pk_mul_f32 v[188:189], v[112:113], 0.5 op_sel_hi:[1,0]
	v_pk_mul_f32 v[186:187], v[94:95], 0.5 op_sel_hi:[1,0]
	v_pk_mul_f32 v[184:185], v[92:93], 0.5 op_sel_hi:[1,0]
	v_pk_mul_f32 v[182:183], v[86:87], 0.5 op_sel_hi:[1,0]
	v_pk_mul_f32 v[180:181], v[84:85], 0.5 op_sel_hi:[1,0]
	v_pk_mul_f32 v[178:179], v[106:107], 0.5 op_sel_hi:[1,0]
	v_pk_mul_f32 v[176:177], v[104:105], 0.5 op_sel_hi:[1,0]
	v_pk_mul_f32 v[174:175], v[98:99], 0.5 op_sel_hi:[1,0]
	v_pk_mul_f32 v[172:173], v[96:97], 0.5 op_sel_hi:[1,0]
	v_pk_mul_f32 v[170:171], v[78:79], 0.5 op_sel_hi:[1,0]
	v_pk_mul_f32 v[168:169], v[76:77], 0.5 op_sel_hi:[1,0]
	v_pk_mul_f32 v[166:167], v[74:75], 0.5 op_sel_hi:[1,0]
	v_pk_mul_f32 v[164:165], v[72:73], 0.5 op_sel_hi:[1,0]
	v_pk_mul_f32 v[160:161], v[90:91], 0.5 op_sel_hi:[1,0]
	v_pk_mul_f32 v[158:159], v[88:89], 0.5 op_sel_hi:[1,0]
	v_pk_mul_f32 v[156:157], v[82:83], 0.5 op_sel_hi:[1,0]
	v_pk_mul_f32 v[154:155], v[80:81], 0.5 op_sel_hi:[1,0]
	v_pk_mul_f32 v[152:153], v[70:71], 0.5 op_sel_hi:[1,0]
	v_pk_mul_f32 v[150:151], v[68:69], 0.5 op_sel_hi:[1,0]
	v_pk_mul_f32 v[148:149], v[66:67], 0.5 op_sel_hi:[1,0]
	v_pk_mul_f32 v[146:147], v[64:65], 0.5 op_sel_hi:[1,0]
	v_pk_mul_f32 v[144:145], v[62:63], 0.5 op_sel_hi:[1,0]
	v_pk_mul_f32 v[142:143], v[60:61], 0.5 op_sel_hi:[1,0]
	v_pk_mul_f32 v[126:127], v[58:59], 0.5 op_sel_hi:[1,0]
	v_pk_mul_f32 v[124:125], v[56:57], 0.5 op_sel_hi:[1,0]
	v_pk_mul_f32 v[122:123], v[46:47], 0.5 op_sel_hi:[1,0]
	v_pk_mul_f32 v[120:121], v[44:45], 0.5 op_sel_hi:[1,0]
	v_pk_mul_f32 v[118:119], v[38:39], 0.5 op_sel_hi:[1,0]
	v_pk_mul_f32 v[116:117], v[36:37], 0.5 op_sel_hi:[1,0]
	v_pk_mul_f32 v[114:115], v[54:55], 0.5 op_sel_hi:[1,0]
	v_pk_mul_f32 v[112:113], v[52:53], 0.5 op_sel_hi:[1,0]
	v_pk_mul_f32 v[110:111], v[50:51], 0.5 op_sel_hi:[1,0]
	v_pk_mul_f32 v[108:109], v[48:49], 0.5 op_sel_hi:[1,0]
	v_pk_mul_f32 v[106:107], v[30:31], 0.5 op_sel_hi:[1,0]
	v_pk_mul_f32 v[104:105], v[28:29], 0.5 op_sel_hi:[1,0]
	v_pk_mul_f32 v[102:103], v[22:23], 0.5 op_sel_hi:[1,0]
	v_pk_mul_f32 v[100:101], v[20:21], 0.5 op_sel_hi:[1,0]
	v_pk_mul_f32 v[98:99], v[42:43], 0.5 op_sel_hi:[1,0]
	v_pk_mul_f32 v[96:97], v[40:41], 0.5 op_sel_hi:[1,0]
	v_pk_mul_f32 v[94:95], v[34:35], 0.5 op_sel_hi:[1,0]
	v_pk_mul_f32 v[92:93], v[32:33], 0.5 op_sel_hi:[1,0]
	v_pk_mul_f32 v[90:91], v[14:15], 0.5 op_sel_hi:[1,0]
	v_pk_mul_f32 v[88:89], v[12:13], 0.5 op_sel_hi:[1,0]
	v_pk_mul_f32 v[86:87], v[10:11], 0.5 op_sel_hi:[1,0]
	v_pk_mul_f32 v[84:85], v[8:9], 0.5 op_sel_hi:[1,0]
	v_pk_mul_f32 v[82:83], v[26:27], 0.5 op_sel_hi:[1,0]
	v_pk_mul_f32 v[80:81], v[24:25], 0.5 op_sel_hi:[1,0]
	v_pk_mul_f32 v[78:79], v[18:19], 0.5 op_sel_hi:[1,0]
	v_pk_mul_f32 v[76:77], v[16:17], 0.5 op_sel_hi:[1,0]
	v_pk_mul_f32 v[74:75], v[6:7], 0.5 op_sel_hi:[1,0]
	v_pk_mul_f32 v[72:73], v[4:5], 0.5 op_sel_hi:[1,0]
	v_pk_mul_f32 v[70:71], v[2:3], 0.5 op_sel_hi:[1,0]
	v_pk_mul_f32 v[68:69], v[0:1], 0.5 op_sel_hi:[1,0]

.LBB0_323:
	ds_read_b128 v[128:131], v222
	ds_read_b128 v[132:135], v222 offset:1024
	ds_read_b128 v[136:139], v222 offset:2048
	ds_read_b128 v[140:143], v222 offset:3072
	ds_read_b128 v[144:147], v223
	ds_read_b128 v[148:151], v223 offset:1024
	ds_read_b128 v[152:155], v223 offset:2048
	ds_read_b128 v[156:159], v223 offset:3072
	s_add_i32 s53, s50, 2
	s_add_u32 s54, s0, 0x80
	s_addc_u32 s51, s1, 0
	s_cmp_eq_u32 s78, s50
	s_cselect_b32 s50, s46, s54
	s_cselect_b32 s51, s47, s51
	s_cselect_b32 s55, s49, s52
	s_cselect_b32 s54, s48, s33
	v_lshl_add_u64 v[160:161], s[0:1], 0, v[176:177]
	s_add_i32 m0, s71, 0xc000
	ds_read_b128 v[184:187], v224
	ds_read_b128 v[188:191], v224 offset:1024
	ds_read_b128 v[192:195], v224 offset:2048
	ds_read_b128 v[196:199], v224 offset:3072
	ds_read_b128 v[200:203], v224 offset:4096
	ds_read_b128 v[204:207], v224 offset:5120
	ds_read_b128 v[208:211], v224 offset:6144
	ds_read_b128 v[212:215], v224 offset:7168
	global_load_lds_dwordx4 v[160:161], off
	v_lshl_add_u64 v[160:161], s[0:1], 0, v[178:179]
	s_add_i32 m0, s71, 0xe000
	s_nop 0
	global_load_lds_dwordx4 v[160:161], off
	s_waitcnt vmcnt(8)
	s_waitcnt lgkmcnt(0)
	s_barrier
	s_setprio 1
	s_waitcnt lgkmcnt(0)
	v_mfma_f32_16x16x32_bf16 v[124:127], v[128:131], v[184:187], v[124:127]
	v_mfma_f32_16x16x32_bf16 v[124:127], v[132:135], v[188:191], v[124:127]
	v_mfma_f32_16x16x32_bf16 v[120:123], v[136:139], v[184:187], v[120:123]
	v_mfma_f32_16x16x32_bf16 v[120:123], v[140:143], v[188:191], v[120:123]
	v_mfma_f32_16x16x32_bf16 v[108:111], v[128:131], v[192:195], v[108:111]
	v_mfma_f32_16x16x32_bf16 v[108:111], v[132:135], v[196:199], v[108:111]
	v_mfma_f32_16x16x32_bf16 v[104:107], v[136:139], v[192:195], v[104:107]
	v_mfma_f32_16x16x32_bf16 v[104:107], v[140:143], v[196:199], v[104:107]
	v_mfma_f32_16x16x32_bf16 v[92:95], v[128:131], v[200:203], v[92:95]
	v_mfma_f32_16x16x32_bf16 v[92:95], v[132:135], v[204:207], v[92:95]
	v_mfma_f32_16x16x32_bf16 v[88:91], v[136:139], v[200:203], v[88:91]
	v_mfma_f32_16x16x32_bf16 v[88:91], v[140:143], v[204:207], v[88:91]
	v_mfma_f32_16x16x32_bf16 v[76:79], v[128:131], v[208:211], v[76:79]
	v_mfma_f32_16x16x32_bf16 v[76:79], v[132:135], v[212:215], v[76:79]
	v_mfma_f32_16x16x32_bf16 v[72:75], v[136:139], v[208:211], v[72:75]
	v_mfma_f32_16x16x32_bf16 v[72:75], v[140:143], v[212:215], v[72:75]
	s_setprio 0
	s_setprio 1
	v_mfma_f32_16x16x32_bf16 v[116:119], v[144:147], v[184:187], v[116:119]
	v_mfma_f32_16x16x32_bf16 v[116:119], v[148:151], v[188:191], v[116:119]
	v_mfma_f32_16x16x32_bf16 v[112:115], v[152:155], v[184:187], v[112:115]
	v_mfma_f32_16x16x32_bf16 v[112:115], v[156:159], v[188:191], v[112:115]
	v_mfma_f32_16x16x32_bf16 v[100:103], v[144:147], v[192:195], v[100:103]
	v_mfma_f32_16x16x32_bf16 v[100:103], v[148:151], v[196:199], v[100:103]
	v_mfma_f32_16x16x32_bf16 v[96:99], v[152:155], v[192:195], v[96:99]
	v_mfma_f32_16x16x32_bf16 v[96:99], v[156:159], v[196:199], v[96:99]
	v_mfma_f32_16x16x32_bf16 v[84:87], v[144:147], v[200:203], v[84:87]
	v_mfma_f32_16x16x32_bf16 v[84:87], v[148:151], v[204:207], v[84:87]
	v_mfma_f32_16x16x32_bf16 v[80:83], v[152:155], v[200:203], v[80:83]
	v_mfma_f32_16x16x32_bf16 v[80:83], v[156:159], v[204:207], v[80:83]
	v_mfma_f32_16x16x32_bf16 v[68:71], v[144:147], v[208:211], v[68:71]
	v_mfma_f32_16x16x32_bf16 v[68:71], v[148:151], v[212:215], v[68:71]
	v_mfma_f32_16x16x32_bf16 v[64:67], v[152:155], v[208:211], v[64:67]
	v_mfma_f32_16x16x32_bf16 v[64:67], v[156:159], v[212:215], v[64:67]
	s_setprio 0
	s_barrier
	s_add_i32 s60, s82, s70
	v_lshl_add_u64 v[160:161], s[54:55], 0, v[166:167]
	s_mov_b32 m0, s60
	ds_read_b128 v[184:187], v224 offset:16384
	ds_read_b128 v[188:191], v224 offset:17408
	ds_read_b128 v[192:195], v224 offset:18432
	ds_read_b128 v[196:199], v224 offset:19456
	ds_read_b128 v[200:203], v224 offset:20480
	ds_read_b128 v[204:207], v224 offset:21504
	ds_read_b128 v[208:211], v224 offset:22528
	ds_read_b128 v[212:215], v224 offset:23552
	global_load_lds_dwordx4 v[160:161], off
	s_add_i32 m0, s60, 0x2000
	v_lshl_add_u64 v[216:217], s[54:55], 0, v[170:171]
	s_add_u32 s54, s54, s10
	s_addc_u32 s55, s55, s11
	s_add_i32 s60, s83, s70
	global_load_lds_dwordx4 v[216:217], off
	v_lshl_add_u64 v[218:219], s[54:55], 0, v[166:167]
	s_mov_b32 m0, s60
	v_lshl_add_u64 v[230:231], s[54:55], 0, v[170:171]
	global_load_lds_dwordx4 v[218:219], off
	s_add_i32 m0, s60, 0x2000
	v_lshl_add_u64 v[232:233], s[50:51], 0, v[164:165]
	global_load_lds_dwordx4 v[230:231], off
	s_mov_b32 m0, s71
	v_lshl_add_u64 v[234:235], s[50:51], 0, v[168:169]
	global_load_lds_dwordx4 v[232:233], off
	s_mov_b32 m0, s72
	s_nop 0
	global_load_lds_dwordx4 v[234:235], off
	s_waitcnt vmcnt(8)
	s_waitcnt lgkmcnt(0)
	s_barrier
	s_setprio 1
	s_waitcnt lgkmcnt(0)
	v_mfma_f32_16x16x32_bf16 v[60:63], v[128:131], v[184:187], v[60:63]
	v_mfma_f32_16x16x32_bf16 v[60:63], v[132:135], v[188:191], v[60:63]
	v_mfma_f32_16x16x32_bf16 v[56:59], v[136:139], v[184:187], v[56:59]
	v_mfma_f32_16x16x32_bf16 v[56:59], v[140:143], v[188:191], v[56:59]
	v_mfma_f32_16x16x32_bf16 v[44:47], v[128:131], v[192:195], v[44:47]
	v_mfma_f32_16x16x32_bf16 v[44:47], v[132:135], v[196:199], v[44:47]
	v_mfma_f32_16x16x32_bf16 v[40:43], v[136:139], v[192:195], v[40:43]
	v_mfma_f32_16x16x32_bf16 v[40:43], v[140:143], v[196:199], v[40:43]
	v_mfma_f32_16x16x32_bf16 v[28:31], v[128:131], v[200:203], v[28:31]
	v_mfma_f32_16x16x32_bf16 v[28:31], v[132:135], v[204:207], v[28:31]
	v_mfma_f32_16x16x32_bf16 v[24:27], v[136:139], v[200:203], v[24:27]
	v_mfma_f32_16x16x32_bf16 v[24:27], v[140:143], v[204:207], v[24:27]
	v_mfma_f32_16x16x32_bf16 v[12:15], v[128:131], v[208:211], v[12:15]
	v_mfma_f32_16x16x32_bf16 v[12:15], v[132:135], v[212:215], v[12:15]
	v_mfma_f32_16x16x32_bf16 v[8:11], v[136:139], v[208:211], v[8:11]
	v_mfma_f32_16x16x32_bf16 v[8:11], v[140:143], v[212:215], v[8:11]
	s_setprio 0
	s_setprio 1
	v_mfma_f32_16x16x32_bf16 v[52:55], v[144:147], v[184:187], v[52:55]
	v_mfma_f32_16x16x32_bf16 v[52:55], v[148:151], v[188:191], v[52:55]
	v_mfma_f32_16x16x32_bf16 v[48:51], v[152:155], v[184:187], v[48:51]
	v_mfma_f32_16x16x32_bf16 v[48:51], v[156:159], v[188:191], v[48:51]
	v_mfma_f32_16x16x32_bf16 v[36:39], v[144:147], v[192:195], v[36:39]
	v_mfma_f32_16x16x32_bf16 v[36:39], v[148:151], v[196:199], v[36:39]
	v_mfma_f32_16x16x32_bf16 v[32:35], v[152:155], v[192:195], v[32:35]
	v_mfma_f32_16x16x32_bf16 v[32:35], v[156:159], v[196:199], v[32:35]
	v_mfma_f32_16x16x32_bf16 v[20:23], v[144:147], v[200:203], v[20:23]
	v_mfma_f32_16x16x32_bf16 v[20:23], v[148:151], v[204:207], v[20:23]
	v_mfma_f32_16x16x32_bf16 v[16:19], v[152:155], v[200:203], v[16:19]
	v_mfma_f32_16x16x32_bf16 v[16:19], v[156:159], v[204:207], v[16:19]
	v_mfma_f32_16x16x32_bf16 v[4:7], v[144:147], v[208:211], v[4:7]
	v_mfma_f32_16x16x32_bf16 v[4:7], v[148:151], v[212:215], v[4:7]
	v_mfma_f32_16x16x32_bf16 v[0:3], v[152:155], v[208:211], v[0:3]
	v_mfma_f32_16x16x32_bf16 v[0:3], v[156:159], v[212:215], v[0:3]
	s_setprio 0
	s_barrier
	s_add_i32 s54, 0, 0x18000
	s_add_i32 s55, 0, 0x1c000
	v_add_u32_e32 v140, s54, v221
	v_add_u32_e32 v156, s55, v221
	ds_read_b128 v[128:131], v140
	ds_read_b128 v[132:135], v140 offset:1024
	ds_read_b128 v[136:139], v140 offset:2048
	ds_read_b128 v[140:143], v140 offset:3072
	ds_read_b128 v[144:147], v156
	ds_read_b128 v[148:151], v156 offset:1024
	ds_read_b128 v[152:155], v156 offset:2048
	ds_read_b128 v[156:159], v156 offset:3072
	s_add_u32 s50, s50, s10
	s_addc_u32 s51, s51, s11
	s_mov_b32 m0, s73
	v_lshl_add_u64 v[236:237], s[50:51], 0, v[164:165]
	ds_read_b128 v[184:187], v224 offset:32768
	ds_read_b128 v[188:191], v224 offset:33792
	ds_read_b128 v[192:195], v224 offset:34816
	ds_read_b128 v[196:199], v224 offset:35840
	ds_read_b128 v[200:203], v224 offset:36864
	ds_read_b128 v[204:207], v224 offset:37888
	ds_read_b128 v[208:211], v224 offset:38912
	ds_read_b128 v[212:215], v224 offset:39936
	global_load_lds_dwordx4 v[236:237], off
	v_lshl_add_u64 v[236:237], s[50:51], 0, v[168:169]
	s_mov_b32 m0, s74
	s_nop 0
	global_load_lds_dwordx4 v[236:237], off
	s_waitcnt vmcnt(8)
	s_waitcnt lgkmcnt(0)
	s_barrier
	s_setprio 1
	s_waitcnt lgkmcnt(0)
	v_mfma_f32_16x16x32_bf16 v[124:127], v[128:131], v[184:187], v[124:127]
	v_mfma_f32_16x16x32_bf16 v[124:127], v[132:135], v[188:191], v[124:127]
	v_mfma_f32_16x16x32_bf16 v[120:123], v[136:139], v[184:187], v[120:123]
	v_mfma_f32_16x16x32_bf16 v[120:123], v[140:143], v[188:191], v[120:123]
	v_mfma_f32_16x16x32_bf16 v[108:111], v[128:131], v[192:195], v[108:111]
	v_mfma_f32_16x16x32_bf16 v[108:111], v[132:135], v[196:199], v[108:111]
	v_mfma_f32_16x16x32_bf16 v[104:107], v[136:139], v[192:195], v[104:107]
	v_mfma_f32_16x16x32_bf16 v[104:107], v[140:143], v[196:199], v[104:107]
	v_mfma_f32_16x16x32_bf16 v[92:95], v[128:131], v[200:203], v[92:95]
	v_mfma_f32_16x16x32_bf16 v[92:95], v[132:135], v[204:207], v[92:95]
	v_mfma_f32_16x16x32_bf16 v[88:91], v[136:139], v[200:203], v[88:91]
	v_mfma_f32_16x16x32_bf16 v[88:91], v[140:143], v[204:207], v[88:91]
	v_mfma_f32_16x16x32_bf16 v[76:79], v[128:131], v[208:211], v[76:79]
	v_mfma_f32_16x16x32_bf16 v[76:79], v[132:135], v[212:215], v[76:79]
	v_mfma_f32_16x16x32_bf16 v[72:75], v[136:139], v[208:211], v[72:75]
	v_mfma_f32_16x16x32_bf16 v[72:75], v[140:143], v[212:215], v[72:75]
	s_setprio 0
	s_setprio 1
	v_mfma_f32_16x16x32_bf16 v[116:119], v[144:147], v[184:187], v[116:119]
	v_mfma_f32_16x16x32_bf16 v[116:119], v[148:151], v[188:191], v[116:119]
	v_mfma_f32_16x16x32_bf16 v[112:115], v[152:155], v[184:187], v[112:115]
	v_mfma_f32_16x16x32_bf16 v[112:115], v[156:159], v[188:191], v[112:115]
	v_mfma_f32_16x16x32_bf16 v[100:103], v[144:147], v[192:195], v[100:103]
	v_mfma_f32_16x16x32_bf16 v[100:103], v[148:151], v[196:199], v[100:103]
	v_mfma_f32_16x16x32_bf16 v[96:99], v[152:155], v[192:195], v[96:99]
	v_mfma_f32_16x16x32_bf16 v[96:99], v[156:159], v[196:199], v[96:99]
	v_mfma_f32_16x16x32_bf16 v[84:87], v[144:147], v[200:203], v[84:87]
	v_mfma_f32_16x16x32_bf16 v[84:87], v[148:151], v[204:207], v[84:87]
	v_mfma_f32_16x16x32_bf16 v[80:83], v[152:155], v[200:203], v[80:83]
	v_mfma_f32_16x16x32_bf16 v[80:83], v[156:159], v[204:207], v[80:83]
	v_mfma_f32_16x16x32_bf16 v[68:71], v[144:147], v[208:211], v[68:71]
	v_mfma_f32_16x16x32_bf16 v[68:71], v[148:151], v[212:215], v[68:71]
	v_mfma_f32_16x16x32_bf16 v[64:67], v[152:155], v[208:211], v[64:67]
	v_mfma_f32_16x16x32_bf16 v[64:67], v[156:159], v[212:215], v[64:67]
	s_setprio 0
	s_barrier
	s_add_i32 s50, s54, s70
	v_lshl_add_u64 v[160:161], v[160:161], 0, s[36:37]
	s_mov_b32 m0, s50
	ds_read_b128 v[184:187], v224 offset:49152
	ds_read_b128 v[188:191], v224 offset:50176
	ds_read_b128 v[192:195], v224 offset:51200
	ds_read_b128 v[196:199], v224 offset:52224
	ds_read_b128 v[200:203], v224 offset:53248
	ds_read_b128 v[204:207], v224 offset:54272
	ds_read_b128 v[208:211], v224 offset:55296
	ds_read_b128 v[212:215], v224 offset:56320
	global_load_lds_dwordx4 v[160:161], off
	v_lshl_add_u64 v[160:161], v[216:217], 0, s[36:37]
	s_add_i32 m0, s50, 0x2000
	s_add_i32 s50, s55, s70
	global_load_lds_dwordx4 v[160:161], off
	v_lshl_add_u64 v[160:161], v[218:219], 0, s[36:37]
	s_mov_b32 m0, s50
	s_nop 0
	global_load_lds_dwordx4 v[160:161], off
	v_lshl_add_u64 v[160:161], v[230:231], 0, s[36:37]
	s_add_i32 m0, s50, 0x2000
	s_nop 0
	global_load_lds_dwordx4 v[160:161], off
	v_lshl_add_u64 v[160:161], v[232:233], 0, s[36:37]
	s_mov_b32 m0, s76
	s_nop 0
	global_load_lds_dwordx4 v[160:161], off
	v_lshl_add_u64 v[160:161], v[234:235], 0, s[36:37]
	s_mov_b32 m0, s77
	s_nop 0
	global_load_lds_dwordx4 v[160:161], off
	s_waitcnt vmcnt(8)
	s_waitcnt lgkmcnt(0)
	s_barrier
	s_setprio 1
	s_waitcnt lgkmcnt(0)
	v_mfma_f32_16x16x32_bf16 v[60:63], v[128:131], v[184:187], v[60:63]
	v_mfma_f32_16x16x32_bf16 v[60:63], v[132:135], v[188:191], v[60:63]
	v_mfma_f32_16x16x32_bf16 v[56:59], v[136:139], v[184:187], v[56:59]
	v_mfma_f32_16x16x32_bf16 v[56:59], v[140:143], v[188:191], v[56:59]
	v_mfma_f32_16x16x32_bf16 v[44:47], v[128:131], v[192:195], v[44:47]
	v_mfma_f32_16x16x32_bf16 v[44:47], v[132:135], v[196:199], v[44:47]
	v_mfma_f32_16x16x32_bf16 v[40:43], v[136:139], v[192:195], v[40:43]
	v_mfma_f32_16x16x32_bf16 v[40:43], v[140:143], v[196:199], v[40:43]
	v_mfma_f32_16x16x32_bf16 v[28:31], v[128:131], v[200:203], v[28:31]
	v_mfma_f32_16x16x32_bf16 v[28:31], v[132:135], v[204:207], v[28:31]
	v_mfma_f32_16x16x32_bf16 v[24:27], v[136:139], v[200:203], v[24:27]
	v_mfma_f32_16x16x32_bf16 v[24:27], v[140:143], v[204:207], v[24:27]
	v_mfma_f32_16x16x32_bf16 v[12:15], v[128:131], v[208:211], v[12:15]
	v_mfma_f32_16x16x32_bf16 v[12:15], v[132:135], v[212:215], v[12:15]
	v_mfma_f32_16x16x32_bf16 v[8:11], v[136:139], v[208:211], v[8:11]
	v_mfma_f32_16x16x32_bf16 v[8:11], v[140:143], v[212:215], v[8:11]
	s_setprio 0
	s_setprio 1
	v_mfma_f32_16x16x32_bf16 v[52:55], v[144:147], v[184:187], v[52:55]
	v_mfma_f32_16x16x32_bf16 v[52:55], v[148:151], v[188:191], v[52:55]
	v_mfma_f32_16x16x32_bf16 v[48:51], v[152:155], v[184:187], v[48:51]
	v_mfma_f32_16x16x32_bf16 v[48:51], v[156:159], v[188:191], v[48:51]
	v_mfma_f32_16x16x32_bf16 v[36:39], v[144:147], v[192:195], v[36:39]
	v_mfma_f32_16x16x32_bf16 v[36:39], v[148:151], v[196:199], v[36:39]
	v_mfma_f32_16x16x32_bf16 v[32:35], v[152:155], v[192:195], v[32:35]
	v_mfma_f32_16x16x32_bf16 v[32:35], v[156:159], v[196:199], v[32:35]
	v_mfma_f32_16x16x32_bf16 v[20:23], v[144:147], v[200:203], v[20:23]
	v_mfma_f32_16x16x32_bf16 v[20:23], v[148:151], v[204:207], v[20:23]
	v_mfma_f32_16x16x32_bf16 v[16:19], v[152:155], v[200:203], v[16:19]
	v_mfma_f32_16x16x32_bf16 v[16:19], v[156:159], v[204:207], v[16:19]
	v_mfma_f32_16x16x32_bf16 v[4:7], v[144:147], v[208:211], v[4:7]
	v_mfma_f32_16x16x32_bf16 v[4:7], v[148:151], v[212:215], v[4:7]
	v_mfma_f32_16x16x32_bf16 v[0:3], v[152:155], v[208:211], v[0:3]
	v_mfma_f32_16x16x32_bf16 v[0:3], v[156:159], v[212:215], v[0:3]
	s_setprio 0
	s_barrier
	s_add_u32 s0, s0, 0x100
	s_addc_u32 s1, s1, 0
	s_add_u32 s33, s33, 0x100
	s_addc_u32 s52, s52, 0
	s_cmp_ge_i32 s53, s75
	s_mov_b32 s50, s53
	s_cbranch_scc0 .LBB0_323

.LBB0_592:
	ds_read_b128 v[144:147], v157
	ds_read_b128 v[148:151], v157 offset:1024
	ds_read_b128 v[164:167], v157 offset:2048
	ds_read_b128 v[168:171], v157 offset:3072
	ds_read_b128 v[172:175], v158
	ds_read_b128 v[176:179], v158 offset:1024
	ds_read_b128 v[180:183], v158 offset:2048
	ds_read_b128 v[184:187], v158 offset:3072
	s_add_i32 s64, s34, 2
	s_add_u32 s65, s30, 0x80
	s_addc_u32 s35, s31, 0
	s_cmp_eq_u32 s49, s34
	s_cselect_b32 s34, s2, s65
	s_cselect_b32 s35, s3, s35
	s_cselect_b32 s67, s29, s63
	s_cselect_b32 s66, s28, s62
	v_lshl_add_u64 v[152:153], s[30:31], 0, v[136:137]
	s_add_i32 m0, s41, 0xc000
	ds_read_b128 v[188:191], v159
	ds_read_b128 v[192:195], v159 offset:1024
	ds_read_b128 v[196:199], v159 offset:2048
	ds_read_b128 v[200:203], v159 offset:3072
	ds_read_b128 v[204:207], v159 offset:4096
	ds_read_b128 v[208:211], v159 offset:5120
	ds_read_b128 v[212:215], v159 offset:6144
	ds_read_b128 v[216:219], v159 offset:7168
	global_load_lds_dwordx4 v[152:153], off
	v_lshl_add_u64 v[152:153], s[30:31], 0, v[138:139]
	s_add_i32 m0, s41, 0xe000
	s_nop 0
	global_load_lds_dwordx4 v[152:153], off
	s_waitcnt vmcnt(8)
	s_waitcnt lgkmcnt(0)
	s_barrier
	s_setprio 1
	s_waitcnt lgkmcnt(0)
	v_mfma_f32_16x16x32_bf16 v[120:123], v[144:147], v[188:191], v[120:123]
	v_mfma_f32_16x16x32_bf16 v[120:123], v[148:151], v[192:195], v[120:123]
	v_mfma_f32_16x16x32_bf16 v[124:127], v[164:167], v[188:191], v[124:127]
	v_mfma_f32_16x16x32_bf16 v[124:127], v[168:171], v[192:195], v[124:127]
	v_mfma_f32_16x16x32_bf16 v[108:111], v[144:147], v[196:199], v[108:111]
	v_mfma_f32_16x16x32_bf16 v[108:111], v[148:151], v[200:203], v[108:111]
	v_mfma_f32_16x16x32_bf16 v[104:107], v[164:167], v[196:199], v[104:107]
	v_mfma_f32_16x16x32_bf16 v[104:107], v[168:171], v[200:203], v[104:107]
	v_mfma_f32_16x16x32_bf16 v[92:95], v[144:147], v[204:207], v[92:95]
	v_mfma_f32_16x16x32_bf16 v[92:95], v[148:151], v[208:211], v[92:95]
	v_mfma_f32_16x16x32_bf16 v[88:91], v[164:167], v[204:207], v[88:91]
	v_mfma_f32_16x16x32_bf16 v[88:91], v[168:171], v[208:211], v[88:91]
	v_mfma_f32_16x16x32_bf16 v[76:79], v[144:147], v[212:215], v[76:79]
	v_mfma_f32_16x16x32_bf16 v[76:79], v[148:151], v[216:219], v[76:79]
	v_mfma_f32_16x16x32_bf16 v[72:75], v[164:167], v[212:215], v[72:75]
	v_mfma_f32_16x16x32_bf16 v[72:75], v[168:171], v[216:219], v[72:75]
	s_setprio 0
	s_setprio 1
	v_mfma_f32_16x16x32_bf16 v[116:119], v[172:175], v[188:191], v[116:119]
	v_mfma_f32_16x16x32_bf16 v[116:119], v[176:179], v[192:195], v[116:119]
	v_mfma_f32_16x16x32_bf16 v[112:115], v[180:183], v[188:191], v[112:115]
	v_mfma_f32_16x16x32_bf16 v[112:115], v[184:187], v[192:195], v[112:115]
	v_mfma_f32_16x16x32_bf16 v[100:103], v[172:175], v[196:199], v[100:103]
	v_mfma_f32_16x16x32_bf16 v[100:103], v[176:179], v[200:203], v[100:103]
	v_mfma_f32_16x16x32_bf16 v[96:99], v[180:183], v[196:199], v[96:99]
	v_mfma_f32_16x16x32_bf16 v[96:99], v[184:187], v[200:203], v[96:99]
	v_mfma_f32_16x16x32_bf16 v[84:87], v[172:175], v[204:207], v[84:87]
	v_mfma_f32_16x16x32_bf16 v[84:87], v[176:179], v[208:211], v[84:87]
	v_mfma_f32_16x16x32_bf16 v[80:83], v[180:183], v[204:207], v[80:83]
	v_mfma_f32_16x16x32_bf16 v[80:83], v[184:187], v[208:211], v[80:83]
	v_mfma_f32_16x16x32_bf16 v[68:71], v[172:175], v[212:215], v[68:71]
	v_mfma_f32_16x16x32_bf16 v[68:71], v[176:179], v[216:219], v[68:71]
	v_mfma_f32_16x16x32_bf16 v[64:67], v[180:183], v[212:215], v[64:67]
	v_mfma_f32_16x16x32_bf16 v[64:67], v[184:187], v[216:219], v[64:67]
	s_setprio 0
	s_barrier
	s_add_i32 s65, s52, s40
	v_lshl_add_u64 v[152:153], s[66:67], 0, v[130:131]
	s_mov_b32 m0, s65
	ds_read_b128 v[188:191], v159 offset:16384
	ds_read_b128 v[192:195], v159 offset:17408
	ds_read_b128 v[196:199], v159 offset:18432
	ds_read_b128 v[200:203], v159 offset:19456
	ds_read_b128 v[204:207], v159 offset:20480
	ds_read_b128 v[208:211], v159 offset:21504
	ds_read_b128 v[212:215], v159 offset:22528
	ds_read_b128 v[216:219], v159 offset:23552
	global_load_lds_dwordx4 v[152:153], off
	s_add_i32 m0, s65, 0x2000
	v_lshl_add_u64 v[160:161], s[66:67], 0, v[134:135]
	s_add_u32 s66, s66, s8
	s_addc_u32 s67, s67, s9
	s_add_i32 s65, s53, s40
	global_load_lds_dwordx4 v[160:161], off
	v_lshl_add_u64 v[222:223], s[66:67], 0, v[130:131]
	s_mov_b32 m0, s65
	v_lshl_add_u64 v[224:225], s[66:67], 0, v[134:135]
	global_load_lds_dwordx4 v[222:223], off
	s_add_i32 m0, s65, 0x2000
	v_lshl_add_u64 v[226:227], s[34:35], 0, v[128:129]
	global_load_lds_dwordx4 v[224:225], off
	s_mov_b32 m0, s41
	v_lshl_add_u64 v[228:229], s[34:35], 0, v[132:133]
	global_load_lds_dwordx4 v[226:227], off
	s_mov_b32 m0, s42
	s_nop 0
	global_load_lds_dwordx4 v[228:229], off
	s_waitcnt vmcnt(8)
	s_waitcnt lgkmcnt(0)
	s_barrier
	s_setprio 1
	s_waitcnt lgkmcnt(0)
	v_mfma_f32_16x16x32_bf16 v[60:63], v[144:147], v[188:191], v[60:63]
	v_mfma_f32_16x16x32_bf16 v[60:63], v[148:151], v[192:195], v[60:63]
	v_mfma_f32_16x16x32_bf16 v[56:59], v[164:167], v[188:191], v[56:59]
	v_mfma_f32_16x16x32_bf16 v[56:59], v[168:171], v[192:195], v[56:59]
	v_mfma_f32_16x16x32_bf16 v[44:47], v[144:147], v[196:199], v[44:47]
	v_mfma_f32_16x16x32_bf16 v[44:47], v[148:151], v[200:203], v[44:47]
	v_mfma_f32_16x16x32_bf16 v[40:43], v[164:167], v[196:199], v[40:43]
	v_mfma_f32_16x16x32_bf16 v[40:43], v[168:171], v[200:203], v[40:43]
	v_mfma_f32_16x16x32_bf16 v[28:31], v[144:147], v[204:207], v[28:31]
	v_mfma_f32_16x16x32_bf16 v[28:31], v[148:151], v[208:211], v[28:31]
	v_mfma_f32_16x16x32_bf16 v[24:27], v[164:167], v[204:207], v[24:27]
	v_mfma_f32_16x16x32_bf16 v[24:27], v[168:171], v[208:211], v[24:27]
	v_mfma_f32_16x16x32_bf16 v[12:15], v[144:147], v[212:215], v[12:15]
	v_mfma_f32_16x16x32_bf16 v[12:15], v[148:151], v[216:219], v[12:15]
	v_mfma_f32_16x16x32_bf16 v[8:11], v[164:167], v[212:215], v[8:11]
	v_mfma_f32_16x16x32_bf16 v[8:11], v[168:171], v[216:219], v[8:11]
	s_setprio 0
	s_setprio 1
	v_mfma_f32_16x16x32_bf16 v[52:55], v[172:175], v[188:191], v[52:55]
	v_mfma_f32_16x16x32_bf16 v[52:55], v[176:179], v[192:195], v[52:55]
	v_mfma_f32_16x16x32_bf16 v[48:51], v[180:183], v[188:191], v[48:51]
	v_mfma_f32_16x16x32_bf16 v[48:51], v[184:187], v[192:195], v[48:51]
	v_mfma_f32_16x16x32_bf16 v[36:39], v[172:175], v[196:199], v[36:39]
	v_mfma_f32_16x16x32_bf16 v[36:39], v[176:179], v[200:203], v[36:39]
	v_mfma_f32_16x16x32_bf16 v[32:35], v[180:183], v[196:199], v[32:35]
	v_mfma_f32_16x16x32_bf16 v[32:35], v[184:187], v[200:203], v[32:35]
	v_mfma_f32_16x16x32_bf16 v[20:23], v[172:175], v[204:207], v[20:23]
	v_mfma_f32_16x16x32_bf16 v[20:23], v[176:179], v[208:211], v[20:23]
	v_mfma_f32_16x16x32_bf16 v[16:19], v[180:183], v[204:207], v[16:19]
	v_mfma_f32_16x16x32_bf16 v[16:19], v[184:187], v[208:211], v[16:19]
	v_mfma_f32_16x16x32_bf16 v[4:7], v[172:175], v[212:215], v[4:7]
	v_mfma_f32_16x16x32_bf16 v[4:7], v[176:179], v[216:219], v[4:7]
	v_mfma_f32_16x16x32_bf16 v[0:3], v[180:183], v[212:215], v[0:3]
	v_mfma_f32_16x16x32_bf16 v[0:3], v[184:187], v[216:219], v[0:3]
	s_setprio 0
	s_barrier
	s_add_i32 s65, 0, 0x18000
	s_add_i32 s66, 0, 0x1c000
	v_add_u32_e32 v168, s65, v155
	v_add_u32_e32 v184, s66, v155
	ds_read_b128 v[144:147], v168
	ds_read_b128 v[148:151], v168 offset:1024
	ds_read_b128 v[164:167], v168 offset:2048
	ds_read_b128 v[168:171], v168 offset:3072
	ds_read_b128 v[172:175], v184
	ds_read_b128 v[176:179], v184 offset:1024
	ds_read_b128 v[180:183], v184 offset:2048
	ds_read_b128 v[184:187], v184 offset:3072
	s_add_u32 s34, s34, s8
	s_addc_u32 s35, s35, s9
	s_mov_b32 m0, s43
	v_lshl_add_u64 v[230:231], s[34:35], 0, v[128:129]
	ds_read_b128 v[188:191], v159 offset:32768
	ds_read_b128 v[192:195], v159 offset:33792
	ds_read_b128 v[196:199], v159 offset:34816
	ds_read_b128 v[200:203], v159 offset:35840
	ds_read_b128 v[204:207], v159 offset:36864
	ds_read_b128 v[208:211], v159 offset:37888
	ds_read_b128 v[212:215], v159 offset:38912
	ds_read_b128 v[216:219], v159 offset:39936
	global_load_lds_dwordx4 v[230:231], off
	v_lshl_add_u64 v[230:231], s[34:35], 0, v[132:133]
	s_mov_b32 m0, s44
	s_nop 0
	global_load_lds_dwordx4 v[230:231], off
	s_waitcnt vmcnt(8)
	s_waitcnt lgkmcnt(0)
	s_barrier
	s_setprio 1
	s_waitcnt lgkmcnt(0)
	v_mfma_f32_16x16x32_bf16 v[120:123], v[144:147], v[188:191], v[120:123]
	v_mfma_f32_16x16x32_bf16 v[120:123], v[148:151], v[192:195], v[120:123]
	v_mfma_f32_16x16x32_bf16 v[124:127], v[164:167], v[188:191], v[124:127]
	v_mfma_f32_16x16x32_bf16 v[124:127], v[168:171], v[192:195], v[124:127]
	v_mfma_f32_16x16x32_bf16 v[108:111], v[144:147], v[196:199], v[108:111]
	v_mfma_f32_16x16x32_bf16 v[108:111], v[148:151], v[200:203], v[108:111]
	v_mfma_f32_16x16x32_bf16 v[104:107], v[164:167], v[196:199], v[104:107]
	v_mfma_f32_16x16x32_bf16 v[104:107], v[168:171], v[200:203], v[104:107]
	v_mfma_f32_16x16x32_bf16 v[92:95], v[144:147], v[204:207], v[92:95]
	v_mfma_f32_16x16x32_bf16 v[92:95], v[148:151], v[208:211], v[92:95]
	v_mfma_f32_16x16x32_bf16 v[88:91], v[164:167], v[204:207], v[88:91]
	v_mfma_f32_16x16x32_bf16 v[88:91], v[168:171], v[208:211], v[88:91]
	v_mfma_f32_16x16x32_bf16 v[76:79], v[144:147], v[212:215], v[76:79]
	v_mfma_f32_16x16x32_bf16 v[76:79], v[148:151], v[216:219], v[76:79]
	v_mfma_f32_16x16x32_bf16 v[72:75], v[164:167], v[212:215], v[72:75]
	v_mfma_f32_16x16x32_bf16 v[72:75], v[168:171], v[216:219], v[72:75]
	s_setprio 0
	s_setprio 1
	v_mfma_f32_16x16x32_bf16 v[116:119], v[172:175], v[188:191], v[116:119]
	v_mfma_f32_16x16x32_bf16 v[116:119], v[176:179], v[192:195], v[116:119]
	v_mfma_f32_16x16x32_bf16 v[112:115], v[180:183], v[188:191], v[112:115]
	v_mfma_f32_16x16x32_bf16 v[112:115], v[184:187], v[192:195], v[112:115]
	v_mfma_f32_16x16x32_bf16 v[100:103], v[172:175], v[196:199], v[100:103]
	v_mfma_f32_16x16x32_bf16 v[100:103], v[176:179], v[200:203], v[100:103]
	v_mfma_f32_16x16x32_bf16 v[96:99], v[180:183], v[196:199], v[96:99]
	v_mfma_f32_16x16x32_bf16 v[96:99], v[184:187], v[200:203], v[96:99]
	v_mfma_f32_16x16x32_bf16 v[84:87], v[172:175], v[204:207], v[84:87]
	v_mfma_f32_16x16x32_bf16 v[84:87], v[176:179], v[208:211], v[84:87]
	v_mfma_f32_16x16x32_bf16 v[80:83], v[180:183], v[204:207], v[80:83]
	v_mfma_f32_16x16x32_bf16 v[80:83], v[184:187], v[208:211], v[80:83]
	v_mfma_f32_16x16x32_bf16 v[68:71], v[172:175], v[212:215], v[68:71]
	v_mfma_f32_16x16x32_bf16 v[68:71], v[176:179], v[216:219], v[68:71]
	v_mfma_f32_16x16x32_bf16 v[64:67], v[180:183], v[212:215], v[64:67]
	v_mfma_f32_16x16x32_bf16 v[64:67], v[184:187], v[216:219], v[64:67]
	s_setprio 0
	s_barrier
	s_add_i32 s34, s65, s40
	v_lshl_add_u64 v[152:153], v[152:153], 0, s[14:15]
	s_mov_b32 m0, s34
	ds_read_b128 v[188:191], v159 offset:49152
	ds_read_b128 v[192:195], v159 offset:50176
	ds_read_b128 v[196:199], v159 offset:51200
	ds_read_b128 v[200:203], v159 offset:52224
	ds_read_b128 v[204:207], v159 offset:53248
	ds_read_b128 v[208:211], v159 offset:54272
	ds_read_b128 v[212:215], v159 offset:55296
	ds_read_b128 v[216:219], v159 offset:56320
	global_load_lds_dwordx4 v[152:153], off
	v_lshl_add_u64 v[152:153], v[160:161], 0, s[14:15]
	s_add_i32 m0, s34, 0x2000
	s_add_i32 s34, s66, s40
	global_load_lds_dwordx4 v[152:153], off
	v_lshl_add_u64 v[152:153], v[222:223], 0, s[14:15]
	s_mov_b32 m0, s34
	s_nop 0
	global_load_lds_dwordx4 v[152:153], off
	v_lshl_add_u64 v[152:153], v[224:225], 0, s[14:15]
	s_add_i32 m0, s34, 0x2000
	s_nop 0
	global_load_lds_dwordx4 v[152:153], off
	v_lshl_add_u64 v[152:153], v[226:227], 0, s[14:15]
	s_mov_b32 m0, s46
	s_nop 0
	global_load_lds_dwordx4 v[152:153], off
	v_lshl_add_u64 v[152:153], v[228:229], 0, s[14:15]
	s_mov_b32 m0, s47
	s_nop 0
	global_load_lds_dwordx4 v[152:153], off
	s_waitcnt vmcnt(8)
	s_waitcnt lgkmcnt(0)
	s_barrier
	s_setprio 1
	s_waitcnt lgkmcnt(0)
	v_mfma_f32_16x16x32_bf16 v[60:63], v[144:147], v[188:191], v[60:63]
	v_mfma_f32_16x16x32_bf16 v[60:63], v[148:151], v[192:195], v[60:63]
	v_mfma_f32_16x16x32_bf16 v[56:59], v[164:167], v[188:191], v[56:59]
	v_mfma_f32_16x16x32_bf16 v[56:59], v[168:171], v[192:195], v[56:59]
	v_mfma_f32_16x16x32_bf16 v[44:47], v[144:147], v[196:199], v[44:47]
	v_mfma_f32_16x16x32_bf16 v[44:47], v[148:151], v[200:203], v[44:47]
	v_mfma_f32_16x16x32_bf16 v[40:43], v[164:167], v[196:199], v[40:43]
	v_mfma_f32_16x16x32_bf16 v[40:43], v[168:171], v[200:203], v[40:43]
	v_mfma_f32_16x16x32_bf16 v[28:31], v[144:147], v[204:207], v[28:31]
	v_mfma_f32_16x16x32_bf16 v[28:31], v[148:151], v[208:211], v[28:31]
	v_mfma_f32_16x16x32_bf16 v[24:27], v[164:167], v[204:207], v[24:27]
	v_mfma_f32_16x16x32_bf16 v[24:27], v[168:171], v[208:211], v[24:27]
	v_mfma_f32_16x16x32_bf16 v[12:15], v[144:147], v[212:215], v[12:15]
	v_mfma_f32_16x16x32_bf16 v[12:15], v[148:151], v[216:219], v[12:15]
	v_mfma_f32_16x16x32_bf16 v[8:11], v[164:167], v[212:215], v[8:11]
	v_mfma_f32_16x16x32_bf16 v[8:11], v[168:171], v[216:219], v[8:11]
	s_setprio 0
	s_setprio 1
	v_mfma_f32_16x16x32_bf16 v[52:55], v[172:175], v[188:191], v[52:55]
	v_mfma_f32_16x16x32_bf16 v[52:55], v[176:179], v[192:195], v[52:55]
	v_mfma_f32_16x16x32_bf16 v[48:51], v[180:183], v[188:191], v[48:51]
	v_mfma_f32_16x16x32_bf16 v[48:51], v[184:187], v[192:195], v[48:51]
	v_mfma_f32_16x16x32_bf16 v[36:39], v[172:175], v[196:199], v[36:39]
	v_mfma_f32_16x16x32_bf16 v[36:39], v[176:179], v[200:203], v[36:39]
	v_mfma_f32_16x16x32_bf16 v[32:35], v[180:183], v[196:199], v[32:35]
	v_mfma_f32_16x16x32_bf16 v[32:35], v[184:187], v[200:203], v[32:35]
	v_mfma_f32_16x16x32_bf16 v[20:23], v[172:175], v[204:207], v[20:23]
	v_mfma_f32_16x16x32_bf16 v[20:23], v[176:179], v[208:211], v[20:23]
	v_mfma_f32_16x16x32_bf16 v[16:19], v[180:183], v[204:207], v[16:19]
	v_mfma_f32_16x16x32_bf16 v[16:19], v[184:187], v[208:211], v[16:19]
	v_mfma_f32_16x16x32_bf16 v[4:7], v[172:175], v[212:215], v[4:7]
	v_mfma_f32_16x16x32_bf16 v[4:7], v[176:179], v[216:219], v[4:7]
	v_mfma_f32_16x16x32_bf16 v[0:3], v[180:183], v[212:215], v[0:3]
	v_mfma_f32_16x16x32_bf16 v[0:3], v[184:187], v[216:219], v[0:3]
	s_setprio 0
	s_barrier
	s_add_u32 s30, s30, 0x100
	s_addc_u32 s31, s31, 0
	s_add_u32 s62, s62, 0x100
	s_addc_u32 s63, s63, 0
	s_cmp_ge_i32 s64, s48
	s_mov_b32 s34, s64
	s_cbranch_scc0 .LBB0_592

.LBB0_763:
	ds_read_b128 v[128:131], v181
	ds_read_b128 v[132:135], v181 offset:1024
	ds_read_b128 v[136:139], v181 offset:2048
	ds_read_b128 v[140:143], v181 offset:3072
	ds_read_b128 v[144:147], v182
	ds_read_b128 v[148:151], v182 offset:1024
	ds_read_b128 v[168:171], v182 offset:2048
	ds_read_b128 v[172:175], v182 offset:3072
	s_add_i32 s54, s26, 2
	s_add_u32 s55, s24, 0x80
	s_addc_u32 s27, s25, 0
	s_cmp_eq_u32 s43, s26
	s_cselect_b32 s26, s2, s55
	s_cselect_b32 s27, s3, s27
	s_cselect_b32 s61, s23, s53
	s_cselect_b32 s60, s22, s52
	v_lshl_add_u64 v[176:177], s[24:25], 0, v[160:161]
	s_add_i32 m0, s35, 0xc000
	ds_read_b128 v[184:187], v183
	ds_read_b128 v[188:191], v183 offset:1024
	ds_read_b128 v[192:195], v183 offset:2048
	ds_read_b128 v[196:199], v183 offset:3072
	ds_read_b128 v[200:203], v183 offset:4096
	ds_read_b128 v[204:207], v183 offset:5120
	ds_read_b128 v[208:211], v183 offset:6144
	ds_read_b128 v[212:215], v183 offset:7168
	global_load_lds_dwordx4 v[176:177], off
	v_lshl_add_u64 v[176:177], s[24:25], 0, v[162:163]
	s_add_i32 m0, s35, 0xe000
	s_nop 0
	global_load_lds_dwordx4 v[176:177], off
	s_waitcnt vmcnt(8)
	s_waitcnt lgkmcnt(0)
	s_barrier
	s_setprio 1
	s_waitcnt lgkmcnt(0)
	v_mfma_f32_16x16x32_bf16 v[120:123], v[128:131], v[184:187], v[120:123]
	v_mfma_f32_16x16x32_bf16 v[120:123], v[132:135], v[188:191], v[120:123]
	v_mfma_f32_16x16x32_bf16 v[124:127], v[136:139], v[184:187], v[124:127]
	v_mfma_f32_16x16x32_bf16 v[124:127], v[140:143], v[188:191], v[124:127]
	v_mfma_f32_16x16x32_bf16 v[108:111], v[128:131], v[192:195], v[108:111]
	v_mfma_f32_16x16x32_bf16 v[108:111], v[132:135], v[196:199], v[108:111]
	v_mfma_f32_16x16x32_bf16 v[104:107], v[136:139], v[192:195], v[104:107]
	v_mfma_f32_16x16x32_bf16 v[104:107], v[140:143], v[196:199], v[104:107]
	v_mfma_f32_16x16x32_bf16 v[92:95], v[128:131], v[200:203], v[92:95]
	v_mfma_f32_16x16x32_bf16 v[92:95], v[132:135], v[204:207], v[92:95]
	v_mfma_f32_16x16x32_bf16 v[88:91], v[136:139], v[200:203], v[88:91]
	v_mfma_f32_16x16x32_bf16 v[88:91], v[140:143], v[204:207], v[88:91]
	v_mfma_f32_16x16x32_bf16 v[76:79], v[128:131], v[208:211], v[76:79]
	v_mfma_f32_16x16x32_bf16 v[76:79], v[132:135], v[212:215], v[76:79]
	v_mfma_f32_16x16x32_bf16 v[72:75], v[136:139], v[208:211], v[72:75]
	v_mfma_f32_16x16x32_bf16 v[72:75], v[140:143], v[212:215], v[72:75]
	s_setprio 0
	s_setprio 1
	v_mfma_f32_16x16x32_bf16 v[116:119], v[144:147], v[184:187], v[116:119]
	v_mfma_f32_16x16x32_bf16 v[116:119], v[148:151], v[188:191], v[116:119]
	v_mfma_f32_16x16x32_bf16 v[112:115], v[168:171], v[184:187], v[112:115]
	v_mfma_f32_16x16x32_bf16 v[112:115], v[172:175], v[188:191], v[112:115]
	v_mfma_f32_16x16x32_bf16 v[100:103], v[144:147], v[192:195], v[100:103]
	v_mfma_f32_16x16x32_bf16 v[100:103], v[148:151], v[196:199], v[100:103]
	v_mfma_f32_16x16x32_bf16 v[96:99], v[168:171], v[192:195], v[96:99]
	v_mfma_f32_16x16x32_bf16 v[96:99], v[172:175], v[196:199], v[96:99]
	v_mfma_f32_16x16x32_bf16 v[84:87], v[144:147], v[200:203], v[84:87]
	v_mfma_f32_16x16x32_bf16 v[84:87], v[148:151], v[204:207], v[84:87]
	v_mfma_f32_16x16x32_bf16 v[80:83], v[168:171], v[200:203], v[80:83]
	v_mfma_f32_16x16x32_bf16 v[80:83], v[172:175], v[204:207], v[80:83]
	v_mfma_f32_16x16x32_bf16 v[68:71], v[144:147], v[208:211], v[68:71]
	v_mfma_f32_16x16x32_bf16 v[68:71], v[148:151], v[212:215], v[68:71]
	v_mfma_f32_16x16x32_bf16 v[64:67], v[168:171], v[208:211], v[64:67]
	v_mfma_f32_16x16x32_bf16 v[64:67], v[172:175], v[212:215], v[64:67]
	s_setprio 0
	s_barrier
	s_add_i32 s55, s46, s34
	v_lshl_add_u64 v[176:177], s[60:61], 0, v[154:155]
	s_mov_b32 m0, s55
	ds_read_b128 v[184:187], v183 offset:16384
	ds_read_b128 v[188:191], v183 offset:17408
	ds_read_b128 v[192:195], v183 offset:18432
	ds_read_b128 v[196:199], v183 offset:19456
	ds_read_b128 v[200:203], v183 offset:20480
	ds_read_b128 v[204:207], v183 offset:21504
	ds_read_b128 v[208:211], v183 offset:22528
	ds_read_b128 v[212:215], v183 offset:23552
	global_load_lds_dwordx4 v[176:177], off
	s_add_i32 m0, s55, 0x2000
	v_lshl_add_u64 v[216:217], s[60:61], 0, v[158:159]
	s_add_u32 s60, s60, s8
	s_addc_u32 s61, s61, s9
	s_add_i32 s55, s47, s34
	global_load_lds_dwordx4 v[216:217], off
	v_lshl_add_u64 v[218:219], s[60:61], 0, v[154:155]
	s_mov_b32 m0, s55
	v_lshl_add_u64 v[222:223], s[60:61], 0, v[158:159]
	global_load_lds_dwordx4 v[218:219], off
	s_add_i32 m0, s55, 0x2000
	v_lshl_add_u64 v[224:225], s[26:27], 0, v[152:153]
	global_load_lds_dwordx4 v[222:223], off
	s_mov_b32 m0, s35
	v_lshl_add_u64 v[226:227], s[26:27], 0, v[156:157]
	global_load_lds_dwordx4 v[224:225], off
	s_mov_b32 m0, s36
	s_nop 0
	global_load_lds_dwordx4 v[226:227], off
	s_waitcnt vmcnt(8)
	s_waitcnt lgkmcnt(0)
	s_barrier
	s_setprio 1
	s_waitcnt lgkmcnt(0)
	v_mfma_f32_16x16x32_bf16 v[60:63], v[128:131], v[184:187], v[60:63]
	v_mfma_f32_16x16x32_bf16 v[60:63], v[132:135], v[188:191], v[60:63]
	v_mfma_f32_16x16x32_bf16 v[56:59], v[136:139], v[184:187], v[56:59]
	v_mfma_f32_16x16x32_bf16 v[56:59], v[140:143], v[188:191], v[56:59]
	v_mfma_f32_16x16x32_bf16 v[44:47], v[128:131], v[192:195], v[44:47]
	v_mfma_f32_16x16x32_bf16 v[44:47], v[132:135], v[196:199], v[44:47]
	v_mfma_f32_16x16x32_bf16 v[40:43], v[136:139], v[192:195], v[40:43]
	v_mfma_f32_16x16x32_bf16 v[40:43], v[140:143], v[196:199], v[40:43]
	v_mfma_f32_16x16x32_bf16 v[28:31], v[128:131], v[200:203], v[28:31]
	v_mfma_f32_16x16x32_bf16 v[28:31], v[132:135], v[204:207], v[28:31]
	v_mfma_f32_16x16x32_bf16 v[24:27], v[136:139], v[200:203], v[24:27]
	v_mfma_f32_16x16x32_bf16 v[24:27], v[140:143], v[204:207], v[24:27]
	v_mfma_f32_16x16x32_bf16 v[12:15], v[128:131], v[208:211], v[12:15]
	v_mfma_f32_16x16x32_bf16 v[12:15], v[132:135], v[212:215], v[12:15]
	v_mfma_f32_16x16x32_bf16 v[8:11], v[136:139], v[208:211], v[8:11]
	v_mfma_f32_16x16x32_bf16 v[8:11], v[140:143], v[212:215], v[8:11]
	s_setprio 0
	s_setprio 1
	v_mfma_f32_16x16x32_bf16 v[52:55], v[144:147], v[184:187], v[52:55]
	v_mfma_f32_16x16x32_bf16 v[52:55], v[148:151], v[188:191], v[52:55]
	v_mfma_f32_16x16x32_bf16 v[48:51], v[168:171], v[184:187], v[48:51]
	v_mfma_f32_16x16x32_bf16 v[48:51], v[172:175], v[188:191], v[48:51]
	v_mfma_f32_16x16x32_bf16 v[36:39], v[144:147], v[192:195], v[36:39]
	v_mfma_f32_16x16x32_bf16 v[36:39], v[148:151], v[196:199], v[36:39]
	v_mfma_f32_16x16x32_bf16 v[32:35], v[168:171], v[192:195], v[32:35]
	v_mfma_f32_16x16x32_bf16 v[32:35], v[172:175], v[196:199], v[32:35]
	v_mfma_f32_16x16x32_bf16 v[20:23], v[144:147], v[200:203], v[20:23]
	v_mfma_f32_16x16x32_bf16 v[20:23], v[148:151], v[204:207], v[20:23]
	v_mfma_f32_16x16x32_bf16 v[16:19], v[168:171], v[200:203], v[16:19]
	v_mfma_f32_16x16x32_bf16 v[16:19], v[172:175], v[204:207], v[16:19]
	v_mfma_f32_16x16x32_bf16 v[4:7], v[144:147], v[208:211], v[4:7]
	v_mfma_f32_16x16x32_bf16 v[4:7], v[148:151], v[212:215], v[4:7]
	v_mfma_f32_16x16x32_bf16 v[0:3], v[168:171], v[208:211], v[0:3]
	v_mfma_f32_16x16x32_bf16 v[0:3], v[172:175], v[212:215], v[0:3]
	s_setprio 0
	s_barrier
	s_add_i32 s55, 0, 0x18000
	s_add_i32 s60, 0, 0x1c000
	v_add_u32_e32 v140, s55, v179
	v_add_u32_e32 v172, s60, v179
	ds_read_b128 v[128:131], v140
	ds_read_b128 v[132:135], v140 offset:1024
	ds_read_b128 v[136:139], v140 offset:2048
	ds_read_b128 v[140:143], v140 offset:3072
	ds_read_b128 v[144:147], v172
	ds_read_b128 v[148:151], v172 offset:1024
	ds_read_b128 v[168:171], v172 offset:2048
	ds_read_b128 v[172:175], v172 offset:3072
	s_add_u32 s26, s26, s8
	s_addc_u32 s27, s27, s9
	s_mov_b32 m0, s37
	v_lshl_add_u64 v[228:229], s[26:27], 0, v[152:153]
	ds_read_b128 v[184:187], v183 offset:32768
	ds_read_b128 v[188:191], v183 offset:33792
	ds_read_b128 v[192:195], v183 offset:34816
	ds_read_b128 v[196:199], v183 offset:35840
	ds_read_b128 v[200:203], v183 offset:36864
	ds_read_b128 v[204:207], v183 offset:37888
	ds_read_b128 v[208:211], v183 offset:38912
	ds_read_b128 v[212:215], v183 offset:39936
	global_load_lds_dwordx4 v[228:229], off
	v_lshl_add_u64 v[228:229], s[26:27], 0, v[156:157]
	s_mov_b32 m0, s38
	s_nop 0
	global_load_lds_dwordx4 v[228:229], off
	s_waitcnt vmcnt(8)
	s_waitcnt lgkmcnt(0)
	s_barrier
	s_setprio 1
	s_waitcnt lgkmcnt(0)
	v_mfma_f32_16x16x32_bf16 v[120:123], v[128:131], v[184:187], v[120:123]
	v_mfma_f32_16x16x32_bf16 v[120:123], v[132:135], v[188:191], v[120:123]
	v_mfma_f32_16x16x32_bf16 v[124:127], v[136:139], v[184:187], v[124:127]
	v_mfma_f32_16x16x32_bf16 v[124:127], v[140:143], v[188:191], v[124:127]
	v_mfma_f32_16x16x32_bf16 v[108:111], v[128:131], v[192:195], v[108:111]
	v_mfma_f32_16x16x32_bf16 v[108:111], v[132:135], v[196:199], v[108:111]
	v_mfma_f32_16x16x32_bf16 v[104:107], v[136:139], v[192:195], v[104:107]
	v_mfma_f32_16x16x32_bf16 v[104:107], v[140:143], v[196:199], v[104:107]
	v_mfma_f32_16x16x32_bf16 v[92:95], v[128:131], v[200:203], v[92:95]
	v_mfma_f32_16x16x32_bf16 v[92:95], v[132:135], v[204:207], v[92:95]
	v_mfma_f32_16x16x32_bf16 v[88:91], v[136:139], v[200:203], v[88:91]
	v_mfma_f32_16x16x32_bf16 v[88:91], v[140:143], v[204:207], v[88:91]
	v_mfma_f32_16x16x32_bf16 v[76:79], v[128:131], v[208:211], v[76:79]
	v_mfma_f32_16x16x32_bf16 v[76:79], v[132:135], v[212:215], v[76:79]
	v_mfma_f32_16x16x32_bf16 v[72:75], v[136:139], v[208:211], v[72:75]
	v_mfma_f32_16x16x32_bf16 v[72:75], v[140:143], v[212:215], v[72:75]
	s_setprio 0
	s_setprio 1
	v_mfma_f32_16x16x32_bf16 v[116:119], v[144:147], v[184:187], v[116:119]
	v_mfma_f32_16x16x32_bf16 v[116:119], v[148:151], v[188:191], v[116:119]
	v_mfma_f32_16x16x32_bf16 v[112:115], v[168:171], v[184:187], v[112:115]
	v_mfma_f32_16x16x32_bf16 v[112:115], v[172:175], v[188:191], v[112:115]
	v_mfma_f32_16x16x32_bf16 v[100:103], v[144:147], v[192:195], v[100:103]
	v_mfma_f32_16x16x32_bf16 v[100:103], v[148:151], v[196:199], v[100:103]
	v_mfma_f32_16x16x32_bf16 v[96:99], v[168:171], v[192:195], v[96:99]
	v_mfma_f32_16x16x32_bf16 v[96:99], v[172:175], v[196:199], v[96:99]
	v_mfma_f32_16x16x32_bf16 v[84:87], v[144:147], v[200:203], v[84:87]
	v_mfma_f32_16x16x32_bf16 v[84:87], v[148:151], v[204:207], v[84:87]
	v_mfma_f32_16x16x32_bf16 v[80:83], v[168:171], v[200:203], v[80:83]
	v_mfma_f32_16x16x32_bf16 v[80:83], v[172:175], v[204:207], v[80:83]
	v_mfma_f32_16x16x32_bf16 v[68:71], v[144:147], v[208:211], v[68:71]
	v_mfma_f32_16x16x32_bf16 v[68:71], v[148:151], v[212:215], v[68:71]
	v_mfma_f32_16x16x32_bf16 v[64:67], v[168:171], v[208:211], v[64:67]
	v_mfma_f32_16x16x32_bf16 v[64:67], v[172:175], v[212:215], v[64:67]
	s_setprio 0
	s_barrier
	s_add_i32 s26, s55, s34
	v_lshl_add_u64 v[176:177], v[176:177], 0, s[16:17]
	s_mov_b32 m0, s26
	ds_read_b128 v[184:187], v183 offset:49152
	ds_read_b128 v[188:191], v183 offset:50176
	ds_read_b128 v[192:195], v183 offset:51200
	ds_read_b128 v[196:199], v183 offset:52224
	ds_read_b128 v[200:203], v183 offset:53248
	ds_read_b128 v[204:207], v183 offset:54272
	ds_read_b128 v[208:211], v183 offset:55296
	ds_read_b128 v[212:215], v183 offset:56320
	global_load_lds_dwordx4 v[176:177], off
	v_lshl_add_u64 v[176:177], v[216:217], 0, s[16:17]
	s_add_i32 m0, s26, 0x2000
	s_add_i32 s26, s60, s34
	global_load_lds_dwordx4 v[176:177], off
	v_lshl_add_u64 v[176:177], v[218:219], 0, s[16:17]
	s_mov_b32 m0, s26
	s_nop 0
	global_load_lds_dwordx4 v[176:177], off
	v_lshl_add_u64 v[176:177], v[222:223], 0, s[16:17]
	s_add_i32 m0, s26, 0x2000
	s_nop 0
	global_load_lds_dwordx4 v[176:177], off
	v_lshl_add_u64 v[176:177], v[224:225], 0, s[16:17]
	s_mov_b32 m0, s40
	s_nop 0
	global_load_lds_dwordx4 v[176:177], off
	v_lshl_add_u64 v[176:177], v[226:227], 0, s[16:17]
	s_mov_b32 m0, s41
	s_nop 0
	global_load_lds_dwordx4 v[176:177], off
	s_waitcnt vmcnt(8)
	s_waitcnt lgkmcnt(0)
	s_barrier
	s_setprio 1
	s_waitcnt lgkmcnt(0)
	v_mfma_f32_16x16x32_bf16 v[60:63], v[128:131], v[184:187], v[60:63]
	v_mfma_f32_16x16x32_bf16 v[60:63], v[132:135], v[188:191], v[60:63]
	v_mfma_f32_16x16x32_bf16 v[56:59], v[136:139], v[184:187], v[56:59]
	v_mfma_f32_16x16x32_bf16 v[56:59], v[140:143], v[188:191], v[56:59]
	v_mfma_f32_16x16x32_bf16 v[44:47], v[128:131], v[192:195], v[44:47]
	v_mfma_f32_16x16x32_bf16 v[44:47], v[132:135], v[196:199], v[44:47]
	v_mfma_f32_16x16x32_bf16 v[40:43], v[136:139], v[192:195], v[40:43]
	v_mfma_f32_16x16x32_bf16 v[40:43], v[140:143], v[196:199], v[40:43]
	v_mfma_f32_16x16x32_bf16 v[28:31], v[128:131], v[200:203], v[28:31]
	v_mfma_f32_16x16x32_bf16 v[28:31], v[132:135], v[204:207], v[28:31]
	v_mfma_f32_16x16x32_bf16 v[24:27], v[136:139], v[200:203], v[24:27]
	v_mfma_f32_16x16x32_bf16 v[24:27], v[140:143], v[204:207], v[24:27]
	v_mfma_f32_16x16x32_bf16 v[12:15], v[128:131], v[208:211], v[12:15]
	v_mfma_f32_16x16x32_bf16 v[12:15], v[132:135], v[212:215], v[12:15]
	v_mfma_f32_16x16x32_bf16 v[8:11], v[136:139], v[208:211], v[8:11]
	v_mfma_f32_16x16x32_bf16 v[8:11], v[140:143], v[212:215], v[8:11]
	s_setprio 0
	s_setprio 1
	v_mfma_f32_16x16x32_bf16 v[52:55], v[144:147], v[184:187], v[52:55]
	v_mfma_f32_16x16x32_bf16 v[52:55], v[148:151], v[188:191], v[52:55]
	v_mfma_f32_16x16x32_bf16 v[48:51], v[168:171], v[184:187], v[48:51]
	v_mfma_f32_16x16x32_bf16 v[48:51], v[172:175], v[188:191], v[48:51]
	v_mfma_f32_16x16x32_bf16 v[36:39], v[144:147], v[192:195], v[36:39]
	v_mfma_f32_16x16x32_bf16 v[36:39], v[148:151], v[196:199], v[36:39]
	v_mfma_f32_16x16x32_bf16 v[32:35], v[168:171], v[192:195], v[32:35]
	v_mfma_f32_16x16x32_bf16 v[32:35], v[172:175], v[196:199], v[32:35]
	v_mfma_f32_16x16x32_bf16 v[20:23], v[144:147], v[200:203], v[20:23]
	v_mfma_f32_16x16x32_bf16 v[20:23], v[148:151], v[204:207], v[20:23]
	v_mfma_f32_16x16x32_bf16 v[16:19], v[168:171], v[200:203], v[16:19]
	v_mfma_f32_16x16x32_bf16 v[16:19], v[172:175], v[204:207], v[16:19]
	v_mfma_f32_16x16x32_bf16 v[4:7], v[144:147], v[208:211], v[4:7]
	v_mfma_f32_16x16x32_bf16 v[4:7], v[148:151], v[212:215], v[4:7]
	v_mfma_f32_16x16x32_bf16 v[0:3], v[168:171], v[208:211], v[0:3]
	v_mfma_f32_16x16x32_bf16 v[0:3], v[172:175], v[212:215], v[0:3]
	s_setprio 0
	s_barrier
	s_add_u32 s24, s24, 0x100
	s_addc_u32 s25, s25, 0
	s_add_u32 s52, s52, 0x100
	s_addc_u32 s53, s53, 0
	s_cmp_ge_i32 s54, s42
	s_mov_b32 s26, s54
	s_cbranch_scc0 .LBB0_763

.LBB0_849:
	ds_read_b128 v[112:115], v209
	ds_read_b128 v[116:119], v209 offset:1024
	ds_read_b128 v[120:123], v209 offset:2048
	ds_read_b128 v[128:131], v209 offset:3072
	ds_read_b128 v[144:147], v210
	ds_read_b128 v[148:151], v210 offset:1024
	ds_read_b128 v[152:155], v210 offset:2048
	ds_read_b128 v[156:159], v210 offset:3072
	s_add_i32 s62, s30, 2
	s_add_u32 s63, s28, 0x80
	s_addc_u32 s31, s29, 0
	s_cmp_eq_u32 s46, s30
	s_cselect_b32 s30, s4, s63
	s_cselect_b32 s31, s5, s31
	s_cselect_b32 s65, s27, s61
	s_cselect_b32 s64, s26, s60
	v_lshl_add_u64 v[204:205], s[28:29], 0, v[180:181]
	s_add_i32 m0, s38, 0xc000
	ds_read_b128 v[160:163], v211
	ds_read_b128 v[164:167], v211 offset:1024
	ds_read_b128 v[168:171], v211 offset:2048
	ds_read_b128 v[172:175], v211 offset:3072
	ds_read_b128 v[188:191], v211 offset:4096
	ds_read_b128 v[192:195], v211 offset:5120
	ds_read_b128 v[196:199], v211 offset:6144
	ds_read_b128 v[200:203], v211 offset:7168
	global_load_lds_dwordx4 v[204:205], off
	v_lshl_add_u64 v[204:205], s[28:29], 0, v[182:183]
	s_add_i32 m0, s38, 0xe000
	s_nop 0
	global_load_lds_dwordx4 v[204:205], off
	s_waitcnt vmcnt(8)
	s_waitcnt lgkmcnt(0)
	s_barrier
	s_setprio 1
	s_waitcnt lgkmcnt(0)
	v_mfma_f32_16x16x32_bf16 v[136:139], v[112:115], v[160:163], v[136:139]
	v_mfma_f32_16x16x32_bf16 v[136:139], v[116:119], v[164:167], v[136:139]
	v_mfma_f32_16x16x32_bf16 v[140:143], v[120:123], v[160:163], v[140:143]
	v_mfma_f32_16x16x32_bf16 v[140:143], v[128:131], v[164:167], v[140:143]
	v_mfma_f32_16x16x32_bf16 v[108:111], v[112:115], v[168:171], v[108:111]
	v_mfma_f32_16x16x32_bf16 v[108:111], v[116:119], v[172:175], v[108:111]
	v_mfma_f32_16x16x32_bf16 v[104:107], v[120:123], v[168:171], v[104:107]
	v_mfma_f32_16x16x32_bf16 v[104:107], v[128:131], v[172:175], v[104:107]
	v_mfma_f32_16x16x32_bf16 v[92:95], v[112:115], v[188:191], v[92:95]
	v_mfma_f32_16x16x32_bf16 v[92:95], v[116:119], v[192:195], v[92:95]
	v_mfma_f32_16x16x32_bf16 v[88:91], v[120:123], v[188:191], v[88:91]
	v_mfma_f32_16x16x32_bf16 v[88:91], v[128:131], v[192:195], v[88:91]
	v_mfma_f32_16x16x32_bf16 v[76:79], v[112:115], v[196:199], v[76:79]
	v_mfma_f32_16x16x32_bf16 v[76:79], v[116:119], v[200:203], v[76:79]
	v_mfma_f32_16x16x32_bf16 v[72:75], v[120:123], v[196:199], v[72:75]
	v_mfma_f32_16x16x32_bf16 v[72:75], v[128:131], v[200:203], v[72:75]
	s_setprio 0
	s_setprio 1
	v_mfma_f32_16x16x32_bf16 v[132:135], v[144:147], v[160:163], v[132:135]
	v_mfma_f32_16x16x32_bf16 v[132:135], v[148:151], v[164:167], v[132:135]
	v_mfma_f32_16x16x32_bf16 v[124:127], v[152:155], v[160:163], v[124:127]
	v_mfma_f32_16x16x32_bf16 v[124:127], v[156:159], v[164:167], v[124:127]
	v_mfma_f32_16x16x32_bf16 v[100:103], v[144:147], v[168:171], v[100:103]
	v_mfma_f32_16x16x32_bf16 v[100:103], v[148:151], v[172:175], v[100:103]
	v_mfma_f32_16x16x32_bf16 v[96:99], v[152:155], v[168:171], v[96:99]
	v_mfma_f32_16x16x32_bf16 v[96:99], v[156:159], v[172:175], v[96:99]
	v_mfma_f32_16x16x32_bf16 v[84:87], v[144:147], v[188:191], v[84:87]
	v_mfma_f32_16x16x32_bf16 v[84:87], v[148:151], v[192:195], v[84:87]
	v_mfma_f32_16x16x32_bf16 v[80:83], v[152:155], v[188:191], v[80:83]
	v_mfma_f32_16x16x32_bf16 v[80:83], v[156:159], v[192:195], v[80:83]
	v_mfma_f32_16x16x32_bf16 v[68:71], v[144:147], v[196:199], v[68:71]
	v_mfma_f32_16x16x32_bf16 v[68:71], v[148:151], v[200:203], v[68:71]
	v_mfma_f32_16x16x32_bf16 v[64:67], v[152:155], v[196:199], v[64:67]
	v_mfma_f32_16x16x32_bf16 v[64:67], v[156:159], v[200:203], v[64:67]
	s_setprio 0
	s_barrier
	s_add_i32 s63, s50, s37
	v_lshl_add_u64 v[204:205], s[64:65], 0, v[176:177]
	s_mov_b32 m0, s63
	ds_read_b128 v[160:163], v211 offset:16384
	ds_read_b128 v[164:167], v211 offset:17408
	ds_read_b128 v[168:171], v211 offset:18432
	ds_read_b128 v[172:175], v211 offset:19456
	ds_read_b128 v[188:191], v211 offset:20480
	ds_read_b128 v[192:195], v211 offset:21504
	ds_read_b128 v[196:199], v211 offset:22528
	ds_read_b128 v[200:203], v211 offset:23552
	global_load_lds_dwordx4 v[204:205], off
	s_add_i32 m0, s63, 0x2000
	v_lshl_add_u64 v[214:215], s[64:65], 0, v[178:179]
	s_add_u32 s64, s64, s10
	s_addc_u32 s65, s65, s11
	s_add_i32 s63, s51, s37
	global_load_lds_dwordx4 v[214:215], off
	v_lshl_add_u64 v[216:217], s[64:65], 0, v[176:177]
	s_mov_b32 m0, s63
	v_lshl_add_u64 v[218:219], s[64:65], 0, v[178:179]
	global_load_lds_dwordx4 v[216:217], off
	s_add_i32 m0, s63, 0x2000
	v_lshl_add_u64 v[222:223], s[30:31], 0, v[176:177]
	global_load_lds_dwordx4 v[218:219], off
	s_mov_b32 m0, s38
	v_lshl_add_u64 v[224:225], s[30:31], 0, v[178:179]
	global_load_lds_dwordx4 v[222:223], off
	s_mov_b32 m0, s39
	s_nop 0
	global_load_lds_dwordx4 v[224:225], off
	s_waitcnt vmcnt(8)
	s_waitcnt lgkmcnt(0)
	s_barrier
	s_setprio 1
	s_waitcnt lgkmcnt(0)
	v_mfma_f32_16x16x32_bf16 v[60:63], v[112:115], v[160:163], v[60:63]
	v_mfma_f32_16x16x32_bf16 v[60:63], v[116:119], v[164:167], v[60:63]
	v_mfma_f32_16x16x32_bf16 v[56:59], v[120:123], v[160:163], v[56:59]
	v_mfma_f32_16x16x32_bf16 v[56:59], v[128:131], v[164:167], v[56:59]
	v_mfma_f32_16x16x32_bf16 v[44:47], v[112:115], v[168:171], v[44:47]
	v_mfma_f32_16x16x32_bf16 v[44:47], v[116:119], v[172:175], v[44:47]
	v_mfma_f32_16x16x32_bf16 v[40:43], v[120:123], v[168:171], v[40:43]
	v_mfma_f32_16x16x32_bf16 v[40:43], v[128:131], v[172:175], v[40:43]
	v_mfma_f32_16x16x32_bf16 v[28:31], v[112:115], v[188:191], v[28:31]
	v_mfma_f32_16x16x32_bf16 v[28:31], v[116:119], v[192:195], v[28:31]
	v_mfma_f32_16x16x32_bf16 v[24:27], v[120:123], v[188:191], v[24:27]
	v_mfma_f32_16x16x32_bf16 v[24:27], v[128:131], v[192:195], v[24:27]
	v_mfma_f32_16x16x32_bf16 v[12:15], v[112:115], v[196:199], v[12:15]
	v_mfma_f32_16x16x32_bf16 v[12:15], v[116:119], v[200:203], v[12:15]
	v_mfma_f32_16x16x32_bf16 v[8:11], v[120:123], v[196:199], v[8:11]
	v_mfma_f32_16x16x32_bf16 v[8:11], v[128:131], v[200:203], v[8:11]
	s_setprio 0
	s_setprio 1
	v_mfma_f32_16x16x32_bf16 v[52:55], v[144:147], v[160:163], v[52:55]
	v_mfma_f32_16x16x32_bf16 v[52:55], v[148:151], v[164:167], v[52:55]
	v_mfma_f32_16x16x32_bf16 v[48:51], v[152:155], v[160:163], v[48:51]
	v_mfma_f32_16x16x32_bf16 v[48:51], v[156:159], v[164:167], v[48:51]
	v_mfma_f32_16x16x32_bf16 v[36:39], v[144:147], v[168:171], v[36:39]
	v_mfma_f32_16x16x32_bf16 v[36:39], v[148:151], v[172:175], v[36:39]
	v_mfma_f32_16x16x32_bf16 v[32:35], v[152:155], v[168:171], v[32:35]
	v_mfma_f32_16x16x32_bf16 v[32:35], v[156:159], v[172:175], v[32:35]
	v_mfma_f32_16x16x32_bf16 v[20:23], v[144:147], v[188:191], v[20:23]
	v_mfma_f32_16x16x32_bf16 v[20:23], v[148:151], v[192:195], v[20:23]
	v_mfma_f32_16x16x32_bf16 v[16:19], v[152:155], v[188:191], v[16:19]
	v_mfma_f32_16x16x32_bf16 v[16:19], v[156:159], v[192:195], v[16:19]
	v_mfma_f32_16x16x32_bf16 v[4:7], v[144:147], v[196:199], v[4:7]
	v_mfma_f32_16x16x32_bf16 v[4:7], v[148:151], v[200:203], v[4:7]
	v_mfma_f32_16x16x32_bf16 v[0:3], v[152:155], v[196:199], v[0:3]
	v_mfma_f32_16x16x32_bf16 v[0:3], v[156:159], v[200:203], v[0:3]
	s_setprio 0
	s_barrier
	s_add_i32 s63, 0, 0x18000
	s_add_i32 s64, 0, 0x1c000
	v_add_u32_e32 v128, s63, v207
	v_add_u32_e32 v156, s64, v207
	ds_read_b128 v[112:115], v128
	ds_read_b128 v[116:119], v128 offset:1024
	ds_read_b128 v[120:123], v128 offset:2048
	ds_read_b128 v[128:131], v128 offset:3072
	ds_read_b128 v[144:147], v156
	ds_read_b128 v[148:151], v156 offset:1024
	ds_read_b128 v[152:155], v156 offset:2048
	ds_read_b128 v[156:159], v156 offset:3072
	s_add_u32 s30, s30, s10
	s_addc_u32 s31, s31, s11
	s_mov_b32 m0, s40
	v_lshl_add_u64 v[226:227], s[30:31], 0, v[176:177]
	ds_read_b128 v[160:163], v211 offset:32768
	ds_read_b128 v[164:167], v211 offset:33792
	ds_read_b128 v[168:171], v211 offset:34816
	ds_read_b128 v[172:175], v211 offset:35840
	ds_read_b128 v[188:191], v211 offset:36864
	ds_read_b128 v[192:195], v211 offset:37888
	ds_read_b128 v[196:199], v211 offset:38912
	ds_read_b128 v[200:203], v211 offset:39936
	global_load_lds_dwordx4 v[226:227], off
	v_lshl_add_u64 v[226:227], s[30:31], 0, v[178:179]
	s_mov_b32 m0, s41
	s_nop 0
	global_load_lds_dwordx4 v[226:227], off
	s_waitcnt vmcnt(8)
	s_waitcnt lgkmcnt(0)
	s_barrier
	s_setprio 1
	s_waitcnt lgkmcnt(0)
	v_mfma_f32_16x16x32_bf16 v[136:139], v[112:115], v[160:163], v[136:139]
	v_mfma_f32_16x16x32_bf16 v[136:139], v[116:119], v[164:167], v[136:139]
	v_mfma_f32_16x16x32_bf16 v[140:143], v[120:123], v[160:163], v[140:143]
	v_mfma_f32_16x16x32_bf16 v[140:143], v[128:131], v[164:167], v[140:143]
	v_mfma_f32_16x16x32_bf16 v[108:111], v[112:115], v[168:171], v[108:111]
	v_mfma_f32_16x16x32_bf16 v[108:111], v[116:119], v[172:175], v[108:111]
	v_mfma_f32_16x16x32_bf16 v[104:107], v[120:123], v[168:171], v[104:107]
	v_mfma_f32_16x16x32_bf16 v[104:107], v[128:131], v[172:175], v[104:107]
	v_mfma_f32_16x16x32_bf16 v[92:95], v[112:115], v[188:191], v[92:95]
	v_mfma_f32_16x16x32_bf16 v[92:95], v[116:119], v[192:195], v[92:95]
	v_mfma_f32_16x16x32_bf16 v[88:91], v[120:123], v[188:191], v[88:91]
	v_mfma_f32_16x16x32_bf16 v[88:91], v[128:131], v[192:195], v[88:91]
	v_mfma_f32_16x16x32_bf16 v[76:79], v[112:115], v[196:199], v[76:79]
	v_mfma_f32_16x16x32_bf16 v[76:79], v[116:119], v[200:203], v[76:79]
	v_mfma_f32_16x16x32_bf16 v[72:75], v[120:123], v[196:199], v[72:75]
	v_mfma_f32_16x16x32_bf16 v[72:75], v[128:131], v[200:203], v[72:75]
	s_setprio 0
	s_setprio 1
	v_mfma_f32_16x16x32_bf16 v[132:135], v[144:147], v[160:163], v[132:135]
	v_mfma_f32_16x16x32_bf16 v[132:135], v[148:151], v[164:167], v[132:135]
	v_mfma_f32_16x16x32_bf16 v[124:127], v[152:155], v[160:163], v[124:127]
	v_mfma_f32_16x16x32_bf16 v[124:127], v[156:159], v[164:167], v[124:127]
	v_mfma_f32_16x16x32_bf16 v[100:103], v[144:147], v[168:171], v[100:103]
	v_mfma_f32_16x16x32_bf16 v[100:103], v[148:151], v[172:175], v[100:103]
	v_mfma_f32_16x16x32_bf16 v[96:99], v[152:155], v[168:171], v[96:99]
	v_mfma_f32_16x16x32_bf16 v[96:99], v[156:159], v[172:175], v[96:99]
	v_mfma_f32_16x16x32_bf16 v[84:87], v[144:147], v[188:191], v[84:87]
	v_mfma_f32_16x16x32_bf16 v[84:87], v[148:151], v[192:195], v[84:87]
	v_mfma_f32_16x16x32_bf16 v[80:83], v[152:155], v[188:191], v[80:83]
	v_mfma_f32_16x16x32_bf16 v[80:83], v[156:159], v[192:195], v[80:83]
	v_mfma_f32_16x16x32_bf16 v[68:71], v[144:147], v[196:199], v[68:71]
	v_mfma_f32_16x16x32_bf16 v[68:71], v[148:151], v[200:203], v[68:71]
	v_mfma_f32_16x16x32_bf16 v[64:67], v[152:155], v[196:199], v[64:67]
	v_mfma_f32_16x16x32_bf16 v[64:67], v[156:159], v[200:203], v[64:67]
	s_setprio 0
	s_barrier
	s_add_i32 s30, s63, s37
	v_lshl_add_u64 v[204:205], v[204:205], 0, s[18:19]
	s_mov_b32 m0, s30
	ds_read_b128 v[160:163], v211 offset:49152
	ds_read_b128 v[164:167], v211 offset:50176
	ds_read_b128 v[168:171], v211 offset:51200
	ds_read_b128 v[172:175], v211 offset:52224
	ds_read_b128 v[188:191], v211 offset:53248
	ds_read_b128 v[192:195], v211 offset:54272
	ds_read_b128 v[196:199], v211 offset:55296
	ds_read_b128 v[200:203], v211 offset:56320
	global_load_lds_dwordx4 v[204:205], off
	v_lshl_add_u64 v[204:205], v[214:215], 0, s[18:19]
	s_add_i32 m0, s30, 0x2000
	s_add_i32 s30, s64, s37
	global_load_lds_dwordx4 v[204:205], off
	v_lshl_add_u64 v[204:205], v[216:217], 0, s[18:19]
	s_mov_b32 m0, s30
	s_nop 0
	global_load_lds_dwordx4 v[204:205], off
	v_lshl_add_u64 v[204:205], v[218:219], 0, s[18:19]
	s_add_i32 m0, s30, 0x2000
	s_nop 0
	global_load_lds_dwordx4 v[204:205], off
	v_lshl_add_u64 v[204:205], v[222:223], 0, s[18:19]
	s_mov_b32 m0, s43
	s_nop 0
	global_load_lds_dwordx4 v[204:205], off
	v_lshl_add_u64 v[204:205], v[224:225], 0, s[18:19]
	s_mov_b32 m0, s44
	s_nop 0
	global_load_lds_dwordx4 v[204:205], off
	s_waitcnt vmcnt(8)
	s_waitcnt lgkmcnt(0)
	s_barrier
	s_setprio 1
	s_waitcnt lgkmcnt(0)
	v_mfma_f32_16x16x32_bf16 v[60:63], v[112:115], v[160:163], v[60:63]
	v_mfma_f32_16x16x32_bf16 v[60:63], v[116:119], v[164:167], v[60:63]
	v_mfma_f32_16x16x32_bf16 v[56:59], v[120:123], v[160:163], v[56:59]
	v_mfma_f32_16x16x32_bf16 v[56:59], v[128:131], v[164:167], v[56:59]
	v_mfma_f32_16x16x32_bf16 v[44:47], v[112:115], v[168:171], v[44:47]
	v_mfma_f32_16x16x32_bf16 v[44:47], v[116:119], v[172:175], v[44:47]
	v_mfma_f32_16x16x32_bf16 v[40:43], v[120:123], v[168:171], v[40:43]
	v_mfma_f32_16x16x32_bf16 v[40:43], v[128:131], v[172:175], v[40:43]
	v_mfma_f32_16x16x32_bf16 v[28:31], v[112:115], v[188:191], v[28:31]
	v_mfma_f32_16x16x32_bf16 v[28:31], v[116:119], v[192:195], v[28:31]
	v_mfma_f32_16x16x32_bf16 v[24:27], v[120:123], v[188:191], v[24:27]
	v_mfma_f32_16x16x32_bf16 v[24:27], v[128:131], v[192:195], v[24:27]
	v_mfma_f32_16x16x32_bf16 v[12:15], v[112:115], v[196:199], v[12:15]
	v_mfma_f32_16x16x32_bf16 v[12:15], v[116:119], v[200:203], v[12:15]
	v_mfma_f32_16x16x32_bf16 v[8:11], v[120:123], v[196:199], v[8:11]
	v_mfma_f32_16x16x32_bf16 v[8:11], v[128:131], v[200:203], v[8:11]
	s_setprio 0
	s_setprio 1
	v_mfma_f32_16x16x32_bf16 v[52:55], v[144:147], v[160:163], v[52:55]
	v_mfma_f32_16x16x32_bf16 v[52:55], v[148:151], v[164:167], v[52:55]
	v_mfma_f32_16x16x32_bf16 v[48:51], v[152:155], v[160:163], v[48:51]
	v_mfma_f32_16x16x32_bf16 v[48:51], v[156:159], v[164:167], v[48:51]
	v_mfma_f32_16x16x32_bf16 v[36:39], v[144:147], v[168:171], v[36:39]
	v_mfma_f32_16x16x32_bf16 v[36:39], v[148:151], v[172:175], v[36:39]
	v_mfma_f32_16x16x32_bf16 v[32:35], v[152:155], v[168:171], v[32:35]
	v_mfma_f32_16x16x32_bf16 v[32:35], v[156:159], v[172:175], v[32:35]
	v_mfma_f32_16x16x32_bf16 v[20:23], v[144:147], v[188:191], v[20:23]
	v_mfma_f32_16x16x32_bf16 v[20:23], v[148:151], v[192:195], v[20:23]
	v_mfma_f32_16x16x32_bf16 v[16:19], v[152:155], v[188:191], v[16:19]
	v_mfma_f32_16x16x32_bf16 v[16:19], v[156:159], v[192:195], v[16:19]
	v_mfma_f32_16x16x32_bf16 v[4:7], v[144:147], v[196:199], v[4:7]
	v_mfma_f32_16x16x32_bf16 v[4:7], v[148:151], v[200:203], v[4:7]
	v_mfma_f32_16x16x32_bf16 v[0:3], v[152:155], v[196:199], v[0:3]
	v_mfma_f32_16x16x32_bf16 v[0:3], v[156:159], v[200:203], v[0:3]
	s_setprio 0
	s_barrier
	s_add_u32 s28, s28, 0x100
	s_addc_u32 s29, s29, 0
	s_add_u32 s60, s60, 0x100
	s_addc_u32 s61, s61, 0
	s_cmp_ge_i32 s62, s45
	s_mov_b32 s30, s62
	s_cbranch_scc0 .LBB0_849

.LBB0_949:
	ds_read_b128 v[164:167], v157
	ds_read_b128 v[168:171], v157 offset:1024
	ds_read_b128 v[172:175], v157 offset:2048
	ds_read_b128 v[176:179], v157 offset:3072
	ds_read_b128 v[180:183], v162
	ds_read_b128 v[184:187], v162 offset:1024
	ds_read_b128 v[188:191], v162 offset:2048
	ds_read_b128 v[192:195], v162 offset:3072
	s_add_i32 s68, s34, 2
	s_add_u32 s69, s30, 0x80
	s_addc_u32 s35, s31, 0
	s_cmp_eq_u32 s49, s34
	s_cselect_b32 s34, s2, s69
	s_cselect_b32 s35, s3, s35
	s_cselect_b32 s71, s29, s67
	s_cselect_b32 s70, s28, s66
	v_lshl_add_u64 v[230:231], s[30:31], 0, v[136:137]
	s_add_i32 m0, s41, 0xc000
	ds_read_b128 v[196:199], v163
	ds_read_b128 v[200:203], v163 offset:1024
	ds_read_b128 v[204:207], v163 offset:2048
	ds_read_b128 v[208:211], v163 offset:3072
	ds_read_b128 v[212:215], v163 offset:4096
	ds_read_b128 v[216:219], v163 offset:5120
	ds_read_b128 v[222:225], v163 offset:6144
	ds_read_b128 v[226:229], v163 offset:7168
	global_load_lds_dwordx4 v[230:231], off
	v_lshl_add_u64 v[230:231], s[30:31], 0, v[138:139]
	s_add_i32 m0, s41, 0xe000
	s_nop 0
	global_load_lds_dwordx4 v[230:231], off
	s_waitcnt vmcnt(8)
	s_waitcnt lgkmcnt(0)
	s_barrier
	s_setprio 1
	s_waitcnt lgkmcnt(0)
	v_mfma_f32_16x16x32_bf16 v[120:123], v[164:167], v[196:199], v[120:123]
	v_mfma_f32_16x16x32_bf16 v[120:123], v[168:171], v[200:203], v[120:123]
	v_mfma_f32_16x16x32_bf16 v[124:127], v[172:175], v[196:199], v[124:127]
	v_mfma_f32_16x16x32_bf16 v[124:127], v[176:179], v[200:203], v[124:127]
	v_mfma_f32_16x16x32_bf16 v[108:111], v[164:167], v[204:207], v[108:111]
	v_mfma_f32_16x16x32_bf16 v[108:111], v[168:171], v[208:211], v[108:111]
	v_mfma_f32_16x16x32_bf16 v[104:107], v[172:175], v[204:207], v[104:107]
	v_mfma_f32_16x16x32_bf16 v[104:107], v[176:179], v[208:211], v[104:107]
	v_mfma_f32_16x16x32_bf16 v[92:95], v[164:167], v[212:215], v[92:95]
	v_mfma_f32_16x16x32_bf16 v[92:95], v[168:171], v[216:219], v[92:95]
	v_mfma_f32_16x16x32_bf16 v[88:91], v[172:175], v[212:215], v[88:91]
	v_mfma_f32_16x16x32_bf16 v[88:91], v[176:179], v[216:219], v[88:91]
	v_mfma_f32_16x16x32_bf16 v[76:79], v[164:167], v[222:225], v[76:79]
	v_mfma_f32_16x16x32_bf16 v[76:79], v[168:171], v[226:229], v[76:79]
	v_mfma_f32_16x16x32_bf16 v[72:75], v[172:175], v[222:225], v[72:75]
	v_mfma_f32_16x16x32_bf16 v[72:75], v[176:179], v[226:229], v[72:75]
	s_setprio 0
	s_setprio 1
	v_mfma_f32_16x16x32_bf16 v[116:119], v[180:183], v[196:199], v[116:119]
	v_mfma_f32_16x16x32_bf16 v[116:119], v[184:187], v[200:203], v[116:119]
	v_mfma_f32_16x16x32_bf16 v[112:115], v[188:191], v[196:199], v[112:115]
	v_mfma_f32_16x16x32_bf16 v[112:115], v[192:195], v[200:203], v[112:115]
	v_mfma_f32_16x16x32_bf16 v[100:103], v[180:183], v[204:207], v[100:103]
	v_mfma_f32_16x16x32_bf16 v[100:103], v[184:187], v[208:211], v[100:103]
	v_mfma_f32_16x16x32_bf16 v[96:99], v[188:191], v[204:207], v[96:99]
	v_mfma_f32_16x16x32_bf16 v[96:99], v[192:195], v[208:211], v[96:99]
	v_mfma_f32_16x16x32_bf16 v[84:87], v[180:183], v[212:215], v[84:87]
	v_mfma_f32_16x16x32_bf16 v[84:87], v[184:187], v[216:219], v[84:87]
	v_mfma_f32_16x16x32_bf16 v[80:83], v[188:191], v[212:215], v[80:83]
	v_mfma_f32_16x16x32_bf16 v[80:83], v[192:195], v[216:219], v[80:83]
	v_mfma_f32_16x16x32_bf16 v[68:71], v[180:183], v[222:225], v[68:71]
	v_mfma_f32_16x16x32_bf16 v[68:71], v[184:187], v[226:229], v[68:71]
	v_mfma_f32_16x16x32_bf16 v[64:67], v[188:191], v[222:225], v[64:67]
	v_mfma_f32_16x16x32_bf16 v[64:67], v[192:195], v[226:229], v[64:67]
	s_setprio 0
	s_barrier
	s_add_i32 s69, s52, s40
	v_lshl_add_u64 v[230:231], s[70:71], 0, v[130:131]
	s_mov_b32 m0, s69
	ds_read_b128 v[196:199], v163 offset:16384
	ds_read_b128 v[200:203], v163 offset:17408
	ds_read_b128 v[204:207], v163 offset:18432
	ds_read_b128 v[208:211], v163 offset:19456
	ds_read_b128 v[212:215], v163 offset:20480
	ds_read_b128 v[216:219], v163 offset:21504
	ds_read_b128 v[222:225], v163 offset:22528
	ds_read_b128 v[226:229], v163 offset:23552
	global_load_lds_dwordx4 v[230:231], off
	s_add_i32 m0, s69, 0x2000
	v_lshl_add_u64 v[232:233], s[70:71], 0, v[134:135]
	s_add_u32 s70, s70, s6
	s_addc_u32 s71, s71, s7
	s_add_i32 s69, s53, s40
	global_load_lds_dwordx4 v[232:233], off
	v_lshl_add_u64 v[234:235], s[70:71], 0, v[130:131]
	s_mov_b32 m0, s69
	v_lshl_add_u64 v[236:237], s[70:71], 0, v[134:135]
	global_load_lds_dwordx4 v[234:235], off
	s_add_i32 m0, s69, 0x2000
	v_lshl_add_u64 v[238:239], s[34:35], 0, v[128:129]
	global_load_lds_dwordx4 v[236:237], off
	s_mov_b32 m0, s41
	v_lshl_add_u64 v[240:241], s[34:35], 0, v[132:133]
	global_load_lds_dwordx4 v[238:239], off
	s_mov_b32 m0, s42
	s_nop 0
	global_load_lds_dwordx4 v[240:241], off
	s_waitcnt vmcnt(8)
	s_waitcnt lgkmcnt(0)
	s_barrier
	s_setprio 1
	s_waitcnt lgkmcnt(0)
	v_mfma_f32_16x16x32_bf16 v[60:63], v[164:167], v[196:199], v[60:63]
	v_mfma_f32_16x16x32_bf16 v[60:63], v[168:171], v[200:203], v[60:63]
	v_mfma_f32_16x16x32_bf16 v[56:59], v[172:175], v[196:199], v[56:59]
	v_mfma_f32_16x16x32_bf16 v[56:59], v[176:179], v[200:203], v[56:59]
	v_mfma_f32_16x16x32_bf16 v[44:47], v[164:167], v[204:207], v[44:47]
	v_mfma_f32_16x16x32_bf16 v[44:47], v[168:171], v[208:211], v[44:47]
	v_mfma_f32_16x16x32_bf16 v[40:43], v[172:175], v[204:207], v[40:43]
	v_mfma_f32_16x16x32_bf16 v[40:43], v[176:179], v[208:211], v[40:43]
	v_mfma_f32_16x16x32_bf16 v[28:31], v[164:167], v[212:215], v[28:31]
	v_mfma_f32_16x16x32_bf16 v[28:31], v[168:171], v[216:219], v[28:31]
	v_mfma_f32_16x16x32_bf16 v[24:27], v[172:175], v[212:215], v[24:27]
	v_mfma_f32_16x16x32_bf16 v[24:27], v[176:179], v[216:219], v[24:27]
	v_mfma_f32_16x16x32_bf16 v[12:15], v[164:167], v[222:225], v[12:15]
	v_mfma_f32_16x16x32_bf16 v[12:15], v[168:171], v[226:229], v[12:15]
	v_mfma_f32_16x16x32_bf16 v[8:11], v[172:175], v[222:225], v[8:11]
	v_mfma_f32_16x16x32_bf16 v[8:11], v[176:179], v[226:229], v[8:11]
	s_setprio 0
	s_setprio 1
	v_mfma_f32_16x16x32_bf16 v[52:55], v[180:183], v[196:199], v[52:55]
	v_mfma_f32_16x16x32_bf16 v[52:55], v[184:187], v[200:203], v[52:55]
	v_mfma_f32_16x16x32_bf16 v[48:51], v[188:191], v[196:199], v[48:51]
	v_mfma_f32_16x16x32_bf16 v[48:51], v[192:195], v[200:203], v[48:51]
	v_mfma_f32_16x16x32_bf16 v[36:39], v[180:183], v[204:207], v[36:39]
	v_mfma_f32_16x16x32_bf16 v[36:39], v[184:187], v[208:211], v[36:39]
	v_mfma_f32_16x16x32_bf16 v[32:35], v[188:191], v[204:207], v[32:35]
	v_mfma_f32_16x16x32_bf16 v[32:35], v[192:195], v[208:211], v[32:35]
	v_mfma_f32_16x16x32_bf16 v[20:23], v[180:183], v[212:215], v[20:23]
	v_mfma_f32_16x16x32_bf16 v[20:23], v[184:187], v[216:219], v[20:23]
	v_mfma_f32_16x16x32_bf16 v[16:19], v[188:191], v[212:215], v[16:19]
	v_mfma_f32_16x16x32_bf16 v[16:19], v[192:195], v[216:219], v[16:19]
	v_mfma_f32_16x16x32_bf16 v[4:7], v[180:183], v[222:225], v[4:7]
	v_mfma_f32_16x16x32_bf16 v[4:7], v[184:187], v[226:229], v[4:7]
	v_mfma_f32_16x16x32_bf16 v[0:3], v[188:191], v[222:225], v[0:3]
	v_mfma_f32_16x16x32_bf16 v[0:3], v[192:195], v[226:229], v[0:3]
	s_setprio 0
	s_barrier
	s_add_i32 s69, 0, 0x18000
	s_add_i32 s70, 0, 0x1c000
	v_add_u32_e32 v176, s69, v154
	v_add_u32_e32 v192, s70, v154
	ds_read_b128 v[164:167], v176
	ds_read_b128 v[168:171], v176 offset:1024
	ds_read_b128 v[172:175], v176 offset:2048
	ds_read_b128 v[176:179], v176 offset:3072
	ds_read_b128 v[180:183], v192
	ds_read_b128 v[184:187], v192 offset:1024
	ds_read_b128 v[188:191], v192 offset:2048
	ds_read_b128 v[192:195], v192 offset:3072
	s_add_u32 s34, s34, s6
	s_addc_u32 s35, s35, s7
	s_mov_b32 m0, s43
	v_lshl_add_u64 v[242:243], s[34:35], 0, v[128:129]
	ds_read_b128 v[196:199], v163 offset:32768
	ds_read_b128 v[200:203], v163 offset:33792
	ds_read_b128 v[204:207], v163 offset:34816
	ds_read_b128 v[208:211], v163 offset:35840
	ds_read_b128 v[212:215], v163 offset:36864
	ds_read_b128 v[216:219], v163 offset:37888
	ds_read_b128 v[222:225], v163 offset:38912
	ds_read_b128 v[226:229], v163 offset:39936
	global_load_lds_dwordx4 v[242:243], off
	v_lshl_add_u64 v[242:243], s[34:35], 0, v[132:133]
	s_mov_b32 m0, s44
	s_nop 0
	global_load_lds_dwordx4 v[242:243], off
	s_waitcnt vmcnt(8)
	s_waitcnt lgkmcnt(0)
	s_barrier
	s_setprio 1
	s_waitcnt lgkmcnt(0)
	v_mfma_f32_16x16x32_bf16 v[120:123], v[164:167], v[196:199], v[120:123]
	v_mfma_f32_16x16x32_bf16 v[120:123], v[168:171], v[200:203], v[120:123]
	v_mfma_f32_16x16x32_bf16 v[124:127], v[172:175], v[196:199], v[124:127]
	v_mfma_f32_16x16x32_bf16 v[124:127], v[176:179], v[200:203], v[124:127]
	v_mfma_f32_16x16x32_bf16 v[108:111], v[164:167], v[204:207], v[108:111]
	v_mfma_f32_16x16x32_bf16 v[108:111], v[168:171], v[208:211], v[108:111]
	v_mfma_f32_16x16x32_bf16 v[104:107], v[172:175], v[204:207], v[104:107]
	v_mfma_f32_16x16x32_bf16 v[104:107], v[176:179], v[208:211], v[104:107]
	v_mfma_f32_16x16x32_bf16 v[92:95], v[164:167], v[212:215], v[92:95]
	v_mfma_f32_16x16x32_bf16 v[92:95], v[168:171], v[216:219], v[92:95]
	v_mfma_f32_16x16x32_bf16 v[88:91], v[172:175], v[212:215], v[88:91]
	v_mfma_f32_16x16x32_bf16 v[88:91], v[176:179], v[216:219], v[88:91]
	v_mfma_f32_16x16x32_bf16 v[76:79], v[164:167], v[222:225], v[76:79]
	v_mfma_f32_16x16x32_bf16 v[76:79], v[168:171], v[226:229], v[76:79]
	v_mfma_f32_16x16x32_bf16 v[72:75], v[172:175], v[222:225], v[72:75]
	v_mfma_f32_16x16x32_bf16 v[72:75], v[176:179], v[226:229], v[72:75]
	s_setprio 0
	s_setprio 1
	v_mfma_f32_16x16x32_bf16 v[116:119], v[180:183], v[196:199], v[116:119]
	v_mfma_f32_16x16x32_bf16 v[116:119], v[184:187], v[200:203], v[116:119]
	v_mfma_f32_16x16x32_bf16 v[112:115], v[188:191], v[196:199], v[112:115]
	v_mfma_f32_16x16x32_bf16 v[112:115], v[192:195], v[200:203], v[112:115]
	v_mfma_f32_16x16x32_bf16 v[100:103], v[180:183], v[204:207], v[100:103]
	v_mfma_f32_16x16x32_bf16 v[100:103], v[184:187], v[208:211], v[100:103]
	v_mfma_f32_16x16x32_bf16 v[96:99], v[188:191], v[204:207], v[96:99]
	v_mfma_f32_16x16x32_bf16 v[96:99], v[192:195], v[208:211], v[96:99]
	v_mfma_f32_16x16x32_bf16 v[84:87], v[180:183], v[212:215], v[84:87]
	v_mfma_f32_16x16x32_bf16 v[84:87], v[184:187], v[216:219], v[84:87]
	v_mfma_f32_16x16x32_bf16 v[80:83], v[188:191], v[212:215], v[80:83]
	v_mfma_f32_16x16x32_bf16 v[80:83], v[192:195], v[216:219], v[80:83]
	v_mfma_f32_16x16x32_bf16 v[68:71], v[180:183], v[222:225], v[68:71]
	v_mfma_f32_16x16x32_bf16 v[68:71], v[184:187], v[226:229], v[68:71]
	v_mfma_f32_16x16x32_bf16 v[64:67], v[188:191], v[222:225], v[64:67]
	v_mfma_f32_16x16x32_bf16 v[64:67], v[192:195], v[226:229], v[64:67]
	s_setprio 0
	s_barrier
	s_add_i32 s34, s69, s40
	v_lshl_add_u64 v[230:231], v[230:231], 0, s[12:13]
	s_mov_b32 m0, s34
	ds_read_b128 v[196:199], v163 offset:49152
	ds_read_b128 v[200:203], v163 offset:50176
	ds_read_b128 v[204:207], v163 offset:51200
	ds_read_b128 v[208:211], v163 offset:52224
	ds_read_b128 v[212:215], v163 offset:53248
	ds_read_b128 v[216:219], v163 offset:54272
	ds_read_b128 v[222:225], v163 offset:55296
	ds_read_b128 v[226:229], v163 offset:56320
	global_load_lds_dwordx4 v[230:231], off
	v_lshl_add_u64 v[230:231], v[232:233], 0, s[12:13]
	s_add_i32 m0, s34, 0x2000
	s_add_i32 s34, s70, s40
	global_load_lds_dwordx4 v[230:231], off
	v_lshl_add_u64 v[230:231], v[234:235], 0, s[12:13]
	s_mov_b32 m0, s34
	s_nop 0
	global_load_lds_dwordx4 v[230:231], off
	v_lshl_add_u64 v[230:231], v[236:237], 0, s[12:13]
	s_add_i32 m0, s34, 0x2000
	s_nop 0
	global_load_lds_dwordx4 v[230:231], off
	v_lshl_add_u64 v[230:231], v[238:239], 0, s[12:13]
	s_mov_b32 m0, s46
	s_nop 0
	global_load_lds_dwordx4 v[230:231], off
	v_lshl_add_u64 v[230:231], v[240:241], 0, s[12:13]
	s_mov_b32 m0, s47
	s_nop 0
	global_load_lds_dwordx4 v[230:231], off
	s_waitcnt vmcnt(8)
	s_waitcnt lgkmcnt(0)
	s_barrier
	s_setprio 1
	s_waitcnt lgkmcnt(0)
	v_mfma_f32_16x16x32_bf16 v[60:63], v[164:167], v[196:199], v[60:63]
	v_mfma_f32_16x16x32_bf16 v[60:63], v[168:171], v[200:203], v[60:63]
	v_mfma_f32_16x16x32_bf16 v[56:59], v[172:175], v[196:199], v[56:59]
	v_mfma_f32_16x16x32_bf16 v[56:59], v[176:179], v[200:203], v[56:59]
	v_mfma_f32_16x16x32_bf16 v[44:47], v[164:167], v[204:207], v[44:47]
	v_mfma_f32_16x16x32_bf16 v[44:47], v[168:171], v[208:211], v[44:47]
	v_mfma_f32_16x16x32_bf16 v[40:43], v[172:175], v[204:207], v[40:43]
	v_mfma_f32_16x16x32_bf16 v[40:43], v[176:179], v[208:211], v[40:43]
	v_mfma_f32_16x16x32_bf16 v[28:31], v[164:167], v[212:215], v[28:31]
	v_mfma_f32_16x16x32_bf16 v[28:31], v[168:171], v[216:219], v[28:31]
	v_mfma_f32_16x16x32_bf16 v[24:27], v[172:175], v[212:215], v[24:27]
	v_mfma_f32_16x16x32_bf16 v[24:27], v[176:179], v[216:219], v[24:27]
	v_mfma_f32_16x16x32_bf16 v[12:15], v[164:167], v[222:225], v[12:15]
	v_mfma_f32_16x16x32_bf16 v[12:15], v[168:171], v[226:229], v[12:15]
	v_mfma_f32_16x16x32_bf16 v[8:11], v[172:175], v[222:225], v[8:11]
	v_mfma_f32_16x16x32_bf16 v[8:11], v[176:179], v[226:229], v[8:11]
	s_setprio 0
	s_setprio 1
	v_mfma_f32_16x16x32_bf16 v[52:55], v[180:183], v[196:199], v[52:55]
	v_mfma_f32_16x16x32_bf16 v[52:55], v[184:187], v[200:203], v[52:55]
	v_mfma_f32_16x16x32_bf16 v[48:51], v[188:191], v[196:199], v[48:51]
	v_mfma_f32_16x16x32_bf16 v[48:51], v[192:195], v[200:203], v[48:51]
	v_mfma_f32_16x16x32_bf16 v[36:39], v[180:183], v[204:207], v[36:39]
	v_mfma_f32_16x16x32_bf16 v[36:39], v[184:187], v[208:211], v[36:39]
	v_mfma_f32_16x16x32_bf16 v[32:35], v[188:191], v[204:207], v[32:35]
	v_mfma_f32_16x16x32_bf16 v[32:35], v[192:195], v[208:211], v[32:35]
	v_mfma_f32_16x16x32_bf16 v[20:23], v[180:183], v[212:215], v[20:23]
	v_mfma_f32_16x16x32_bf16 v[20:23], v[184:187], v[216:219], v[20:23]
	v_mfma_f32_16x16x32_bf16 v[16:19], v[188:191], v[212:215], v[16:19]
	v_mfma_f32_16x16x32_bf16 v[16:19], v[192:195], v[216:219], v[16:19]
	v_mfma_f32_16x16x32_bf16 v[4:7], v[180:183], v[222:225], v[4:7]
	v_mfma_f32_16x16x32_bf16 v[4:7], v[184:187], v[226:229], v[4:7]
	v_mfma_f32_16x16x32_bf16 v[0:3], v[188:191], v[222:225], v[0:3]
	v_mfma_f32_16x16x32_bf16 v[0:3], v[192:195], v[226:229], v[0:3]
	s_setprio 0
	s_barrier
	s_add_u32 s30, s30, 0x100
	s_addc_u32 s31, s31, 0
	s_add_u32 s66, s66, 0x100
	s_addc_u32 s67, s67, 0
	s_cmp_ge_i32 s68, s48
	s_mov_b32 s34, s68
	s_cbranch_scc0 .LBB0_949

.LBB0_970:
	ds_read_b128 v[170:173], v139
	ds_read_b128 v[174:177], v139 offset:1024
	ds_read_b128 v[178:181], v139 offset:2048
	ds_read_b128 v[182:185], v139 offset:3072
	ds_read_b128 v[186:189], v165
	ds_read_b128 v[190:193], v165 offset:1024
	ds_read_b128 v[194:197], v165 offset:2048
	ds_read_b128 v[198:201], v165 offset:3072
	s_add_i32 s8, s4, 2
	s_add_u32 s9, s2, 0x80
	s_addc_u32 s5, s3, 0
	s_cmp_eq_u32 s52, s4
	s_cselect_b32 s4, s30, s9
	s_cselect_b32 s5, s31, s5
	s_cselect_b32 s11, s35, s7
	s_cselect_b32 s10, s34, s6
	v_lshl_add_u64 v[218:219], s[2:3], 0, v[156:157]
	s_add_i32 m0, s42, 0xc000
	ds_read_b128 v[202:205], v166
	ds_read_b128 v[206:209], v166 offset:1024
	ds_read_b128 v[210:213], v166 offset:2048
	ds_read_b128 v[214:217], v166 offset:3072
	ds_read_b128 v[222:225], v166 offset:4096
	ds_read_b128 v[226:229], v166 offset:5120
	ds_read_b128 v[230:233], v166 offset:6144
	ds_read_b128 v[234:237], v166 offset:7168
	global_load_lds_dwordx4 v[218:219], off
	v_lshl_add_u64 v[218:219], s[2:3], 0, v[158:159]
	s_add_i32 m0, s42, 0xe000
	s_nop 0
	global_load_lds_dwordx4 v[218:219], off
	s_waitcnt vmcnt(8)
	s_waitcnt lgkmcnt(0)
	s_barrier
	s_setprio 1
	s_waitcnt lgkmcnt(0)
	v_mfma_f32_16x16x32_bf16 v[124:127], v[170:173], v[202:205], v[124:127]
	v_mfma_f32_16x16x32_bf16 v[124:127], v[174:177], v[206:209], v[124:127]
	v_mfma_f32_16x16x32_bf16 v[120:123], v[178:181], v[202:205], v[120:123]
	v_mfma_f32_16x16x32_bf16 v[120:123], v[182:185], v[206:209], v[120:123]
	v_mfma_f32_16x16x32_bf16 v[108:111], v[170:173], v[210:213], v[108:111]
	v_mfma_f32_16x16x32_bf16 v[108:111], v[174:177], v[214:217], v[108:111]
	v_mfma_f32_16x16x32_bf16 v[104:107], v[178:181], v[210:213], v[104:107]
	v_mfma_f32_16x16x32_bf16 v[104:107], v[182:185], v[214:217], v[104:107]
	v_mfma_f32_16x16x32_bf16 v[92:95], v[170:173], v[222:225], v[92:95]
	v_mfma_f32_16x16x32_bf16 v[92:95], v[174:177], v[226:229], v[92:95]
	v_mfma_f32_16x16x32_bf16 v[88:91], v[178:181], v[222:225], v[88:91]
	v_mfma_f32_16x16x32_bf16 v[88:91], v[182:185], v[226:229], v[88:91]
	v_mfma_f32_16x16x32_bf16 v[76:79], v[170:173], v[230:233], v[76:79]
	v_mfma_f32_16x16x32_bf16 v[76:79], v[174:177], v[234:237], v[76:79]
	v_mfma_f32_16x16x32_bf16 v[72:75], v[178:181], v[230:233], v[72:75]
	v_mfma_f32_16x16x32_bf16 v[72:75], v[182:185], v[234:237], v[72:75]
	s_setprio 0
	s_setprio 1
	v_mfma_f32_16x16x32_bf16 v[116:119], v[186:189], v[202:205], v[116:119]
	v_mfma_f32_16x16x32_bf16 v[116:119], v[190:193], v[206:209], v[116:119]
	v_mfma_f32_16x16x32_bf16 v[112:115], v[194:197], v[202:205], v[112:115]
	v_mfma_f32_16x16x32_bf16 v[112:115], v[198:201], v[206:209], v[112:115]
	v_mfma_f32_16x16x32_bf16 v[100:103], v[186:189], v[210:213], v[100:103]
	v_mfma_f32_16x16x32_bf16 v[100:103], v[190:193], v[214:217], v[100:103]
	v_mfma_f32_16x16x32_bf16 v[96:99], v[194:197], v[210:213], v[96:99]
	v_mfma_f32_16x16x32_bf16 v[96:99], v[198:201], v[214:217], v[96:99]
	v_mfma_f32_16x16x32_bf16 v[84:87], v[186:189], v[222:225], v[84:87]
	v_mfma_f32_16x16x32_bf16 v[84:87], v[190:193], v[226:229], v[84:87]
	v_mfma_f32_16x16x32_bf16 v[80:83], v[194:197], v[222:225], v[80:83]
	v_mfma_f32_16x16x32_bf16 v[80:83], v[198:201], v[226:229], v[80:83]
	v_mfma_f32_16x16x32_bf16 v[68:71], v[186:189], v[230:233], v[68:71]
	v_mfma_f32_16x16x32_bf16 v[68:71], v[190:193], v[234:237], v[68:71]
	v_mfma_f32_16x16x32_bf16 v[64:67], v[194:197], v[230:233], v[64:67]
	v_mfma_f32_16x16x32_bf16 v[64:67], v[198:201], v[234:237], v[64:67]
	s_setprio 0
	s_barrier
	s_add_i32 s9, s60, s39
	v_lshl_add_u64 v[218:219], s[10:11], 0, v[132:133]
	s_mov_b32 m0, s9
	ds_read_b128 v[202:205], v166 offset:16384
	ds_read_b128 v[206:209], v166 offset:17408
	ds_read_b128 v[210:213], v166 offset:18432
	ds_read_b128 v[214:217], v166 offset:19456
	ds_read_b128 v[222:225], v166 offset:20480
	ds_read_b128 v[226:229], v166 offset:21504
	ds_read_b128 v[230:233], v166 offset:22528
	ds_read_b128 v[234:237], v166 offset:23552
	global_load_lds_dwordx4 v[218:219], off
	s_add_i32 m0, s9, 0x2000
	v_lshl_add_u64 v[238:239], s[10:11], 0, v[128:129]
	s_add_u32 s10, s10, s18
	s_addc_u32 s11, s11, s19
	s_add_i32 s9, s61, s39
	global_load_lds_dwordx4 v[238:239], off
	v_lshl_add_u64 v[240:241], s[10:11], 0, v[132:133]
	s_mov_b32 m0, s9
	v_lshl_add_u64 v[242:243], s[10:11], 0, v[128:129]
	global_load_lds_dwordx4 v[240:241], off
	s_add_i32 m0, s9, 0x2000
	v_lshl_add_u64 v[244:245], s[4:5], 0, v[134:135]
	global_load_lds_dwordx4 v[242:243], off
	s_mov_b32 m0, s42
	v_lshl_add_u64 v[246:247], s[4:5], 0, v[130:131]
	global_load_lds_dwordx4 v[244:245], off
	s_mov_b32 m0, s43
	s_nop 0
	global_load_lds_dwordx4 v[246:247], off
	s_waitcnt vmcnt(8)
	s_waitcnt lgkmcnt(0)
	s_barrier
	s_setprio 1
	s_waitcnt lgkmcnt(0)
	v_mfma_f32_16x16x32_bf16 v[60:63], v[170:173], v[202:205], v[60:63]
	v_mfma_f32_16x16x32_bf16 v[60:63], v[174:177], v[206:209], v[60:63]
	v_mfma_f32_16x16x32_bf16 v[56:59], v[178:181], v[202:205], v[56:59]
	v_mfma_f32_16x16x32_bf16 v[56:59], v[182:185], v[206:209], v[56:59]
	v_mfma_f32_16x16x32_bf16 v[44:47], v[170:173], v[210:213], v[44:47]
	v_mfma_f32_16x16x32_bf16 v[44:47], v[174:177], v[214:217], v[44:47]
	v_mfma_f32_16x16x32_bf16 v[40:43], v[178:181], v[210:213], v[40:43]
	v_mfma_f32_16x16x32_bf16 v[40:43], v[182:185], v[214:217], v[40:43]
	v_mfma_f32_16x16x32_bf16 v[28:31], v[170:173], v[222:225], v[28:31]
	v_mfma_f32_16x16x32_bf16 v[28:31], v[174:177], v[226:229], v[28:31]
	v_mfma_f32_16x16x32_bf16 v[24:27], v[178:181], v[222:225], v[24:27]
	v_mfma_f32_16x16x32_bf16 v[24:27], v[182:185], v[226:229], v[24:27]
	v_mfma_f32_16x16x32_bf16 v[12:15], v[170:173], v[230:233], v[12:15]
	v_mfma_f32_16x16x32_bf16 v[12:15], v[174:177], v[234:237], v[12:15]
	v_mfma_f32_16x16x32_bf16 v[8:11], v[178:181], v[230:233], v[8:11]
	v_mfma_f32_16x16x32_bf16 v[8:11], v[182:185], v[234:237], v[8:11]
	s_setprio 0
	s_setprio 1
	v_mfma_f32_16x16x32_bf16 v[52:55], v[186:189], v[202:205], v[52:55]
	v_mfma_f32_16x16x32_bf16 v[52:55], v[190:193], v[206:209], v[52:55]
	v_mfma_f32_16x16x32_bf16 v[48:51], v[194:197], v[202:205], v[48:51]
	v_mfma_f32_16x16x32_bf16 v[48:51], v[198:201], v[206:209], v[48:51]
	v_mfma_f32_16x16x32_bf16 v[36:39], v[186:189], v[210:213], v[36:39]
	v_mfma_f32_16x16x32_bf16 v[36:39], v[190:193], v[214:217], v[36:39]
	v_mfma_f32_16x16x32_bf16 v[32:35], v[194:197], v[210:213], v[32:35]
	v_mfma_f32_16x16x32_bf16 v[32:35], v[198:201], v[214:217], v[32:35]
	v_mfma_f32_16x16x32_bf16 v[20:23], v[186:189], v[222:225], v[20:23]
	v_mfma_f32_16x16x32_bf16 v[20:23], v[190:193], v[226:229], v[20:23]
	v_mfma_f32_16x16x32_bf16 v[16:19], v[194:197], v[222:225], v[16:19]
	v_mfma_f32_16x16x32_bf16 v[16:19], v[198:201], v[226:229], v[16:19]
	v_mfma_f32_16x16x32_bf16 v[4:7], v[186:189], v[230:233], v[4:7]
	v_mfma_f32_16x16x32_bf16 v[4:7], v[190:193], v[234:237], v[4:7]
	v_mfma_f32_16x16x32_bf16 v[0:3], v[194:197], v[230:233], v[0:3]
	v_mfma_f32_16x16x32_bf16 v[0:3], v[198:201], v[234:237], v[0:3]
	s_setprio 0
	s_barrier
	s_add_i32 s9, 0, 0x18000
	v_add_u32_e32 v169, s9, v164
	s_add_i32 s10, 0, 0x1c000
	ds_read_b128 v[170:173], v169
	ds_read_b128 v[174:177], v169 offset:1024
	ds_read_b128 v[178:181], v169 offset:2048
	ds_read_b128 v[182:185], v169 offset:3072
	v_add_u32_e32 v169, s10, v164
	ds_read_b128 v[186:189], v169
	ds_read_b128 v[190:193], v169 offset:1024
	ds_read_b128 v[194:197], v169 offset:2048
	ds_read_b128 v[198:201], v169 offset:3072
	s_add_u32 s4, s4, s18
	s_addc_u32 s5, s5, s19
	s_mov_b32 m0, s44
	v_lshl_add_u64 v[248:249], s[4:5], 0, v[134:135]
	ds_read_b128 v[202:205], v166 offset:32768
	ds_read_b128 v[206:209], v166 offset:33792
	ds_read_b128 v[210:213], v166 offset:34816
	ds_read_b128 v[214:217], v166 offset:35840
	ds_read_b128 v[222:225], v166 offset:36864
	ds_read_b128 v[226:229], v166 offset:37888
	ds_read_b128 v[230:233], v166 offset:38912
	ds_read_b128 v[234:237], v166 offset:39936
	global_load_lds_dwordx4 v[248:249], off
	v_lshl_add_u64 v[248:249], s[4:5], 0, v[130:131]
	s_mov_b32 m0, s45
	s_nop 0
	global_load_lds_dwordx4 v[248:249], off
	s_waitcnt vmcnt(8)
	s_waitcnt lgkmcnt(0)
	s_barrier
	s_setprio 1
	s_waitcnt lgkmcnt(0)
	v_mfma_f32_16x16x32_bf16 v[124:127], v[170:173], v[202:205], v[124:127]
	v_mfma_f32_16x16x32_bf16 v[124:127], v[174:177], v[206:209], v[124:127]
	v_mfma_f32_16x16x32_bf16 v[120:123], v[178:181], v[202:205], v[120:123]
	v_mfma_f32_16x16x32_bf16 v[120:123], v[182:185], v[206:209], v[120:123]
	v_mfma_f32_16x16x32_bf16 v[108:111], v[170:173], v[210:213], v[108:111]
	v_mfma_f32_16x16x32_bf16 v[108:111], v[174:177], v[214:217], v[108:111]
	v_mfma_f32_16x16x32_bf16 v[104:107], v[178:181], v[210:213], v[104:107]
	v_mfma_f32_16x16x32_bf16 v[104:107], v[182:185], v[214:217], v[104:107]
	v_mfma_f32_16x16x32_bf16 v[92:95], v[170:173], v[222:225], v[92:95]
	v_mfma_f32_16x16x32_bf16 v[92:95], v[174:177], v[226:229], v[92:95]
	v_mfma_f32_16x16x32_bf16 v[88:91], v[178:181], v[222:225], v[88:91]
	v_mfma_f32_16x16x32_bf16 v[88:91], v[182:185], v[226:229], v[88:91]
	v_mfma_f32_16x16x32_bf16 v[76:79], v[170:173], v[230:233], v[76:79]
	v_mfma_f32_16x16x32_bf16 v[76:79], v[174:177], v[234:237], v[76:79]
	v_mfma_f32_16x16x32_bf16 v[72:75], v[178:181], v[230:233], v[72:75]
	v_mfma_f32_16x16x32_bf16 v[72:75], v[182:185], v[234:237], v[72:75]
	s_setprio 0
	s_setprio 1
	v_mfma_f32_16x16x32_bf16 v[116:119], v[186:189], v[202:205], v[116:119]
	v_mfma_f32_16x16x32_bf16 v[116:119], v[190:193], v[206:209], v[116:119]
	v_mfma_f32_16x16x32_bf16 v[112:115], v[194:197], v[202:205], v[112:115]
	v_mfma_f32_16x16x32_bf16 v[112:115], v[198:201], v[206:209], v[112:115]
	v_mfma_f32_16x16x32_bf16 v[100:103], v[186:189], v[210:213], v[100:103]
	v_mfma_f32_16x16x32_bf16 v[100:103], v[190:193], v[214:217], v[100:103]
	v_mfma_f32_16x16x32_bf16 v[96:99], v[194:197], v[210:213], v[96:99]
	v_mfma_f32_16x16x32_bf16 v[96:99], v[198:201], v[214:217], v[96:99]
	v_mfma_f32_16x16x32_bf16 v[84:87], v[186:189], v[222:225], v[84:87]
	v_mfma_f32_16x16x32_bf16 v[84:87], v[190:193], v[226:229], v[84:87]
	v_mfma_f32_16x16x32_bf16 v[80:83], v[194:197], v[222:225], v[80:83]
	v_mfma_f32_16x16x32_bf16 v[80:83], v[198:201], v[226:229], v[80:83]
	v_mfma_f32_16x16x32_bf16 v[68:71], v[186:189], v[230:233], v[68:71]
	v_mfma_f32_16x16x32_bf16 v[68:71], v[190:193], v[234:237], v[68:71]
	v_mfma_f32_16x16x32_bf16 v[64:67], v[194:197], v[230:233], v[64:67]
	v_mfma_f32_16x16x32_bf16 v[64:67], v[198:201], v[234:237], v[64:67]
	s_setprio 0
	s_barrier
	s_add_i32 s4, s9, s39
	v_lshl_add_u64 v[218:219], v[218:219], 0, s[24:25]
	s_mov_b32 m0, s4
	ds_read_b128 v[202:205], v166 offset:49152
	ds_read_b128 v[206:209], v166 offset:50176
	ds_read_b128 v[210:213], v166 offset:51200
	ds_read_b128 v[214:217], v166 offset:52224
	ds_read_b128 v[222:225], v166 offset:53248
	ds_read_b128 v[226:229], v166 offset:54272
	ds_read_b128 v[230:233], v166 offset:55296
	ds_read_b128 v[234:237], v166 offset:56320
	global_load_lds_dwordx4 v[218:219], off
	v_lshl_add_u64 v[218:219], v[238:239], 0, s[24:25]
	s_add_i32 m0, s4, 0x2000
	s_add_i32 s4, s10, s39
	global_load_lds_dwordx4 v[218:219], off
	v_lshl_add_u64 v[218:219], v[240:241], 0, s[24:25]
	s_mov_b32 m0, s4
	s_nop 0
	global_load_lds_dwordx4 v[218:219], off
	v_lshl_add_u64 v[218:219], v[242:243], 0, s[24:25]
	s_add_i32 m0, s4, 0x2000
	s_nop 0
	global_load_lds_dwordx4 v[218:219], off
	v_lshl_add_u64 v[218:219], v[244:245], 0, s[24:25]
	s_mov_b32 m0, s49
	s_nop 0
	global_load_lds_dwordx4 v[218:219], off
	v_lshl_add_u64 v[218:219], v[246:247], 0, s[24:25]
	s_mov_b32 m0, s50
	s_nop 0
	global_load_lds_dwordx4 v[218:219], off
	s_waitcnt vmcnt(8)
	s_waitcnt lgkmcnt(0)
	s_barrier
	s_setprio 1
	s_waitcnt lgkmcnt(0)
	v_mfma_f32_16x16x32_bf16 v[60:63], v[170:173], v[202:205], v[60:63]
	v_mfma_f32_16x16x32_bf16 v[60:63], v[174:177], v[206:209], v[60:63]
	v_mfma_f32_16x16x32_bf16 v[56:59], v[178:181], v[202:205], v[56:59]
	v_mfma_f32_16x16x32_bf16 v[56:59], v[182:185], v[206:209], v[56:59]
	v_mfma_f32_16x16x32_bf16 v[44:47], v[170:173], v[210:213], v[44:47]
	v_mfma_f32_16x16x32_bf16 v[44:47], v[174:177], v[214:217], v[44:47]
	v_mfma_f32_16x16x32_bf16 v[40:43], v[178:181], v[210:213], v[40:43]
	v_mfma_f32_16x16x32_bf16 v[40:43], v[182:185], v[214:217], v[40:43]
	v_mfma_f32_16x16x32_bf16 v[28:31], v[170:173], v[222:225], v[28:31]
	v_mfma_f32_16x16x32_bf16 v[28:31], v[174:177], v[226:229], v[28:31]
	v_mfma_f32_16x16x32_bf16 v[24:27], v[178:181], v[222:225], v[24:27]
	v_mfma_f32_16x16x32_bf16 v[24:27], v[182:185], v[226:229], v[24:27]
	v_mfma_f32_16x16x32_bf16 v[12:15], v[170:173], v[230:233], v[12:15]
	v_mfma_f32_16x16x32_bf16 v[12:15], v[174:177], v[234:237], v[12:15]
	v_mfma_f32_16x16x32_bf16 v[8:11], v[178:181], v[230:233], v[8:11]
	v_mfma_f32_16x16x32_bf16 v[8:11], v[182:185], v[234:237], v[8:11]
	s_setprio 0
	s_setprio 1
	v_mfma_f32_16x16x32_bf16 v[52:55], v[186:189], v[202:205], v[52:55]
	v_mfma_f32_16x16x32_bf16 v[52:55], v[190:193], v[206:209], v[52:55]
	v_mfma_f32_16x16x32_bf16 v[48:51], v[194:197], v[202:205], v[48:51]
	v_mfma_f32_16x16x32_bf16 v[48:51], v[198:201], v[206:209], v[48:51]
	v_mfma_f32_16x16x32_bf16 v[36:39], v[186:189], v[210:213], v[36:39]
	v_mfma_f32_16x16x32_bf16 v[36:39], v[190:193], v[214:217], v[36:39]
	v_mfma_f32_16x16x32_bf16 v[32:35], v[194:197], v[210:213], v[32:35]
	v_mfma_f32_16x16x32_bf16 v[32:35], v[198:201], v[214:217], v[32:35]
	v_mfma_f32_16x16x32_bf16 v[20:23], v[186:189], v[222:225], v[20:23]
	v_mfma_f32_16x16x32_bf16 v[20:23], v[190:193], v[226:229], v[20:23]
	v_mfma_f32_16x16x32_bf16 v[16:19], v[194:197], v[222:225], v[16:19]
	v_mfma_f32_16x16x32_bf16 v[16:19], v[198:201], v[226:229], v[16:19]
	v_mfma_f32_16x16x32_bf16 v[4:7], v[186:189], v[230:233], v[4:7]
	v_mfma_f32_16x16x32_bf16 v[4:7], v[190:193], v[234:237], v[4:7]
	v_mfma_f32_16x16x32_bf16 v[0:3], v[194:197], v[230:233], v[0:3]
	v_mfma_f32_16x16x32_bf16 v[0:3], v[198:201], v[234:237], v[0:3]
	s_setprio 0
	s_barrier
	s_add_u32 s2, s2, 0x100
	s_addc_u32 s3, s3, 0
	s_add_u32 s6, s6, 0x100
	s_addc_u32 s7, s7, 0
	s_cmp_ge_i32 s8, s51
	s_mov_b32 s4, s8
	s_cbranch_scc0 .LBB0_970

.LBB0_1056:
	ds_read_b128 v[140:143], v222
	ds_read_b128 v[144:147], v222 offset:1024
	ds_read_b128 v[148:151], v222 offset:2048
	ds_read_b128 v[152:155], v222 offset:3072
	ds_read_b128 v[156:159], v223
	ds_read_b128 v[160:163], v223 offset:1024
	ds_read_b128 v[164:167], v223 offset:2048
	ds_read_b128 v[168:171], v223 offset:3072
	s_add_i32 s62, s26, 2
	s_add_u32 s27, s24, 0x4000
	s_addc_u32 s28, s25, 0
	s_cmp_eq_u32 s46, s26
	s_cselect_b32 s30, s0, s27
	s_cselect_b32 s31, s1, s28
	s_cselect_b32 s28, s22, s60
	s_cselect_b32 s29, s23, s61
	s_add_u32 s26, s30, 0x8000
	s_addc_u32 s27, s31, 0
	v_lshl_add_u64 v[204:205], s[24:25], 0, v[132:133]
	s_add_i32 m0, s38, 0xc000
	ds_read_b128 v[172:175], v224
	ds_read_b128 v[176:179], v224 offset:1024
	ds_read_b128 v[180:183], v224 offset:2048
	ds_read_b128 v[184:187], v224 offset:3072
	ds_read_b128 v[188:191], v224 offset:4096
	ds_read_b128 v[192:195], v224 offset:5120
	ds_read_b128 v[196:199], v224 offset:6144
	ds_read_b128 v[200:203], v224 offset:7168
	global_load_lds_dwordx4 v[204:205], off
	v_lshl_add_u64 v[204:205], s[24:25], 0, v[134:135]
	s_add_i32 m0, s38, 0xe000
	s_nop 0
	global_load_lds_dwordx4 v[204:205], off
	s_waitcnt vmcnt(8)
	s_waitcnt lgkmcnt(0)
	s_barrier
	s_setprio 1
	s_waitcnt lgkmcnt(0)
	v_mfma_f32_16x16x32_bf16 v[124:127], v[140:143], v[172:175], v[124:127]
	v_mfma_f32_16x16x32_bf16 v[124:127], v[144:147], v[176:179], v[124:127]
	v_mfma_f32_16x16x32_bf16 v[120:123], v[148:151], v[172:175], v[120:123]
	v_mfma_f32_16x16x32_bf16 v[120:123], v[152:155], v[176:179], v[120:123]
	v_mfma_f32_16x16x32_bf16 v[116:119], v[140:143], v[180:183], v[116:119]
	v_mfma_f32_16x16x32_bf16 v[116:119], v[144:147], v[184:187], v[116:119]
	v_mfma_f32_16x16x32_bf16 v[112:115], v[148:151], v[180:183], v[112:115]
	v_mfma_f32_16x16x32_bf16 v[112:115], v[152:155], v[184:187], v[112:115]
	v_mfma_f32_16x16x32_bf16 v[104:107], v[140:143], v[188:191], v[104:107]
	v_mfma_f32_16x16x32_bf16 v[104:107], v[144:147], v[192:195], v[104:107]
	v_mfma_f32_16x16x32_bf16 v[96:99], v[148:151], v[188:191], v[96:99]
	v_mfma_f32_16x16x32_bf16 v[96:99], v[152:155], v[192:195], v[96:99]
	v_mfma_f32_16x16x32_bf16 v[88:91], v[140:143], v[196:199], v[88:91]
	v_mfma_f32_16x16x32_bf16 v[88:91], v[144:147], v[200:203], v[88:91]
	v_mfma_f32_16x16x32_bf16 v[80:83], v[148:151], v[196:199], v[80:83]
	v_mfma_f32_16x16x32_bf16 v[80:83], v[152:155], v[200:203], v[80:83]
	s_setprio 0
	s_setprio 1
	v_mfma_f32_16x16x32_bf16 v[108:111], v[156:159], v[172:175], v[108:111]
	v_mfma_f32_16x16x32_bf16 v[108:111], v[160:163], v[176:179], v[108:111]
	v_mfma_f32_16x16x32_bf16 v[100:103], v[164:167], v[172:175], v[100:103]
	v_mfma_f32_16x16x32_bf16 v[100:103], v[168:171], v[176:179], v[100:103]
	v_mfma_f32_16x16x32_bf16 v[92:95], v[156:159], v[180:183], v[92:95]
	v_mfma_f32_16x16x32_bf16 v[92:95], v[160:163], v[184:187], v[92:95]
	v_mfma_f32_16x16x32_bf16 v[84:87], v[164:167], v[180:183], v[84:87]
	v_mfma_f32_16x16x32_bf16 v[84:87], v[168:171], v[184:187], v[84:87]
	v_mfma_f32_16x16x32_bf16 v[76:79], v[156:159], v[188:191], v[76:79]
	v_mfma_f32_16x16x32_bf16 v[76:79], v[160:163], v[192:195], v[76:79]
	v_mfma_f32_16x16x32_bf16 v[72:75], v[164:167], v[188:191], v[72:75]
	v_mfma_f32_16x16x32_bf16 v[72:75], v[168:171], v[192:195], v[72:75]
	v_mfma_f32_16x16x32_bf16 v[68:71], v[156:159], v[196:199], v[68:71]
	v_mfma_f32_16x16x32_bf16 v[68:71], v[160:163], v[200:203], v[68:71]
	v_mfma_f32_16x16x32_bf16 v[64:67], v[164:167], v[196:199], v[64:67]
	v_mfma_f32_16x16x32_bf16 v[64:67], v[168:171], v[200:203], v[64:67]
	s_setprio 0
	s_barrier
	s_add_i32 s63, s50, s37
	v_lshl_add_u64 v[204:205], s[28:29], 0, v[128:129]
	s_mov_b32 m0, s63
	ds_read_b128 v[172:175], v224 offset:16384
	ds_read_b128 v[176:179], v224 offset:17408
	ds_read_b128 v[180:183], v224 offset:18432
	ds_read_b128 v[184:187], v224 offset:19456
	ds_read_b128 v[188:191], v224 offset:20480
	ds_read_b128 v[192:195], v224 offset:21504
	ds_read_b128 v[196:199], v224 offset:22528
	ds_read_b128 v[200:203], v224 offset:23552
	global_load_lds_dwordx4 v[204:205], off
	s_add_i32 m0, s63, 0x2000
	s_add_u32 s64, s28, 0x4000
	v_lshl_add_u64 v[204:205], s[28:29], 0, v[130:131]
	s_addc_u32 s65, s29, 0
	s_add_i32 s63, s51, s37
	global_load_lds_dwordx4 v[204:205], off
	v_lshl_add_u64 v[204:205], s[64:65], 0, v[128:129]
	s_mov_b32 m0, s63
	s_nop 0
	global_load_lds_dwordx4 v[204:205], off
	v_lshl_add_u64 v[204:205], s[64:65], 0, v[130:131]
	s_add_i32 m0, s63, 0x2000
	s_nop 0
	global_load_lds_dwordx4 v[204:205], off
	v_lshl_add_u64 v[204:205], s[30:31], 0, v[128:129]
	s_mov_b32 m0, s38
	s_nop 0
	global_load_lds_dwordx4 v[204:205], off
	v_lshl_add_u64 v[204:205], s[30:31], 0, v[130:131]
	s_mov_b32 m0, s39
	s_nop 0
	global_load_lds_dwordx4 v[204:205], off
	s_waitcnt vmcnt(8)
	s_waitcnt lgkmcnt(0)
	s_barrier
	s_setprio 1
	s_waitcnt lgkmcnt(0)
	v_mfma_f32_16x16x32_bf16 v[60:63], v[140:143], v[172:175], v[60:63]
	v_mfma_f32_16x16x32_bf16 v[60:63], v[144:147], v[176:179], v[60:63]
	v_mfma_f32_16x16x32_bf16 v[56:59], v[148:151], v[172:175], v[56:59]
	v_mfma_f32_16x16x32_bf16 v[56:59], v[152:155], v[176:179], v[56:59]
	v_mfma_f32_16x16x32_bf16 v[52:55], v[140:143], v[180:183], v[52:55]
	v_mfma_f32_16x16x32_bf16 v[52:55], v[144:147], v[184:187], v[52:55]
	v_mfma_f32_16x16x32_bf16 v[48:51], v[148:151], v[180:183], v[48:51]
	v_mfma_f32_16x16x32_bf16 v[48:51], v[152:155], v[184:187], v[48:51]
	v_mfma_f32_16x16x32_bf16 v[40:43], v[140:143], v[188:191], v[40:43]
	v_mfma_f32_16x16x32_bf16 v[40:43], v[144:147], v[192:195], v[40:43]
	v_mfma_f32_16x16x32_bf16 v[32:35], v[148:151], v[188:191], v[32:35]
	v_mfma_f32_16x16x32_bf16 v[32:35], v[152:155], v[192:195], v[32:35]
	v_mfma_f32_16x16x32_bf16 v[24:27], v[140:143], v[196:199], v[24:27]
	v_mfma_f32_16x16x32_bf16 v[24:27], v[144:147], v[200:203], v[24:27]
	v_mfma_f32_16x16x32_bf16 v[16:19], v[148:151], v[196:199], v[16:19]
	v_mfma_f32_16x16x32_bf16 v[16:19], v[152:155], v[200:203], v[16:19]
	s_setprio 0
	s_setprio 1
	v_mfma_f32_16x16x32_bf16 v[44:47], v[156:159], v[172:175], v[44:47]
	v_mfma_f32_16x16x32_bf16 v[44:47], v[160:163], v[176:179], v[44:47]
	v_mfma_f32_16x16x32_bf16 v[36:39], v[164:167], v[172:175], v[36:39]
	v_mfma_f32_16x16x32_bf16 v[36:39], v[168:171], v[176:179], v[36:39]
	v_mfma_f32_16x16x32_bf16 v[28:31], v[156:159], v[180:183], v[28:31]
	v_mfma_f32_16x16x32_bf16 v[28:31], v[160:163], v[184:187], v[28:31]
	v_mfma_f32_16x16x32_bf16 v[20:23], v[164:167], v[180:183], v[20:23]
	v_mfma_f32_16x16x32_bf16 v[20:23], v[168:171], v[184:187], v[20:23]
	v_mfma_f32_16x16x32_bf16 v[12:15], v[156:159], v[188:191], v[12:15]
	v_mfma_f32_16x16x32_bf16 v[12:15], v[160:163], v[192:195], v[12:15]
	v_mfma_f32_16x16x32_bf16 v[8:11], v[164:167], v[188:191], v[8:11]
	v_mfma_f32_16x16x32_bf16 v[8:11], v[168:171], v[192:195], v[8:11]
	v_mfma_f32_16x16x32_bf16 v[4:7], v[156:159], v[196:199], v[4:7]
	v_mfma_f32_16x16x32_bf16 v[4:7], v[160:163], v[200:203], v[4:7]
	v_mfma_f32_16x16x32_bf16 v[0:3], v[164:167], v[196:199], v[0:3]
	v_mfma_f32_16x16x32_bf16 v[0:3], v[168:171], v[200:203], v[0:3]
	s_setprio 0
	s_barrier
	s_add_i32 s63, 0, 0x18000
	s_add_i32 s64, 0, 0x1c000
	v_add_u32_e32 v152, s63, v219
	v_add_u32_e32 v168, s64, v219
	ds_read_b128 v[140:143], v152
	ds_read_b128 v[144:147], v152 offset:1024
	ds_read_b128 v[148:151], v152 offset:2048
	ds_read_b128 v[152:155], v152 offset:3072
	ds_read_b128 v[156:159], v168
	ds_read_b128 v[160:163], v168 offset:1024
	ds_read_b128 v[164:167], v168 offset:2048
	ds_read_b128 v[168:171], v168 offset:3072
	s_add_u32 s30, s30, 0x4000
	s_addc_u32 s31, s31, 0
	s_mov_b32 m0, s40
	v_lshl_add_u64 v[204:205], s[30:31], 0, v[128:129]
	ds_read_b128 v[172:175], v224 offset:32768
	ds_read_b128 v[176:179], v224 offset:33792
	ds_read_b128 v[180:183], v224 offset:34816
	ds_read_b128 v[184:187], v224 offset:35840
	ds_read_b128 v[188:191], v224 offset:36864
	ds_read_b128 v[192:195], v224 offset:37888
	ds_read_b128 v[196:199], v224 offset:38912
	ds_read_b128 v[200:203], v224 offset:39936
	global_load_lds_dwordx4 v[204:205], off
	v_lshl_add_u64 v[204:205], s[30:31], 0, v[130:131]
	s_mov_b32 m0, s41
	s_nop 0
	global_load_lds_dwordx4 v[204:205], off
	s_waitcnt vmcnt(8)
	s_waitcnt lgkmcnt(0)
	s_barrier
	s_setprio 1
	s_waitcnt lgkmcnt(0)
	v_mfma_f32_16x16x32_bf16 v[124:127], v[140:143], v[172:175], v[124:127]
	v_mfma_f32_16x16x32_bf16 v[124:127], v[144:147], v[176:179], v[124:127]
	v_mfma_f32_16x16x32_bf16 v[120:123], v[148:151], v[172:175], v[120:123]
	v_mfma_f32_16x16x32_bf16 v[120:123], v[152:155], v[176:179], v[120:123]
	v_mfma_f32_16x16x32_bf16 v[116:119], v[140:143], v[180:183], v[116:119]
	v_mfma_f32_16x16x32_bf16 v[116:119], v[144:147], v[184:187], v[116:119]
	v_mfma_f32_16x16x32_bf16 v[112:115], v[148:151], v[180:183], v[112:115]
	v_mfma_f32_16x16x32_bf16 v[112:115], v[152:155], v[184:187], v[112:115]
	v_mfma_f32_16x16x32_bf16 v[104:107], v[140:143], v[188:191], v[104:107]
	v_mfma_f32_16x16x32_bf16 v[104:107], v[144:147], v[192:195], v[104:107]
	v_mfma_f32_16x16x32_bf16 v[96:99], v[148:151], v[188:191], v[96:99]
	v_mfma_f32_16x16x32_bf16 v[96:99], v[152:155], v[192:195], v[96:99]
	v_mfma_f32_16x16x32_bf16 v[88:91], v[140:143], v[196:199], v[88:91]
	v_mfma_f32_16x16x32_bf16 v[88:91], v[144:147], v[200:203], v[88:91]
	v_mfma_f32_16x16x32_bf16 v[80:83], v[148:151], v[196:199], v[80:83]
	v_mfma_f32_16x16x32_bf16 v[80:83], v[152:155], v[200:203], v[80:83]
	s_setprio 0
	s_setprio 1
	v_mfma_f32_16x16x32_bf16 v[108:111], v[156:159], v[172:175], v[108:111]
	v_mfma_f32_16x16x32_bf16 v[108:111], v[160:163], v[176:179], v[108:111]
	v_mfma_f32_16x16x32_bf16 v[100:103], v[164:167], v[172:175], v[100:103]
	v_mfma_f32_16x16x32_bf16 v[100:103], v[168:171], v[176:179], v[100:103]
	v_mfma_f32_16x16x32_bf16 v[92:95], v[156:159], v[180:183], v[92:95]
	v_mfma_f32_16x16x32_bf16 v[92:95], v[160:163], v[184:187], v[92:95]
	v_mfma_f32_16x16x32_bf16 v[84:87], v[164:167], v[180:183], v[84:87]
	v_mfma_f32_16x16x32_bf16 v[84:87], v[168:171], v[184:187], v[84:87]
	v_mfma_f32_16x16x32_bf16 v[76:79], v[156:159], v[188:191], v[76:79]
	v_mfma_f32_16x16x32_bf16 v[76:79], v[160:163], v[192:195], v[76:79]
	v_mfma_f32_16x16x32_bf16 v[72:75], v[164:167], v[188:191], v[72:75]
	v_mfma_f32_16x16x32_bf16 v[72:75], v[168:171], v[192:195], v[72:75]
	v_mfma_f32_16x16x32_bf16 v[68:71], v[156:159], v[196:199], v[68:71]
	v_mfma_f32_16x16x32_bf16 v[68:71], v[160:163], v[200:203], v[68:71]
	v_mfma_f32_16x16x32_bf16 v[64:67], v[164:167], v[196:199], v[64:67]
	v_mfma_f32_16x16x32_bf16 v[64:67], v[168:171], v[200:203], v[64:67]
	s_setprio 0
	s_barrier
	s_add_u32 s30, s28, 0x8000
	s_addc_u32 s31, s29, 0
	s_add_i32 s63, s63, s37
	v_lshl_add_u64 v[204:205], s[30:31], 0, v[128:129]
	s_mov_b32 m0, s63
	ds_read_b128 v[172:175], v224 offset:49152
	ds_read_b128 v[176:179], v224 offset:50176
	ds_read_b128 v[180:183], v224 offset:51200
	ds_read_b128 v[184:187], v224 offset:52224
	ds_read_b128 v[188:191], v224 offset:53248
	ds_read_b128 v[192:195], v224 offset:54272
	ds_read_b128 v[196:199], v224 offset:55296
	ds_read_b128 v[200:203], v224 offset:56320
	global_load_lds_dwordx4 v[204:205], off
	s_add_i32 m0, s63, 0x2000
	s_add_u32 s28, s28, 0xc000
	v_lshl_add_u64 v[204:205], s[30:31], 0, v[130:131]
	s_addc_u32 s29, s29, 0
	s_add_i32 s30, s64, s37
	global_load_lds_dwordx4 v[204:205], off
	v_lshl_add_u64 v[204:205], s[28:29], 0, v[128:129]
	s_mov_b32 m0, s30
	s_nop 0
	global_load_lds_dwordx4 v[204:205], off
	v_lshl_add_u64 v[204:205], s[28:29], 0, v[130:131]
	s_add_i32 m0, s30, 0x2000
	s_nop 0
	global_load_lds_dwordx4 v[204:205], off
	v_lshl_add_u64 v[204:205], s[26:27], 0, v[128:129]
	s_mov_b32 m0, s44
	s_nop 0
	global_load_lds_dwordx4 v[204:205], off
	v_lshl_add_u64 v[204:205], s[26:27], 0, v[130:131]
	s_mov_b32 m0, s45
	s_nop 0
	global_load_lds_dwordx4 v[204:205], off
	s_waitcnt vmcnt(8)
	s_waitcnt lgkmcnt(0)
	s_barrier
	s_setprio 1
	s_waitcnt lgkmcnt(0)
	v_mfma_f32_16x16x32_bf16 v[60:63], v[140:143], v[172:175], v[60:63]
	v_mfma_f32_16x16x32_bf16 v[60:63], v[144:147], v[176:179], v[60:63]
	v_mfma_f32_16x16x32_bf16 v[56:59], v[148:151], v[172:175], v[56:59]
	v_mfma_f32_16x16x32_bf16 v[56:59], v[152:155], v[176:179], v[56:59]
	v_mfma_f32_16x16x32_bf16 v[52:55], v[140:143], v[180:183], v[52:55]
	v_mfma_f32_16x16x32_bf16 v[52:55], v[144:147], v[184:187], v[52:55]
	v_mfma_f32_16x16x32_bf16 v[48:51], v[148:151], v[180:183], v[48:51]
	v_mfma_f32_16x16x32_bf16 v[48:51], v[152:155], v[184:187], v[48:51]
	v_mfma_f32_16x16x32_bf16 v[40:43], v[140:143], v[188:191], v[40:43]
	v_mfma_f32_16x16x32_bf16 v[40:43], v[144:147], v[192:195], v[40:43]
	v_mfma_f32_16x16x32_bf16 v[32:35], v[148:151], v[188:191], v[32:35]
	v_mfma_f32_16x16x32_bf16 v[32:35], v[152:155], v[192:195], v[32:35]
	v_mfma_f32_16x16x32_bf16 v[24:27], v[140:143], v[196:199], v[24:27]
	v_mfma_f32_16x16x32_bf16 v[24:27], v[144:147], v[200:203], v[24:27]
	v_mfma_f32_16x16x32_bf16 v[16:19], v[148:151], v[196:199], v[16:19]
	v_mfma_f32_16x16x32_bf16 v[16:19], v[152:155], v[200:203], v[16:19]
	s_setprio 0
	s_setprio 1
	v_mfma_f32_16x16x32_bf16 v[44:47], v[156:159], v[172:175], v[44:47]
	v_mfma_f32_16x16x32_bf16 v[44:47], v[160:163], v[176:179], v[44:47]
	v_mfma_f32_16x16x32_bf16 v[36:39], v[164:167], v[172:175], v[36:39]
	v_mfma_f32_16x16x32_bf16 v[36:39], v[168:171], v[176:179], v[36:39]
	v_mfma_f32_16x16x32_bf16 v[28:31], v[156:159], v[180:183], v[28:31]
	v_mfma_f32_16x16x32_bf16 v[28:31], v[160:163], v[184:187], v[28:31]
	v_mfma_f32_16x16x32_bf16 v[20:23], v[164:167], v[180:183], v[20:23]
	v_mfma_f32_16x16x32_bf16 v[20:23], v[168:171], v[184:187], v[20:23]
	v_mfma_f32_16x16x32_bf16 v[12:15], v[156:159], v[188:191], v[12:15]
	v_mfma_f32_16x16x32_bf16 v[12:15], v[160:163], v[192:195], v[12:15]
	v_mfma_f32_16x16x32_bf16 v[8:11], v[164:167], v[188:191], v[8:11]
	v_mfma_f32_16x16x32_bf16 v[8:11], v[168:171], v[192:195], v[8:11]
	v_mfma_f32_16x16x32_bf16 v[4:7], v[156:159], v[196:199], v[4:7]
	v_mfma_f32_16x16x32_bf16 v[4:7], v[160:163], v[200:203], v[4:7]
	v_mfma_f32_16x16x32_bf16 v[0:3], v[164:167], v[196:199], v[0:3]
	v_mfma_f32_16x16x32_bf16 v[0:3], v[168:171], v[200:203], v[0:3]
	s_setprio 0
	s_barrier
	s_add_u32 s24, s24, 0x10000
	s_addc_u32 s25, s25, 0
	s_add_u32 s60, s60, 0x10000
	s_addc_u32 s61, s61, 0
	s_cmp_ge_i32 s62, s43
	s_mov_b32 s26, s62
	s_cbranch_scc0 .LBB0_1056
	v_pk_mul_f32 v[198:199], v[126:127], 0.5 op_sel_hi:[1,0]
	v_pk_mul_f32 v[200:201], v[124:125], 0.5 op_sel_hi:[1,0]
	v_pk_mul_f32 v[202:203], v[122:123], 0.5 op_sel_hi:[1,0]
	v_pk_mul_f32 v[204:205], v[120:121], 0.5 op_sel_hi:[1,0]
	v_pk_mul_f32 v[208:209], v[110:111], 0.5 op_sel_hi:[1,0]
	v_pk_mul_f32 v[206:207], v[108:109], 0.5 op_sel_hi:[1,0]
	v_pk_mul_f32 v[196:197], v[102:103], 0.5 op_sel_hi:[1,0]
	v_pk_mul_f32 v[194:195], v[100:101], 0.5 op_sel_hi:[1,0]
	v_pk_mul_f32 v[192:193], v[118:119], 0.5 op_sel_hi:[1,0]
	v_pk_mul_f32 v[190:191], v[116:117], 0.5 op_sel_hi:[1,0]
	v_pk_mul_f32 v[188:189], v[114:115], 0.5 op_sel_hi:[1,0]
	v_pk_mul_f32 v[186:187], v[112:113], 0.5 op_sel_hi:[1,0]
	v_pk_mul_f32 v[184:185], v[94:95], 0.5 op_sel_hi:[1,0]
	v_pk_mul_f32 v[182:183], v[92:93], 0.5 op_sel_hi:[1,0]
	v_pk_mul_f32 v[180:181], v[86:87], 0.5 op_sel_hi:[1,0]
	v_pk_mul_f32 v[178:179], v[84:85], 0.5 op_sel_hi:[1,0]
	v_pk_mul_f32 v[176:177], v[106:107], 0.5 op_sel_hi:[1,0]
	v_pk_mul_f32 v[174:175], v[104:105], 0.5 op_sel_hi:[1,0]
	v_pk_mul_f32 v[172:173], v[98:99], 0.5 op_sel_hi:[1,0]
	v_pk_mul_f32 v[170:171], v[96:97], 0.5 op_sel_hi:[1,0]
	v_pk_mul_f32 v[168:169], v[78:79], 0.5 op_sel_hi:[1,0]
	v_pk_mul_f32 v[166:167], v[76:77], 0.5 op_sel_hi:[1,0]
	v_pk_mul_f32 v[164:165], v[74:75], 0.5 op_sel_hi:[1,0]
	v_pk_mul_f32 v[162:163], v[72:73], 0.5 op_sel_hi:[1,0]
	v_pk_mul_f32 v[160:161], v[90:91], 0.5 op_sel_hi:[1,0]
	v_pk_mul_f32 v[158:159], v[88:89], 0.5 op_sel_hi:[1,0]
	v_pk_mul_f32 v[156:157], v[82:83], 0.5 op_sel_hi:[1,0]
	v_pk_mul_f32 v[154:155], v[80:81], 0.5 op_sel_hi:[1,0]
	v_pk_mul_f32 v[152:153], v[70:71], 0.5 op_sel_hi:[1,0]
	v_pk_mul_f32 v[150:151], v[68:69], 0.5 op_sel_hi:[1,0]
	v_pk_mul_f32 v[148:149], v[66:67], 0.5 op_sel_hi:[1,0]
	v_pk_mul_f32 v[146:147], v[64:65], 0.5 op_sel_hi:[1,0]
	v_pk_mul_f32 v[142:143], v[62:63], 0.5 op_sel_hi:[1,0]
	v_pk_mul_f32 v[140:141], v[60:61], 0.5 op_sel_hi:[1,0]
	v_pk_mul_f32 v[126:127], v[58:59], 0.5 op_sel_hi:[1,0]
	v_pk_mul_f32 v[124:125], v[56:57], 0.5 op_sel_hi:[1,0]
	v_pk_mul_f32 v[122:123], v[46:47], 0.5 op_sel_hi:[1,0]
	v_pk_mul_f32 v[120:121], v[44:45], 0.5 op_sel_hi:[1,0]
	v_pk_mul_f32 v[118:119], v[38:39], 0.5 op_sel_hi:[1,0]
	v_pk_mul_f32 v[116:117], v[36:37], 0.5 op_sel_hi:[1,0]
	v_pk_mul_f32 v[114:115], v[54:55], 0.5 op_sel_hi:[1,0]
	v_pk_mul_f32 v[112:113], v[52:53], 0.5 op_sel_hi:[1,0]
	v_pk_mul_f32 v[110:111], v[50:51], 0.5 op_sel_hi:[1,0]
	v_pk_mul_f32 v[108:109], v[48:49], 0.5 op_sel_hi:[1,0]
	v_pk_mul_f32 v[106:107], v[30:31], 0.5 op_sel_hi:[1,0]
	v_pk_mul_f32 v[104:105], v[28:29], 0.5 op_sel_hi:[1,0]
	v_pk_mul_f32 v[102:103], v[22:23], 0.5 op_sel_hi:[1,0]
	v_pk_mul_f32 v[100:101], v[20:21], 0.5 op_sel_hi:[1,0]
	v_pk_mul_f32 v[98:99], v[42:43], 0.5 op_sel_hi:[1,0]
	v_pk_mul_f32 v[96:97], v[40:41], 0.5 op_sel_hi:[1,0]
	v_pk_mul_f32 v[94:95], v[34:35], 0.5 op_sel_hi:[1,0]
	v_pk_mul_f32 v[92:93], v[32:33], 0.5 op_sel_hi:[1,0]
	v_pk_mul_f32 v[90:91], v[14:15], 0.5 op_sel_hi:[1,0]
	v_pk_mul_f32 v[88:89], v[12:13], 0.5 op_sel_hi:[1,0]
	v_pk_mul_f32 v[86:87], v[10:11], 0.5 op_sel_hi:[1,0]
	v_pk_mul_f32 v[84:85], v[8:9], 0.5 op_sel_hi:[1,0]
	v_pk_mul_f32 v[82:83], v[26:27], 0.5 op_sel_hi:[1,0]
	v_pk_mul_f32 v[80:81], v[24:25], 0.5 op_sel_hi:[1,0]
	v_pk_mul_f32 v[78:79], v[18:19], 0.5 op_sel_hi:[1,0]
	v_pk_mul_f32 v[76:77], v[16:17], 0.5 op_sel_hi:[1,0]
	v_pk_mul_f32 v[74:75], v[6:7], 0.5 op_sel_hi:[1,0]
	v_pk_mul_f32 v[72:73], v[4:5], 0.5 op_sel_hi:[1,0]
	v_pk_mul_f32 v[70:71], v[2:3], 0.5 op_sel_hi:[1,0]
	v_pk_mul_f32 v[68:69], v[0:1], 0.5 op_sel_hi:[1,0]

.LBB0_1159:
	ds_read_b128 v[128:131], v205
	ds_read_b128 v[132:135], v205 offset:1024
	ds_read_b128 v[136:139], v205 offset:2048
	ds_read_b128 v[140:143], v205 offset:3072
	ds_read_b128 v[144:147], v206
	ds_read_b128 v[160:163], v206 offset:1024
	ds_read_b128 v[164:167], v206 offset:2048
	ds_read_b128 v[168:171], v206 offset:3072
	s_add_i32 s41, s6, 2
	s_add_u32 s68, s0, 0x80
	s_addc_u32 s7, s1, 0
	s_cmp_eq_u32 s57, s6
	s_cselect_b32 s6, s34, s68
	s_cselect_b32 s7, s35, s7
	s_cselect_b32 s69, s37, s39
	s_cselect_b32 s68, s36, s38
	v_lshl_add_u64 v[200:201], s[0:1], 0, v[152:153]
	s_add_i32 m0, s47, 0xc000
	ds_read_b128 v[172:175], v207
	ds_read_b128 v[176:179], v207 offset:1024
	ds_read_b128 v[180:183], v207 offset:2048
	ds_read_b128 v[184:187], v207 offset:3072
	ds_read_b128 v[188:191], v207 offset:4096
	ds_read_b128 v[192:195], v207 offset:5120
	ds_read_b128 v[196:199], v207 offset:6144
	ds_read_b128 v[212:215], v207 offset:7168
	global_load_lds_dwordx4 v[200:201], off
	v_lshl_add_u64 v[200:201], s[0:1], 0, v[154:155]
	s_add_i32 m0, s47, 0xe000
	s_nop 0
	global_load_lds_dwordx4 v[200:201], off
	s_waitcnt vmcnt(8)
	s_waitcnt lgkmcnt(0)
	s_barrier
	s_setprio 1
	s_waitcnt lgkmcnt(0)
	v_mfma_f32_16x16x32_bf16 v[124:127], v[128:131], v[172:175], v[124:127]
	v_mfma_f32_16x16x32_bf16 v[124:127], v[132:135], v[176:179], v[124:127]
	v_mfma_f32_16x16x32_bf16 v[120:123], v[136:139], v[172:175], v[120:123]
	v_mfma_f32_16x16x32_bf16 v[120:123], v[140:143], v[176:179], v[120:123]
	v_mfma_f32_16x16x32_bf16 v[108:111], v[128:131], v[180:183], v[108:111]
	v_mfma_f32_16x16x32_bf16 v[108:111], v[132:135], v[184:187], v[108:111]
	v_mfma_f32_16x16x32_bf16 v[104:107], v[136:139], v[180:183], v[104:107]
	v_mfma_f32_16x16x32_bf16 v[104:107], v[140:143], v[184:187], v[104:107]
	v_mfma_f32_16x16x32_bf16 v[92:95], v[128:131], v[188:191], v[92:95]
	v_mfma_f32_16x16x32_bf16 v[92:95], v[132:135], v[192:195], v[92:95]
	v_mfma_f32_16x16x32_bf16 v[88:91], v[136:139], v[188:191], v[88:91]
	v_mfma_f32_16x16x32_bf16 v[88:91], v[140:143], v[192:195], v[88:91]
	v_mfma_f32_16x16x32_bf16 v[76:79], v[128:131], v[196:199], v[76:79]
	v_mfma_f32_16x16x32_bf16 v[76:79], v[132:135], v[212:215], v[76:79]
	v_mfma_f32_16x16x32_bf16 v[72:75], v[136:139], v[196:199], v[72:75]
	v_mfma_f32_16x16x32_bf16 v[72:75], v[140:143], v[212:215], v[72:75]
	s_setprio 0
	s_setprio 1
	v_mfma_f32_16x16x32_bf16 v[116:119], v[144:147], v[172:175], v[116:119]
	v_mfma_f32_16x16x32_bf16 v[116:119], v[160:163], v[176:179], v[116:119]
	v_mfma_f32_16x16x32_bf16 v[112:115], v[164:167], v[172:175], v[112:115]
	v_mfma_f32_16x16x32_bf16 v[112:115], v[168:171], v[176:179], v[112:115]
	v_mfma_f32_16x16x32_bf16 v[100:103], v[144:147], v[180:183], v[100:103]
	v_mfma_f32_16x16x32_bf16 v[100:103], v[160:163], v[184:187], v[100:103]
	v_mfma_f32_16x16x32_bf16 v[96:99], v[164:167], v[180:183], v[96:99]
	v_mfma_f32_16x16x32_bf16 v[96:99], v[168:171], v[184:187], v[96:99]
	v_mfma_f32_16x16x32_bf16 v[84:87], v[144:147], v[188:191], v[84:87]
	v_mfma_f32_16x16x32_bf16 v[84:87], v[160:163], v[192:195], v[84:87]
	v_mfma_f32_16x16x32_bf16 v[80:83], v[164:167], v[188:191], v[80:83]
	v_mfma_f32_16x16x32_bf16 v[80:83], v[168:171], v[192:195], v[80:83]
	v_mfma_f32_16x16x32_bf16 v[68:71], v[144:147], v[196:199], v[68:71]
	v_mfma_f32_16x16x32_bf16 v[68:71], v[160:163], v[212:215], v[68:71]
	v_mfma_f32_16x16x32_bf16 v[64:67], v[164:167], v[196:199], v[64:67]
	v_mfma_f32_16x16x32_bf16 v[64:67], v[168:171], v[212:215], v[64:67]
	s_setprio 0
	s_barrier
	s_add_i32 s70, s60, s46
	v_lshl_add_u64 v[200:201], s[68:69], 0, v[148:149]
	s_mov_b32 m0, s70
	ds_read_b128 v[172:175], v207 offset:16384
	ds_read_b128 v[176:179], v207 offset:17408
	ds_read_b128 v[180:183], v207 offset:18432
	ds_read_b128 v[184:187], v207 offset:19456
	ds_read_b128 v[188:191], v207 offset:20480
	ds_read_b128 v[192:195], v207 offset:21504
	ds_read_b128 v[196:199], v207 offset:22528
	ds_read_b128 v[212:215], v207 offset:23552
	global_load_lds_dwordx4 v[200:201], off
	s_add_i32 m0, s70, 0x2000
	v_lshl_add_u64 v[216:217], s[68:69], 0, v[150:151]
	s_add_u32 s68, s68, s10
	s_addc_u32 s69, s69, s11
	s_add_i32 s70, s61, s46
	global_load_lds_dwordx4 v[216:217], off
	v_lshl_add_u64 v[218:219], s[68:69], 0, v[148:149]
	s_mov_b32 m0, s70
	v_lshl_add_u64 v[220:221], s[68:69], 0, v[150:151]
	global_load_lds_dwordx4 v[218:219], off
	s_add_i32 m0, s70, 0x2000
	v_lshl_add_u64 v[222:223], s[6:7], 0, v[148:149]
	global_load_lds_dwordx4 v[220:221], off
	s_mov_b32 m0, s47
	v_lshl_add_u64 v[224:225], s[6:7], 0, v[150:151]
	global_load_lds_dwordx4 v[222:223], off
	s_mov_b32 m0, s48
	s_nop 0
	global_load_lds_dwordx4 v[224:225], off
	s_waitcnt vmcnt(8)
	s_waitcnt lgkmcnt(0)
	s_barrier
	s_setprio 1
	s_waitcnt lgkmcnt(0)
	v_mfma_f32_16x16x32_bf16 v[60:63], v[128:131], v[172:175], v[60:63]
	v_mfma_f32_16x16x32_bf16 v[60:63], v[132:135], v[176:179], v[60:63]
	v_mfma_f32_16x16x32_bf16 v[56:59], v[136:139], v[172:175], v[56:59]
	v_mfma_f32_16x16x32_bf16 v[56:59], v[140:143], v[176:179], v[56:59]
	v_mfma_f32_16x16x32_bf16 v[44:47], v[128:131], v[180:183], v[44:47]
	v_mfma_f32_16x16x32_bf16 v[44:47], v[132:135], v[184:187], v[44:47]
	v_mfma_f32_16x16x32_bf16 v[40:43], v[136:139], v[180:183], v[40:43]
	v_mfma_f32_16x16x32_bf16 v[40:43], v[140:143], v[184:187], v[40:43]
	v_mfma_f32_16x16x32_bf16 v[28:31], v[128:131], v[188:191], v[28:31]
	v_mfma_f32_16x16x32_bf16 v[28:31], v[132:135], v[192:195], v[28:31]
	v_mfma_f32_16x16x32_bf16 v[24:27], v[136:139], v[188:191], v[24:27]
	v_mfma_f32_16x16x32_bf16 v[24:27], v[140:143], v[192:195], v[24:27]
	v_mfma_f32_16x16x32_bf16 v[12:15], v[128:131], v[196:199], v[12:15]
	v_mfma_f32_16x16x32_bf16 v[12:15], v[132:135], v[212:215], v[12:15]
	v_mfma_f32_16x16x32_bf16 v[8:11], v[136:139], v[196:199], v[8:11]
	v_mfma_f32_16x16x32_bf16 v[8:11], v[140:143], v[212:215], v[8:11]
	s_setprio 0
	s_setprio 1
	v_mfma_f32_16x16x32_bf16 v[52:55], v[144:147], v[172:175], v[52:55]
	v_mfma_f32_16x16x32_bf16 v[52:55], v[160:163], v[176:179], v[52:55]
	v_mfma_f32_16x16x32_bf16 v[48:51], v[164:167], v[172:175], v[48:51]
	v_mfma_f32_16x16x32_bf16 v[48:51], v[168:171], v[176:179], v[48:51]
	v_mfma_f32_16x16x32_bf16 v[36:39], v[144:147], v[180:183], v[36:39]
	v_mfma_f32_16x16x32_bf16 v[36:39], v[160:163], v[184:187], v[36:39]
	v_mfma_f32_16x16x32_bf16 v[32:35], v[164:167], v[180:183], v[32:35]
	v_mfma_f32_16x16x32_bf16 v[32:35], v[168:171], v[184:187], v[32:35]
	v_mfma_f32_16x16x32_bf16 v[20:23], v[144:147], v[188:191], v[20:23]
	v_mfma_f32_16x16x32_bf16 v[20:23], v[160:163], v[192:195], v[20:23]
	v_mfma_f32_16x16x32_bf16 v[16:19], v[164:167], v[188:191], v[16:19]
	v_mfma_f32_16x16x32_bf16 v[16:19], v[168:171], v[192:195], v[16:19]
	v_mfma_f32_16x16x32_bf16 v[4:7], v[144:147], v[196:199], v[4:7]
	v_mfma_f32_16x16x32_bf16 v[4:7], v[160:163], v[212:215], v[4:7]
	v_mfma_f32_16x16x32_bf16 v[0:3], v[164:167], v[196:199], v[0:3]
	v_mfma_f32_16x16x32_bf16 v[0:3], v[168:171], v[212:215], v[0:3]
	s_setprio 0
	s_barrier
	s_add_i32 s68, 0, 0x18000
	s_add_i32 s69, 0, 0x1c000
	v_add_u32_e32 v140, s68, v203
	v_add_u32_e32 v168, s69, v203
	ds_read_b128 v[128:131], v140
	ds_read_b128 v[132:135], v140 offset:1024
	ds_read_b128 v[136:139], v140 offset:2048
	ds_read_b128 v[140:143], v140 offset:3072
	ds_read_b128 v[144:147], v168
	ds_read_b128 v[160:163], v168 offset:1024
	ds_read_b128 v[164:167], v168 offset:2048
	ds_read_b128 v[168:171], v168 offset:3072
	s_add_u32 s6, s6, s10
	s_addc_u32 s7, s7, s11
	s_mov_b32 m0, s49
	v_lshl_add_u64 v[226:227], s[6:7], 0, v[148:149]
	ds_read_b128 v[172:175], v207 offset:32768
	ds_read_b128 v[176:179], v207 offset:33792
	ds_read_b128 v[180:183], v207 offset:34816
	ds_read_b128 v[184:187], v207 offset:35840
	ds_read_b128 v[188:191], v207 offset:36864
	ds_read_b128 v[192:195], v207 offset:37888
	ds_read_b128 v[196:199], v207 offset:38912
	ds_read_b128 v[212:215], v207 offset:39936
	global_load_lds_dwordx4 v[226:227], off
	v_lshl_add_u64 v[226:227], s[6:7], 0, v[150:151]
	s_mov_b32 m0, s50
	s_nop 0
	global_load_lds_dwordx4 v[226:227], off
	s_waitcnt vmcnt(8)
	s_waitcnt lgkmcnt(0)
	s_barrier
	s_setprio 1
	s_waitcnt lgkmcnt(0)
	v_mfma_f32_16x16x32_bf16 v[124:127], v[128:131], v[172:175], v[124:127]
	v_mfma_f32_16x16x32_bf16 v[124:127], v[132:135], v[176:179], v[124:127]
	v_mfma_f32_16x16x32_bf16 v[120:123], v[136:139], v[172:175], v[120:123]
	v_mfma_f32_16x16x32_bf16 v[120:123], v[140:143], v[176:179], v[120:123]
	v_mfma_f32_16x16x32_bf16 v[108:111], v[128:131], v[180:183], v[108:111]
	v_mfma_f32_16x16x32_bf16 v[108:111], v[132:135], v[184:187], v[108:111]
	v_mfma_f32_16x16x32_bf16 v[104:107], v[136:139], v[180:183], v[104:107]
	v_mfma_f32_16x16x32_bf16 v[104:107], v[140:143], v[184:187], v[104:107]
	v_mfma_f32_16x16x32_bf16 v[92:95], v[128:131], v[188:191], v[92:95]
	v_mfma_f32_16x16x32_bf16 v[92:95], v[132:135], v[192:195], v[92:95]
	v_mfma_f32_16x16x32_bf16 v[88:91], v[136:139], v[188:191], v[88:91]
	v_mfma_f32_16x16x32_bf16 v[88:91], v[140:143], v[192:195], v[88:91]
	v_mfma_f32_16x16x32_bf16 v[76:79], v[128:131], v[196:199], v[76:79]
	v_mfma_f32_16x16x32_bf16 v[76:79], v[132:135], v[212:215], v[76:79]
	v_mfma_f32_16x16x32_bf16 v[72:75], v[136:139], v[196:199], v[72:75]
	v_mfma_f32_16x16x32_bf16 v[72:75], v[140:143], v[212:215], v[72:75]
	s_setprio 0
	s_setprio 1
	v_mfma_f32_16x16x32_bf16 v[116:119], v[144:147], v[172:175], v[116:119]
	v_mfma_f32_16x16x32_bf16 v[116:119], v[160:163], v[176:179], v[116:119]
	v_mfma_f32_16x16x32_bf16 v[112:115], v[164:167], v[172:175], v[112:115]
	v_mfma_f32_16x16x32_bf16 v[112:115], v[168:171], v[176:179], v[112:115]
	v_mfma_f32_16x16x32_bf16 v[100:103], v[144:147], v[180:183], v[100:103]
	v_mfma_f32_16x16x32_bf16 v[100:103], v[160:163], v[184:187], v[100:103]
	v_mfma_f32_16x16x32_bf16 v[96:99], v[164:167], v[180:183], v[96:99]
	v_mfma_f32_16x16x32_bf16 v[96:99], v[168:171], v[184:187], v[96:99]
	v_mfma_f32_16x16x32_bf16 v[84:87], v[144:147], v[188:191], v[84:87]
	v_mfma_f32_16x16x32_bf16 v[84:87], v[160:163], v[192:195], v[84:87]
	v_mfma_f32_16x16x32_bf16 v[80:83], v[164:167], v[188:191], v[80:83]
	v_mfma_f32_16x16x32_bf16 v[80:83], v[168:171], v[192:195], v[80:83]
	v_mfma_f32_16x16x32_bf16 v[68:71], v[144:147], v[196:199], v[68:71]
	v_mfma_f32_16x16x32_bf16 v[68:71], v[160:163], v[212:215], v[68:71]
	v_mfma_f32_16x16x32_bf16 v[64:67], v[164:167], v[196:199], v[64:67]
	v_mfma_f32_16x16x32_bf16 v[64:67], v[168:171], v[212:215], v[64:67]
	s_setprio 0
	s_barrier
	s_add_i32 s6, s68, s46
	v_lshl_add_u64 v[200:201], v[200:201], 0, s[20:21]
	s_mov_b32 m0, s6
	ds_read_b128 v[172:175], v207 offset:49152
	ds_read_b128 v[176:179], v207 offset:50176
	ds_read_b128 v[180:183], v207 offset:51200
	ds_read_b128 v[184:187], v207 offset:52224
	ds_read_b128 v[188:191], v207 offset:53248
	ds_read_b128 v[192:195], v207 offset:54272
	ds_read_b128 v[196:199], v207 offset:55296
	ds_read_b128 v[212:215], v207 offset:56320
	global_load_lds_dwordx4 v[200:201], off
	v_lshl_add_u64 v[200:201], v[216:217], 0, s[20:21]
	s_add_i32 m0, s6, 0x2000
	s_add_i32 s6, s69, s46
	global_load_lds_dwordx4 v[200:201], off
	v_lshl_add_u64 v[200:201], v[218:219], 0, s[20:21]
	s_mov_b32 m0, s6
	s_nop 0
	global_load_lds_dwordx4 v[200:201], off
	v_lshl_add_u64 v[200:201], v[220:221], 0, s[20:21]
	s_add_i32 m0, s6, 0x2000
	s_nop 0
	global_load_lds_dwordx4 v[200:201], off
	v_lshl_add_u64 v[200:201], v[222:223], 0, s[20:21]
	s_mov_b32 m0, s54
	s_nop 0
	global_load_lds_dwordx4 v[200:201], off
	v_lshl_add_u64 v[200:201], v[224:225], 0, s[20:21]
	s_mov_b32 m0, s55
	s_nop 0
	global_load_lds_dwordx4 v[200:201], off
	s_waitcnt vmcnt(8)
	s_waitcnt lgkmcnt(0)
	s_barrier
	s_setprio 1
	s_waitcnt lgkmcnt(0)
	v_mfma_f32_16x16x32_bf16 v[60:63], v[128:131], v[172:175], v[60:63]
	v_mfma_f32_16x16x32_bf16 v[60:63], v[132:135], v[176:179], v[60:63]
	v_mfma_f32_16x16x32_bf16 v[56:59], v[136:139], v[172:175], v[56:59]
	v_mfma_f32_16x16x32_bf16 v[56:59], v[140:143], v[176:179], v[56:59]
	v_mfma_f32_16x16x32_bf16 v[44:47], v[128:131], v[180:183], v[44:47]
	v_mfma_f32_16x16x32_bf16 v[44:47], v[132:135], v[184:187], v[44:47]
	v_mfma_f32_16x16x32_bf16 v[40:43], v[136:139], v[180:183], v[40:43]
	v_mfma_f32_16x16x32_bf16 v[40:43], v[140:143], v[184:187], v[40:43]
	v_mfma_f32_16x16x32_bf16 v[28:31], v[128:131], v[188:191], v[28:31]
	v_mfma_f32_16x16x32_bf16 v[28:31], v[132:135], v[192:195], v[28:31]
	v_mfma_f32_16x16x32_bf16 v[24:27], v[136:139], v[188:191], v[24:27]
	v_mfma_f32_16x16x32_bf16 v[24:27], v[140:143], v[192:195], v[24:27]
	v_mfma_f32_16x16x32_bf16 v[12:15], v[128:131], v[196:199], v[12:15]
	v_mfma_f32_16x16x32_bf16 v[12:15], v[132:135], v[212:215], v[12:15]
	v_mfma_f32_16x16x32_bf16 v[8:11], v[136:139], v[196:199], v[8:11]
	v_mfma_f32_16x16x32_bf16 v[8:11], v[140:143], v[212:215], v[8:11]
	s_setprio 0
	s_setprio 1
	v_mfma_f32_16x16x32_bf16 v[52:55], v[144:147], v[172:175], v[52:55]
	v_mfma_f32_16x16x32_bf16 v[52:55], v[160:163], v[176:179], v[52:55]
	v_mfma_f32_16x16x32_bf16 v[48:51], v[164:167], v[172:175], v[48:51]
	v_mfma_f32_16x16x32_bf16 v[48:51], v[168:171], v[176:179], v[48:51]
	v_mfma_f32_16x16x32_bf16 v[36:39], v[144:147], v[180:183], v[36:39]
	v_mfma_f32_16x16x32_bf16 v[36:39], v[160:163], v[184:187], v[36:39]
	v_mfma_f32_16x16x32_bf16 v[32:35], v[164:167], v[180:183], v[32:35]
	v_mfma_f32_16x16x32_bf16 v[32:35], v[168:171], v[184:187], v[32:35]
	v_mfma_f32_16x16x32_bf16 v[20:23], v[144:147], v[188:191], v[20:23]
	v_mfma_f32_16x16x32_bf16 v[20:23], v[160:163], v[192:195], v[20:23]
	v_mfma_f32_16x16x32_bf16 v[16:19], v[164:167], v[188:191], v[16:19]
	v_mfma_f32_16x16x32_bf16 v[16:19], v[168:171], v[192:195], v[16:19]
	v_mfma_f32_16x16x32_bf16 v[4:7], v[144:147], v[196:199], v[4:7]
	v_mfma_f32_16x16x32_bf16 v[4:7], v[160:163], v[212:215], v[4:7]
	v_mfma_f32_16x16x32_bf16 v[0:3], v[164:167], v[196:199], v[0:3]
	v_mfma_f32_16x16x32_bf16 v[0:3], v[168:171], v[212:215], v[0:3]
	s_setprio 0
	s_barrier
	s_add_u32 s0, s0, 0x100
	s_addc_u32 s1, s1, 0
	s_add_u32 s38, s38, 0x100
	s_addc_u32 s39, s39, 0
	s_cmp_ge_i32 s41, s56
	s_mov_b32 s6, s41
	s_cbranch_scc0 .LBB0_1159
